# GEMM loops: keep priority through the trailing barrier (s_barrier before s_setprio 0); attention: loads hoisted to top of each tile step, exps under PV MFMAs, 4-bit K swizzle, prio for waves 0-3
# speedup vs baseline: 1.0135x; 1.0135x over previous
; #define PG8_STAGE(bufoff, gbase, voff) do { _Pragma("unroll") for (int _i = 0; _i < 2; ++_i) \
;         __builtin_amdgcn_global_load_lds((const unsigned*)((const char*)(gbase) + (voff)[_i]), (PG8_LAS unsigned*)(lds + (bufoff) + ldsw + _i * 8192), 16, 0, 0); } while (0)
; #define PG8_LDA(dst, b, h) do { _Pragma("unroll") for (int m = 0; m < 4; ++m) _Pragma("unroll") for (int k = 0; k < 2; ++k) dst[m][k] = *(const PG8_LAS bf16x8*)(lds + PG8_SA(b, h) + aoff + m * 2048 + k * 1024); } while (0)
; #define PG8_LDB(dst, b, h) do { _Pragma("unroll") for (int n = 0; n < 2; ++n) _Pragma("unroll") for (int k = 0; k < 2; ++k) dst[n][k] = *(const PG8_LAS bf16x8*)(lds + PG8_SB(b, h) + boff + n * 2048 + k * 1024); } while (0)
; #define PG8_MMA(ai, bj, At, Bt) do { __builtin_amdgcn_s_setprio(1); _Pragma("unroll") for (int m = 0; m < 4; ++m) _Pragma("unroll") for (int n = 0; n < 2; ++n) _Pragma("unroll") for (int k = 0; k < 2; ++k) \
;         acc[ai][bj][m][n] = __builtin_amdgcn_mfma_f32_16x16x32_bf16(Bt[n][k], At[m][k], acc[ai][bj][m][n], 0, 0, 0); __builtin_amdgcn_s_setprio(0); } while (0)
; #define PG8_WAIT_V(n) asm volatile("s_waitcnt vmcnt(" #n ")" ::: "memory")
; #define PG8_WAIT_L(n) asm volatile("s_waitcnt lgkmcnt(" #n ")" ::: "memory")
; #define PG8_BAR __builtin_amdgcn_s_barrier()
; #define PG8_SCHED __builtin_amdgcn_sched_barrier(0)
; template <class Epi, class Sched, bool ALIGN_EPI = false, bool SP2 = false>
; __device__ __forceinline__ void gemm_phase(PG8_LAS unsigned char* lds, const Gemm g, const Sched& S, const Epi& E) {
;     ...
;             PG8_LDB(B0, 0, 0); PG8_LDB(B1, 0, 1); PG8_SCHED; PG8_LDA(At, 0, 0); PG8_STAGE(PG8_SA(1, 1), a1 + hstepA, voffA);
;             PG8_WAIT_V(8); PG8_WAIT_L(0); PG8_BAR; PG8_MMA(0, 0, At, B0); PG8_MMA(0, 1, At, B1); PG8_BAR; PG8_SCHED;
;             PG8_LDA(At, 0, 1); PG8_STAGE(PG8_SB(0, 0), b2, voffB); PG8_STAGE(PG8_SB(0, 1), b2 + hstepB, voffB); PG8_STAGE(PG8_SA(0, 0), a2, voffA);
.LBB0_244:
	ds_read_b128 v[152:155], v147
	ds_read_b128 v[156:159], v147 offset:1024
	ds_read_b128 v[160:163], v147 offset:2048
	ds_read_b128 v[164:167], v147 offset:3072
	ds_read_b128 v[168:171], v148
	ds_read_b128 v[172:175], v148 offset:1024
	ds_read_b128 v[176:179], v148 offset:2048
	ds_read_b128 v[180:183], v148 offset:3072
	s_add_u32 s28, s26, 0xfffc0080
	s_addc_u32 s29, s27, -1
	s_cmp_eq_u32 s68, 12
	s_cselect_b32 s31, s15, s29
	s_cselect_b32 s30, s62, s28
	s_cselect_b32 s29, s13, s67
	s_cselect_b32 s28, s63, s66
	v_lshl_add_u64 v[184:185], s[26:27], 0, v[136:137]
	s_add_i32 m0, s25, 0xc000
	ds_read_b128 v[188:191], v149
	ds_read_b128 v[192:195], v149 offset:1024
	ds_read_b128 v[196:199], v149 offset:2048
	ds_read_b128 v[200:203], v149 offset:3072
	ds_read_b128 v[204:207], v149 offset:4096
	ds_read_b128 v[208:211], v149 offset:5120
	ds_read_b128 v[212:215], v149 offset:6144
	ds_read_b128 v[216:219], v149 offset:7168
	global_load_lds_dwordx4 v[184:185], off
	v_lshl_add_u64 v[184:185], s[26:27], 0, v[138:139]
	s_add_i32 m0, s25, 0xe000
	s_nop 0
	global_load_lds_dwordx4 v[184:185], off
	s_waitcnt vmcnt(8)
	s_waitcnt lgkmcnt(0)
	s_barrier
	s_setprio 1
	s_waitcnt lgkmcnt(0)
	v_mfma_f32_16x16x32_bf16 v[116:119], v[152:155], v[188:191], v[116:119]
	v_mfma_f32_16x16x32_bf16 v[108:111], v[160:163], v[188:191], v[108:111]
	v_mfma_f32_16x16x32_bf16 v[104:107], v[152:155], v[196:199], v[104:107]
	v_mfma_f32_16x16x32_bf16 v[100:103], v[160:163], v[196:199], v[100:103]
	v_mfma_f32_16x16x32_bf16 v[92:95], v[152:155], v[204:207], v[92:95]
	v_mfma_f32_16x16x32_bf16 v[84:87], v[160:163], v[204:207], v[84:87]
	v_mfma_f32_16x16x32_bf16 v[76:79], v[152:155], v[212:215], v[76:79]
	v_mfma_f32_16x16x32_bf16 v[68:71], v[160:163], v[212:215], v[68:71]
	v_mfma_f32_16x16x32_bf16 v[116:119], v[156:159], v[192:195], v[116:119]
	v_mfma_f32_16x16x32_bf16 v[108:111], v[164:167], v[192:195], v[108:111]
	v_mfma_f32_16x16x32_bf16 v[104:107], v[156:159], v[200:203], v[104:107]
	v_mfma_f32_16x16x32_bf16 v[100:103], v[164:167], v[200:203], v[100:103]
	v_mfma_f32_16x16x32_bf16 v[92:95], v[156:159], v[208:211], v[92:95]
	v_mfma_f32_16x16x32_bf16 v[84:87], v[164:167], v[208:211], v[84:87]
	v_mfma_f32_16x16x32_bf16 v[76:79], v[156:159], v[216:219], v[76:79]
	v_mfma_f32_16x16x32_bf16 v[68:71], v[164:167], v[216:219], v[68:71]
	s_setprio 0
	s_setprio 1
	v_mfma_f32_16x16x32_bf16 v[124:127], v[168:171], v[188:191], v[124:127]
	v_mfma_f32_16x16x32_bf16 v[120:123], v[176:179], v[188:191], v[120:123]
	v_mfma_f32_16x16x32_bf16 v[112:115], v[168:171], v[196:199], v[112:115]
	v_mfma_f32_16x16x32_bf16 v[96:99], v[176:179], v[196:199], v[96:99]
	v_mfma_f32_16x16x32_bf16 v[88:91], v[168:171], v[204:207], v[88:91]
	v_mfma_f32_16x16x32_bf16 v[80:83], v[176:179], v[204:207], v[80:83]
	v_mfma_f32_16x16x32_bf16 v[72:75], v[168:171], v[212:215], v[72:75]
	v_mfma_f32_16x16x32_bf16 v[64:67], v[176:179], v[212:215], v[64:67]
	v_mfma_f32_16x16x32_bf16 v[124:127], v[172:175], v[192:195], v[124:127]
	v_mfma_f32_16x16x32_bf16 v[120:123], v[180:183], v[192:195], v[120:123]
	v_mfma_f32_16x16x32_bf16 v[112:115], v[172:175], v[200:203], v[112:115]
	v_mfma_f32_16x16x32_bf16 v[96:99], v[180:183], v[200:203], v[96:99]
	v_mfma_f32_16x16x32_bf16 v[88:91], v[172:175], v[208:211], v[88:91]
	v_mfma_f32_16x16x32_bf16 v[80:83], v[180:183], v[208:211], v[80:83]
	v_mfma_f32_16x16x32_bf16 v[72:75], v[172:175], v[216:219], v[72:75]
	v_mfma_f32_16x16x32_bf16 v[64:67], v[180:183], v[216:219], v[64:67]
	s_barrier
	s_setprio 0
	s_add_i32 s58, s46, s36
	v_lshl_add_u64 v[184:185], s[28:29], 0, v[132:133]
	s_mov_b32 m0, s58
	ds_read_b128 v[188:191], v149 offset:16384
	ds_read_b128 v[192:195], v149 offset:17408
	ds_read_b128 v[196:199], v149 offset:18432
	ds_read_b128 v[200:203], v149 offset:19456
	ds_read_b128 v[204:207], v149 offset:20480
	ds_read_b128 v[208:211], v149 offset:21504
	ds_read_b128 v[212:215], v149 offset:22528
	ds_read_b128 v[216:219], v149 offset:23552
	global_load_lds_dwordx4 v[184:185], off
	s_add_i32 m0, s58, 0x2000
	s_add_u32 s58, s28, 0x40000
	v_lshl_add_u64 v[220:221], s[28:29], 0, v[128:129]
	s_addc_u32 s59, s29, 0
	s_add_i32 s69, s47, s36
	global_load_lds_dwordx4 v[220:221], off
	v_lshl_add_u64 v[222:223], s[58:59], 0, v[132:133]
	s_mov_b32 m0, s69
	v_lshl_add_u64 v[224:225], s[30:31], 0, v[130:131]
	global_load_lds_dwordx4 v[222:223], off
	v_lshl_add_u64 v[222:223], s[58:59], 0, v[128:129]
	s_add_i32 m0, s69, 0x2000
	s_nop 0
	global_load_lds_dwordx4 v[222:223], off
	v_lshl_add_u64 v[222:223], s[30:31], 0, v[134:135]
	s_mov_b32 m0, s25
	s_nop 0
	global_load_lds_dwordx4 v[222:223], off
	s_mov_b32 m0, s39
	s_nop 0
	global_load_lds_dwordx4 v[224:225], off
	s_waitcnt vmcnt(8)
	s_waitcnt lgkmcnt(0)
	s_barrier
; #define PG8_STAGE(bufoff, gbase, voff) do { _Pragma("unroll") for (int _i = 0; _i < 2; ++_i) \
;         __builtin_amdgcn_global_load_lds((const unsigned*)((const char*)(gbase) + (voff)[_i]), (PG8_LAS unsigned*)(lds + (bufoff) + ldsw + _i * 8192), 16, 0, 0); } while (0)
; #define PG8_LDA(dst, b, h) do { _Pragma("unroll") for (int m = 0; m < 4; ++m) _Pragma("unroll") for (int k = 0; k < 2; ++k) dst[m][k] = *(const PG8_LAS bf16x8*)(lds + PG8_SA(b, h) + aoff + m * 2048 + k * 1024); } while (0)
; #define PG8_LDB(dst, b, h) do { _Pragma("unroll") for (int n = 0; n < 2; ++n) _Pragma("unroll") for (int k = 0; k < 2; ++k) dst[n][k] = *(const PG8_LAS bf16x8*)(lds + PG8_SB(b, h) + boff + n * 2048 + k * 1024); } while (0)
; #define PG8_MMA(ai, bj, At, Bt) do { __builtin_amdgcn_s_setprio(1); _Pragma("unroll") for (int m = 0; m < 4; ++m) _Pragma("unroll") for (int n = 0; n < 2; ++n) _Pragma("unroll") for (int k = 0; k < 2; ++k) \
;         acc[ai][bj][m][n] = __builtin_amdgcn_mfma_f32_16x16x32_bf16(Bt[n][k], At[m][k], acc[ai][bj][m][n], 0, 0, 0); __builtin_amdgcn_s_setprio(0); } while (0)
; #define PG8_WAIT_V(n) asm volatile("s_waitcnt vmcnt(" #n ")" ::: "memory")
; #define PG8_WAIT_L(n) asm volatile("s_waitcnt lgkmcnt(" #n ")" ::: "memory")
; #define PG8_BAR __builtin_amdgcn_s_barrier()
; #define PG8_SCHED __builtin_amdgcn_sched_barrier(0)
; template <class Epi, class Sched, bool ALIGN_EPI = false, bool SP2 = false>
; __device__ __forceinline__ void gemm_phase(PG8_LAS unsigned char* lds, const Gemm g, const Sched& S, const Epi& E) {
;     ...
;             PG8_WAIT_V(8); PG8_WAIT_L(0); PG8_BAR; PG8_MMA(1, 0, At, B0); PG8_MMA(1, 1, At, B1); PG8_BAR; PG8_SCHED;
;             PG8_LDB(B0, 1, 0); PG8_LDB(B1, 1, 1); PG8_SCHED; PG8_LDA(At, 1, 0); PG8_STAGE(PG8_SA(0, 1), a2 + hstepA, voffA);
;             PG8_WAIT_V(8); PG8_WAIT_L(0); PG8_BAR; PG8_MMA(0, 0, At, B0); PG8_MMA(0, 1, At, B1); PG8_BAR; PG8_SCHED;
	s_setprio 1
	s_waitcnt lgkmcnt(0)
	v_mfma_f32_16x16x32_bf16 v[60:63], v[152:155], v[188:191], v[60:63]
	v_mfma_f32_16x16x32_bf16 v[52:55], v[160:163], v[188:191], v[52:55]
	v_mfma_f32_16x16x32_bf16 v[44:47], v[152:155], v[196:199], v[44:47]
	v_mfma_f32_16x16x32_bf16 v[36:39], v[160:163], v[196:199], v[36:39]
	v_mfma_f32_16x16x32_bf16 v[28:31], v[152:155], v[204:207], v[28:31]
	v_mfma_f32_16x16x32_bf16 v[20:23], v[160:163], v[204:207], v[20:23]
	v_mfma_f32_16x16x32_bf16 v[12:15], v[152:155], v[212:215], v[12:15]
	v_mfma_f32_16x16x32_bf16 v[4:7], v[160:163], v[212:215], v[4:7]
	v_mfma_f32_16x16x32_bf16 v[60:63], v[156:159], v[192:195], v[60:63]
	v_mfma_f32_16x16x32_bf16 v[52:55], v[164:167], v[192:195], v[52:55]
	v_mfma_f32_16x16x32_bf16 v[44:47], v[156:159], v[200:203], v[44:47]
	v_mfma_f32_16x16x32_bf16 v[36:39], v[164:167], v[200:203], v[36:39]
	v_mfma_f32_16x16x32_bf16 v[28:31], v[156:159], v[208:211], v[28:31]
	v_mfma_f32_16x16x32_bf16 v[20:23], v[164:167], v[208:211], v[20:23]
	v_mfma_f32_16x16x32_bf16 v[12:15], v[156:159], v[216:219], v[12:15]
	v_mfma_f32_16x16x32_bf16 v[4:7], v[164:167], v[216:219], v[4:7]
	s_setprio 0
	s_setprio 1
	v_mfma_f32_16x16x32_bf16 v[56:59], v[168:171], v[188:191], v[56:59]
	v_mfma_f32_16x16x32_bf16 v[48:51], v[176:179], v[188:191], v[48:51]
	v_mfma_f32_16x16x32_bf16 v[40:43], v[168:171], v[196:199], v[40:43]
	v_mfma_f32_16x16x32_bf16 v[32:35], v[176:179], v[196:199], v[32:35]
	v_mfma_f32_16x16x32_bf16 v[24:27], v[168:171], v[204:207], v[24:27]
	v_mfma_f32_16x16x32_bf16 v[16:19], v[176:179], v[204:207], v[16:19]
	v_mfma_f32_16x16x32_bf16 v[8:11], v[168:171], v[212:215], v[8:11]
	v_mfma_f32_16x16x32_bf16 v[0:3], v[176:179], v[212:215], v[0:3]
	v_mfma_f32_16x16x32_bf16 v[56:59], v[172:175], v[192:195], v[56:59]
	v_mfma_f32_16x16x32_bf16 v[48:51], v[180:183], v[192:195], v[48:51]
	v_mfma_f32_16x16x32_bf16 v[40:43], v[172:175], v[200:203], v[40:43]
	v_mfma_f32_16x16x32_bf16 v[32:35], v[180:183], v[200:203], v[32:35]
	v_mfma_f32_16x16x32_bf16 v[24:27], v[172:175], v[208:211], v[24:27]
	v_mfma_f32_16x16x32_bf16 v[16:19], v[180:183], v[208:211], v[16:19]
	v_mfma_f32_16x16x32_bf16 v[8:11], v[172:175], v[216:219], v[8:11]
	v_mfma_f32_16x16x32_bf16 v[0:3], v[180:183], v[216:219], v[0:3]
	s_barrier
	s_setprio 0
	s_add_i32 s58, 0, 0x18000
	v_add_u32_e32 v151, s58, v145
	s_add_i32 s59, 0, 0x1c000
	ds_read_b128 v[152:155], v151
	ds_read_b128 v[156:159], v151 offset:1024
	ds_read_b128 v[160:163], v151 offset:2048
	ds_read_b128 v[164:167], v151 offset:3072
	v_add_u32_e32 v151, s59, v145
	ds_read_b128 v[168:171], v151
	ds_read_b128 v[172:175], v151 offset:1024
	ds_read_b128 v[176:179], v151 offset:2048
	ds_read_b128 v[180:183], v151 offset:3072
	s_add_u32 s30, s30, 0x40000
	s_addc_u32 s31, s31, 0
	s_mov_b32 m0, s40
	v_lshl_add_u64 v[226:227], s[30:31], 0, v[134:135]
	ds_read_b128 v[188:191], v149 offset:32768
	ds_read_b128 v[192:195], v149 offset:33792
	ds_read_b128 v[196:199], v149 offset:34816
	ds_read_b128 v[200:203], v149 offset:35840
	ds_read_b128 v[204:207], v149 offset:36864
	ds_read_b128 v[208:211], v149 offset:37888
	ds_read_b128 v[212:215], v149 offset:38912
	ds_read_b128 v[216:219], v149 offset:39936
	global_load_lds_dwordx4 v[226:227], off
	v_lshl_add_u64 v[226:227], s[30:31], 0, v[130:131]
	s_mov_b32 m0, s41
	s_nop 0
	global_load_lds_dwordx4 v[226:227], off
	s_waitcnt vmcnt(8)
	s_waitcnt lgkmcnt(0)
	s_barrier
	s_setprio 1
	s_waitcnt lgkmcnt(0)
	v_mfma_f32_16x16x32_bf16 v[116:119], v[152:155], v[188:191], v[116:119]
	v_mfma_f32_16x16x32_bf16 v[108:111], v[160:163], v[188:191], v[108:111]
	v_mfma_f32_16x16x32_bf16 v[104:107], v[152:155], v[196:199], v[104:107]
	v_mfma_f32_16x16x32_bf16 v[100:103], v[160:163], v[196:199], v[100:103]
	v_mfma_f32_16x16x32_bf16 v[92:95], v[152:155], v[204:207], v[92:95]
	v_mfma_f32_16x16x32_bf16 v[84:87], v[160:163], v[204:207], v[84:87]
	v_mfma_f32_16x16x32_bf16 v[76:79], v[152:155], v[212:215], v[76:79]
	v_mfma_f32_16x16x32_bf16 v[68:71], v[160:163], v[212:215], v[68:71]
	v_mfma_f32_16x16x32_bf16 v[116:119], v[156:159], v[192:195], v[116:119]
	v_mfma_f32_16x16x32_bf16 v[108:111], v[164:167], v[192:195], v[108:111]
	v_mfma_f32_16x16x32_bf16 v[104:107], v[156:159], v[200:203], v[104:107]
	v_mfma_f32_16x16x32_bf16 v[100:103], v[164:167], v[200:203], v[100:103]
	v_mfma_f32_16x16x32_bf16 v[92:95], v[156:159], v[208:211], v[92:95]
	v_mfma_f32_16x16x32_bf16 v[84:87], v[164:167], v[208:211], v[84:87]
	v_mfma_f32_16x16x32_bf16 v[76:79], v[156:159], v[216:219], v[76:79]
	v_mfma_f32_16x16x32_bf16 v[68:71], v[164:167], v[216:219], v[68:71]
	s_setprio 0
	s_setprio 1
	v_mfma_f32_16x16x32_bf16 v[124:127], v[168:171], v[188:191], v[124:127]
	v_mfma_f32_16x16x32_bf16 v[120:123], v[176:179], v[188:191], v[120:123]
	v_mfma_f32_16x16x32_bf16 v[112:115], v[168:171], v[196:199], v[112:115]
	v_mfma_f32_16x16x32_bf16 v[96:99], v[176:179], v[196:199], v[96:99]
	v_mfma_f32_16x16x32_bf16 v[88:91], v[168:171], v[204:207], v[88:91]
	v_mfma_f32_16x16x32_bf16 v[80:83], v[176:179], v[204:207], v[80:83]
	v_mfma_f32_16x16x32_bf16 v[72:75], v[168:171], v[212:215], v[72:75]
	v_mfma_f32_16x16x32_bf16 v[64:67], v[176:179], v[212:215], v[64:67]
	v_mfma_f32_16x16x32_bf16 v[124:127], v[172:175], v[192:195], v[124:127]
	v_mfma_f32_16x16x32_bf16 v[120:123], v[180:183], v[192:195], v[120:123]
	v_mfma_f32_16x16x32_bf16 v[112:115], v[172:175], v[200:203], v[112:115]
	v_mfma_f32_16x16x32_bf16 v[96:99], v[180:183], v[200:203], v[96:99]
	v_mfma_f32_16x16x32_bf16 v[88:91], v[172:175], v[208:211], v[88:91]
	v_mfma_f32_16x16x32_bf16 v[80:83], v[180:183], v[208:211], v[80:83]
	v_mfma_f32_16x16x32_bf16 v[72:75], v[172:175], v[216:219], v[72:75]
	v_mfma_f32_16x16x32_bf16 v[64:67], v[180:183], v[216:219], v[64:67]
	s_barrier
; #define PG8_STAGE(bufoff, gbase, voff) do { _Pragma("unroll") for (int _i = 0; _i < 2; ++_i) \
;         __builtin_amdgcn_global_load_lds((const unsigned*)((const char*)(gbase) + (voff)[_i]), (PG8_LAS unsigned*)(lds + (bufoff) + ldsw + _i * 8192), 16, 0, 0); } while (0)
; #define PG8_LDA(dst, b, h) do { _Pragma("unroll") for (int m = 0; m < 4; ++m) _Pragma("unroll") for (int k = 0; k < 2; ++k) dst[m][k] = *(const PG8_LAS bf16x8*)(lds + PG8_SA(b, h) + aoff + m * 2048 + k * 1024); } while (0)
; #define PG8_MMA(ai, bj, At, Bt) do { __builtin_amdgcn_s_setprio(1); _Pragma("unroll") for (int m = 0; m < 4; ++m) _Pragma("unroll") for (int n = 0; n < 2; ++n) _Pragma("unroll") for (int k = 0; k < 2; ++k) \
;         acc[ai][bj][m][n] = __builtin_amdgcn_mfma_f32_16x16x32_bf16(Bt[n][k], At[m][k], acc[ai][bj][m][n], 0, 0, 0); __builtin_amdgcn_s_setprio(0); } while (0)
; #define PG8_WAIT_V(n) asm volatile("s_waitcnt vmcnt(" #n ")" ::: "memory")
; #define PG8_WAIT_L(n) asm volatile("s_waitcnt lgkmcnt(" #n ")" ::: "memory")
; #define PG8_BAR __builtin_amdgcn_s_barrier()
; #define PG8_SCHED __builtin_amdgcn_sched_barrier(0)
; template <class Epi, class Sched, bool ALIGN_EPI = false, bool SP2 = false>
; __device__ __forceinline__ void gemm_phase(PG8_LAS unsigned char* lds, const Gemm g, const Sched& S, const Epi& E) {
;     ...
;             PG8_LDA(At, 1, 1); PG8_STAGE(PG8_SB(1, 0), b3, voffB); PG8_STAGE(PG8_SB(1, 1), b3 + hstepB, voffB); PG8_STAGE(PG8_SA(1, 0), a3, voffA);
;             PG8_WAIT_V(8); PG8_WAIT_L(0); PG8_BAR; PG8_MMA(1, 0, At, B0); PG8_MMA(1, 1, At, B1); PG8_BAR; PG8_SCHED;
	s_setprio 0
	s_add_i32 s30, s58, s36
	v_lshl_add_u64 v[184:185], v[184:185], 0, s[8:9]
	s_mov_b32 m0, s30
	ds_read_b128 v[188:191], v149 offset:49152
	ds_read_b128 v[192:195], v149 offset:50176
	ds_read_b128 v[196:199], v149 offset:51200
	ds_read_b128 v[200:203], v149 offset:52224
	ds_read_b128 v[204:207], v149 offset:53248
	ds_read_b128 v[208:211], v149 offset:54272
	ds_read_b128 v[212:215], v149 offset:55296
	ds_read_b128 v[216:219], v149 offset:56320
	global_load_lds_dwordx4 v[184:185], off
	s_add_i32 m0, s30, 0x2000
	s_add_u32 s28, s28, 0x40080
	v_lshl_add_u64 v[184:185], v[220:221], 0, s[8:9]
	s_addc_u32 s29, s29, 0
	s_add_i32 s30, s59, s36
	global_load_lds_dwordx4 v[184:185], off
	v_lshl_add_u64 v[184:185], s[28:29], 0, v[132:133]
	s_mov_b32 m0, s30
	s_nop 0
	global_load_lds_dwordx4 v[184:185], off
	v_lshl_add_u64 v[184:185], s[28:29], 0, v[128:129]
	s_add_i32 m0, s30, 0x2000
	s_nop 0
	global_load_lds_dwordx4 v[184:185], off
	v_lshl_add_u64 v[184:185], v[222:223], 0, s[8:9]
	s_mov_b32 m0, s43
	s_nop 0
	global_load_lds_dwordx4 v[184:185], off
	v_lshl_add_u64 v[184:185], v[224:225], 0, s[8:9]
	s_mov_b32 m0, s44
	s_nop 0
	global_load_lds_dwordx4 v[184:185], off
	s_waitcnt vmcnt(8)
	s_waitcnt lgkmcnt(0)
	s_barrier
	s_setprio 1
	s_waitcnt lgkmcnt(0)
	v_mfma_f32_16x16x32_bf16 v[60:63], v[152:155], v[188:191], v[60:63]
	v_mfma_f32_16x16x32_bf16 v[52:55], v[160:163], v[188:191], v[52:55]
	v_mfma_f32_16x16x32_bf16 v[44:47], v[152:155], v[196:199], v[44:47]
	v_mfma_f32_16x16x32_bf16 v[36:39], v[160:163], v[196:199], v[36:39]
	v_mfma_f32_16x16x32_bf16 v[28:31], v[152:155], v[204:207], v[28:31]
	v_mfma_f32_16x16x32_bf16 v[20:23], v[160:163], v[204:207], v[20:23]
	v_mfma_f32_16x16x32_bf16 v[12:15], v[152:155], v[212:215], v[12:15]
	v_mfma_f32_16x16x32_bf16 v[4:7], v[160:163], v[212:215], v[4:7]
	v_mfma_f32_16x16x32_bf16 v[60:63], v[156:159], v[192:195], v[60:63]
	v_mfma_f32_16x16x32_bf16 v[52:55], v[164:167], v[192:195], v[52:55]
	v_mfma_f32_16x16x32_bf16 v[44:47], v[156:159], v[200:203], v[44:47]
	v_mfma_f32_16x16x32_bf16 v[36:39], v[164:167], v[200:203], v[36:39]
	v_mfma_f32_16x16x32_bf16 v[28:31], v[156:159], v[208:211], v[28:31]
	v_mfma_f32_16x16x32_bf16 v[20:23], v[164:167], v[208:211], v[20:23]
	v_mfma_f32_16x16x32_bf16 v[12:15], v[156:159], v[216:219], v[12:15]
	v_mfma_f32_16x16x32_bf16 v[4:7], v[164:167], v[216:219], v[4:7]
	s_setprio 0
	s_setprio 1
	v_mfma_f32_16x16x32_bf16 v[56:59], v[168:171], v[188:191], v[56:59]
	v_mfma_f32_16x16x32_bf16 v[48:51], v[176:179], v[188:191], v[48:51]
	v_mfma_f32_16x16x32_bf16 v[40:43], v[168:171], v[196:199], v[40:43]
	v_mfma_f32_16x16x32_bf16 v[32:35], v[176:179], v[196:199], v[32:35]
	v_mfma_f32_16x16x32_bf16 v[24:27], v[168:171], v[204:207], v[24:27]
	v_mfma_f32_16x16x32_bf16 v[16:19], v[176:179], v[204:207], v[16:19]
	v_mfma_f32_16x16x32_bf16 v[8:11], v[168:171], v[212:215], v[8:11]
	v_mfma_f32_16x16x32_bf16 v[0:3], v[176:179], v[212:215], v[0:3]
	v_mfma_f32_16x16x32_bf16 v[56:59], v[172:175], v[192:195], v[56:59]
	v_mfma_f32_16x16x32_bf16 v[48:51], v[180:183], v[192:195], v[48:51]
	v_mfma_f32_16x16x32_bf16 v[40:43], v[172:175], v[200:203], v[40:43]
	v_mfma_f32_16x16x32_bf16 v[32:35], v[180:183], v[200:203], v[32:35]
	v_mfma_f32_16x16x32_bf16 v[24:27], v[172:175], v[208:211], v[24:27]
	v_mfma_f32_16x16x32_bf16 v[16:19], v[180:183], v[208:211], v[16:19]
	v_mfma_f32_16x16x32_bf16 v[8:11], v[172:175], v[216:219], v[8:11]
	v_mfma_f32_16x16x32_bf16 v[0:3], v[180:183], v[216:219], v[0:3]
	s_barrier
	s_setprio 0
	s_add_i32 s68, s68, 2
	s_add_u32 s26, s26, 0x100
	s_addc_u32 s27, s27, 0
	s_add_u32 s66, s66, 0x100
	s_addc_u32 s67, s67, 0
	s_cmp_gt_u32 s68, 13
	s_cbranch_scc0 .LBB0_244
	s_and_b64 vcc, exec, s[10:11]
	s_cbranch_vccz .LBB0_247
	s_barrier

; #define PG8_STAGE(bufoff, gbase, voff) do { _Pragma("unroll") for (int _i = 0; _i < 2; ++_i) \
;         __builtin_amdgcn_global_load_lds((const unsigned*)((const char*)(gbase) + (voff)[_i]), (PG8_LAS unsigned*)(lds + (bufoff) + ldsw + _i * 8192), 16, 0, 0); } while (0)
; #define PG8_LDA(dst, b, h) do { _Pragma("unroll") for (int m = 0; m < 4; ++m) _Pragma("unroll") for (int k = 0; k < 2; ++k) dst[m][k] = *(const PG8_LAS bf16x8*)(lds + PG8_SA(b, h) + aoff + m * 2048 + k * 1024); } while (0)
; #define PG8_LDB(dst, b, h) do { _Pragma("unroll") for (int n = 0; n < 2; ++n) _Pragma("unroll") for (int k = 0; k < 2; ++k) dst[n][k] = *(const PG8_LAS bf16x8*)(lds + PG8_SB(b, h) + boff + n * 2048 + k * 1024); } while (0)
; #define PG8_MMA(ai, bj, At, Bt) do { __builtin_amdgcn_s_setprio(1); _Pragma("unroll") for (int m = 0; m < 4; ++m) _Pragma("unroll") for (int n = 0; n < 2; ++n) _Pragma("unroll") for (int k = 0; k < 2; ++k) \
;         acc[ai][bj][m][n] = __builtin_amdgcn_mfma_f32_16x16x32_bf16(Bt[n][k], At[m][k], acc[ai][bj][m][n], 0, 0, 0); __builtin_amdgcn_s_setprio(0); } while (0)
; #define PG8_WAIT_V(n) asm volatile("s_waitcnt vmcnt(" #n ")" ::: "memory")
; #define PG8_WAIT_L(n) asm volatile("s_waitcnt lgkmcnt(" #n ")" ::: "memory")
; #define PG8_BAR __builtin_amdgcn_s_barrier()
; #define PG8_SCHED __builtin_amdgcn_sched_barrier(0)
; template <class Epi, class Sched, bool ALIGN_EPI = false, bool SP2 = false>
; __device__ __forceinline__ void gemm_phase(PG8_LAS unsigned char* lds, const Gemm g, const Sched& S, const Epi& E) {
;     ...
;             PG8_LDB(B0, 0, 0); PG8_LDB(B1, 0, 1); PG8_SCHED; PG8_LDA(At, 0, 0); PG8_STAGE(PG8_SA(1, 1), a1 + hstepA, voffA);
;             PG8_WAIT_V(8); PG8_WAIT_L(0); PG8_BAR; PG8_MMA(0, 0, At, B0); PG8_MMA(0, 1, At, B1); PG8_BAR; PG8_SCHED;
;             PG8_LDA(At, 0, 1); PG8_STAGE(PG8_SB(0, 0), b2, voffB); PG8_STAGE(PG8_SB(0, 1), b2 + hstepB, voffB); PG8_STAGE(PG8_SA(0, 0), a2, voffA);
.LBB0_318:
	ds_read_b128 v[128:131], v191
	ds_read_b128 v[132:135], v191 offset:1024
	ds_read_b128 v[136:139], v191 offset:2048
	ds_read_b128 v[140:143], v191 offset:3072
	ds_read_b128 v[144:147], v192
	ds_read_b128 v[148:151], v192 offset:1024
	ds_read_b128 v[168:171], v192 offset:2048
	ds_read_b128 v[172:175], v192 offset:3072
	s_add_u32 s28, s26, 0x100
	s_addc_u32 s29, s27, 0
	s_cmp_eq_u32 s72, 40
	s_cselect_b32 s35, s11, s29
	s_cselect_b32 s34, s10, s28
	s_cselect_b32 s31, s23, s71
	s_cselect_b32 s30, s22, s70
	v_lshl_add_u64 v[184:185], s[26:27], 0, v[160:161]
	s_add_i32 m0, s39, 0xc000
	ds_read_b128 v[176:179], v193
	ds_read_b128 v[180:183], v193 offset:1024
	ds_read_b128 v[196:199], v193 offset:2048
	ds_read_b128 v[200:203], v193 offset:3072
	ds_read_b128 v[204:207], v193 offset:4096
	ds_read_b128 v[208:211], v193 offset:5120
	ds_read_b128 v[212:215], v193 offset:6144
	ds_read_b128 v[216:219], v193 offset:7168
	global_load_lds_dwordx4 v[184:185], off
	v_lshl_add_u64 v[184:185], s[26:27], 0, v[162:163]
	s_add_i32 m0, s39, 0xe000
	s_nop 0
	global_load_lds_dwordx4 v[184:185], off
	s_waitcnt vmcnt(8)
	s_waitcnt lgkmcnt(0)
	s_barrier
	s_setprio 1
	s_waitcnt lgkmcnt(0)
	v_mfma_f32_16x16x32_bf16 v[124:127], v[128:131], v[176:179], v[124:127]
	v_mfma_f32_16x16x32_bf16 v[120:123], v[136:139], v[176:179], v[120:123]
	v_mfma_f32_16x16x32_bf16 v[108:111], v[128:131], v[196:199], v[108:111]
	v_mfma_f32_16x16x32_bf16 v[104:107], v[136:139], v[196:199], v[104:107]
	v_mfma_f32_16x16x32_bf16 v[92:95], v[128:131], v[204:207], v[92:95]
	v_mfma_f32_16x16x32_bf16 v[88:91], v[136:139], v[204:207], v[88:91]
	v_mfma_f32_16x16x32_bf16 v[76:79], v[128:131], v[212:215], v[76:79]
	v_mfma_f32_16x16x32_bf16 v[72:75], v[136:139], v[212:215], v[72:75]
	v_mfma_f32_16x16x32_bf16 v[124:127], v[132:135], v[180:183], v[124:127]
	v_mfma_f32_16x16x32_bf16 v[120:123], v[140:143], v[180:183], v[120:123]
	v_mfma_f32_16x16x32_bf16 v[108:111], v[132:135], v[200:203], v[108:111]
	v_mfma_f32_16x16x32_bf16 v[104:107], v[140:143], v[200:203], v[104:107]
	v_mfma_f32_16x16x32_bf16 v[92:95], v[132:135], v[208:211], v[92:95]
	v_mfma_f32_16x16x32_bf16 v[88:91], v[140:143], v[208:211], v[88:91]
	v_mfma_f32_16x16x32_bf16 v[76:79], v[132:135], v[216:219], v[76:79]
	v_mfma_f32_16x16x32_bf16 v[72:75], v[140:143], v[216:219], v[72:75]
	s_setprio 0
	s_setprio 1
	v_mfma_f32_16x16x32_bf16 v[116:119], v[144:147], v[176:179], v[116:119]
	v_mfma_f32_16x16x32_bf16 v[112:115], v[168:171], v[176:179], v[112:115]
	v_mfma_f32_16x16x32_bf16 v[100:103], v[144:147], v[196:199], v[100:103]
	v_mfma_f32_16x16x32_bf16 v[96:99], v[168:171], v[196:199], v[96:99]
	v_mfma_f32_16x16x32_bf16 v[84:87], v[144:147], v[204:207], v[84:87]
	v_mfma_f32_16x16x32_bf16 v[80:83], v[168:171], v[204:207], v[80:83]
	v_mfma_f32_16x16x32_bf16 v[68:71], v[144:147], v[212:215], v[68:71]
	v_mfma_f32_16x16x32_bf16 v[64:67], v[168:171], v[212:215], v[64:67]
	v_mfma_f32_16x16x32_bf16 v[116:119], v[148:151], v[180:183], v[116:119]
	v_mfma_f32_16x16x32_bf16 v[112:115], v[172:175], v[180:183], v[112:115]
	v_mfma_f32_16x16x32_bf16 v[100:103], v[148:151], v[200:203], v[100:103]
	v_mfma_f32_16x16x32_bf16 v[96:99], v[172:175], v[200:203], v[96:99]
	v_mfma_f32_16x16x32_bf16 v[84:87], v[148:151], v[208:211], v[84:87]
	v_mfma_f32_16x16x32_bf16 v[80:83], v[172:175], v[208:211], v[80:83]
	v_mfma_f32_16x16x32_bf16 v[68:71], v[148:151], v[216:219], v[68:71]
	v_mfma_f32_16x16x32_bf16 v[64:67], v[172:175], v[216:219], v[64:67]
	s_barrier
	s_setprio 0
	s_add_i32 s26, s49, s38
	v_lshl_add_u64 v[184:185], s[30:31], 0, v[154:155]
	s_mov_b32 m0, s26
	ds_read_b128 v[176:179], v193 offset:16384
	ds_read_b128 v[180:183], v193 offset:17408
	ds_read_b128 v[196:199], v193 offset:18432
	ds_read_b128 v[200:203], v193 offset:19456
	ds_read_b128 v[204:207], v193 offset:20480
	ds_read_b128 v[208:211], v193 offset:21504
	ds_read_b128 v[212:215], v193 offset:22528
	ds_read_b128 v[216:219], v193 offset:23552
	global_load_lds_dwordx4 v[184:185], off
	s_add_i32 m0, s26, 0x2000
	s_add_u32 s26, s30, 0xb0000
	v_lshl_add_u64 v[220:221], s[30:31], 0, v[158:159]
	s_addc_u32 s27, s31, 0
	s_add_i32 s58, s62, s38
	global_load_lds_dwordx4 v[220:221], off
	v_lshl_add_u64 v[222:223], s[26:27], 0, v[154:155]
	s_mov_b32 m0, s58
	v_lshl_add_u64 v[224:225], s[34:35], 0, v[156:157]
	global_load_lds_dwordx4 v[222:223], off
	v_lshl_add_u64 v[222:223], s[26:27], 0, v[158:159]
	s_add_i32 m0, s58, 0x2000
	s_nop 0
	global_load_lds_dwordx4 v[222:223], off
	v_lshl_add_u64 v[222:223], s[34:35], 0, v[152:153]
	s_mov_b32 m0, s39
	s_nop 0
	global_load_lds_dwordx4 v[222:223], off
	s_mov_b32 m0, s40
	s_nop 0
	global_load_lds_dwordx4 v[224:225], off
	s_waitcnt vmcnt(8)
	s_waitcnt lgkmcnt(0)
	s_barrier
; #define PG8_STAGE(bufoff, gbase, voff) do { _Pragma("unroll") for (int _i = 0; _i < 2; ++_i) \
;         __builtin_amdgcn_global_load_lds((const unsigned*)((const char*)(gbase) + (voff)[_i]), (PG8_LAS unsigned*)(lds + (bufoff) + ldsw + _i * 8192), 16, 0, 0); } while (0)
; #define PG8_LDA(dst, b, h) do { _Pragma("unroll") for (int m = 0; m < 4; ++m) _Pragma("unroll") for (int k = 0; k < 2; ++k) dst[m][k] = *(const PG8_LAS bf16x8*)(lds + PG8_SA(b, h) + aoff + m * 2048 + k * 1024); } while (0)
; #define PG8_LDB(dst, b, h) do { _Pragma("unroll") for (int n = 0; n < 2; ++n) _Pragma("unroll") for (int k = 0; k < 2; ++k) dst[n][k] = *(const PG8_LAS bf16x8*)(lds + PG8_SB(b, h) + boff + n * 2048 + k * 1024); } while (0)
; #define PG8_MMA(ai, bj, At, Bt) do { __builtin_amdgcn_s_setprio(1); _Pragma("unroll") for (int m = 0; m < 4; ++m) _Pragma("unroll") for (int n = 0; n < 2; ++n) _Pragma("unroll") for (int k = 0; k < 2; ++k) \
;         acc[ai][bj][m][n] = __builtin_amdgcn_mfma_f32_16x16x32_bf16(Bt[n][k], At[m][k], acc[ai][bj][m][n], 0, 0, 0); __builtin_amdgcn_s_setprio(0); } while (0)
; #define PG8_WAIT_V(n) asm volatile("s_waitcnt vmcnt(" #n ")" ::: "memory")
; #define PG8_WAIT_L(n) asm volatile("s_waitcnt lgkmcnt(" #n ")" ::: "memory")
; #define PG8_BAR __builtin_amdgcn_s_barrier()
; #define PG8_SCHED __builtin_amdgcn_sched_barrier(0)
; template <class Epi, class Sched, bool ALIGN_EPI = false, bool SP2 = false>
; __device__ __forceinline__ void gemm_phase(PG8_LAS unsigned char* lds, const Gemm g, const Sched& S, const Epi& E) {
;     ...
;             PG8_WAIT_V(8); PG8_WAIT_L(0); PG8_BAR; PG8_MMA(1, 0, At, B0); PG8_MMA(1, 1, At, B1); PG8_BAR; PG8_SCHED;
;             PG8_LDB(B0, 1, 0); PG8_LDB(B1, 1, 1); PG8_SCHED; PG8_LDA(At, 1, 0); PG8_STAGE(PG8_SA(0, 1), a2 + hstepA, voffA);
;             PG8_WAIT_V(8); PG8_WAIT_L(0); PG8_BAR; PG8_MMA(0, 0, At, B0); PG8_MMA(0, 1, At, B1); PG8_BAR; PG8_SCHED;
	s_setprio 1
	s_waitcnt lgkmcnt(0)
	v_mfma_f32_16x16x32_bf16 v[60:63], v[128:131], v[176:179], v[60:63]
	v_mfma_f32_16x16x32_bf16 v[56:59], v[136:139], v[176:179], v[56:59]
	v_mfma_f32_16x16x32_bf16 v[44:47], v[128:131], v[196:199], v[44:47]
	v_mfma_f32_16x16x32_bf16 v[40:43], v[136:139], v[196:199], v[40:43]
	v_mfma_f32_16x16x32_bf16 v[28:31], v[128:131], v[204:207], v[28:31]
	v_mfma_f32_16x16x32_bf16 v[24:27], v[136:139], v[204:207], v[24:27]
	v_mfma_f32_16x16x32_bf16 v[12:15], v[128:131], v[212:215], v[12:15]
	v_mfma_f32_16x16x32_bf16 v[8:11], v[136:139], v[212:215], v[8:11]
	v_mfma_f32_16x16x32_bf16 v[60:63], v[132:135], v[180:183], v[60:63]
	v_mfma_f32_16x16x32_bf16 v[56:59], v[140:143], v[180:183], v[56:59]
	v_mfma_f32_16x16x32_bf16 v[44:47], v[132:135], v[200:203], v[44:47]
	v_mfma_f32_16x16x32_bf16 v[40:43], v[140:143], v[200:203], v[40:43]
	v_mfma_f32_16x16x32_bf16 v[28:31], v[132:135], v[208:211], v[28:31]
	v_mfma_f32_16x16x32_bf16 v[24:27], v[140:143], v[208:211], v[24:27]
	v_mfma_f32_16x16x32_bf16 v[12:15], v[132:135], v[216:219], v[12:15]
	v_mfma_f32_16x16x32_bf16 v[8:11], v[140:143], v[216:219], v[8:11]
	s_setprio 0
	s_setprio 1
	v_mfma_f32_16x16x32_bf16 v[52:55], v[144:147], v[176:179], v[52:55]
	v_mfma_f32_16x16x32_bf16 v[48:51], v[168:171], v[176:179], v[48:51]
	v_mfma_f32_16x16x32_bf16 v[36:39], v[144:147], v[196:199], v[36:39]
	v_mfma_f32_16x16x32_bf16 v[32:35], v[168:171], v[196:199], v[32:35]
	v_mfma_f32_16x16x32_bf16 v[20:23], v[144:147], v[204:207], v[20:23]
	v_mfma_f32_16x16x32_bf16 v[16:19], v[168:171], v[204:207], v[16:19]
	v_mfma_f32_16x16x32_bf16 v[4:7], v[144:147], v[212:215], v[4:7]
	v_mfma_f32_16x16x32_bf16 v[0:3], v[168:171], v[212:215], v[0:3]
	v_mfma_f32_16x16x32_bf16 v[52:55], v[148:151], v[180:183], v[52:55]
	v_mfma_f32_16x16x32_bf16 v[48:51], v[172:175], v[180:183], v[48:51]
	v_mfma_f32_16x16x32_bf16 v[36:39], v[148:151], v[200:203], v[36:39]
	v_mfma_f32_16x16x32_bf16 v[32:35], v[172:175], v[200:203], v[32:35]
	v_mfma_f32_16x16x32_bf16 v[20:23], v[148:151], v[208:211], v[20:23]
	v_mfma_f32_16x16x32_bf16 v[16:19], v[172:175], v[208:211], v[16:19]
	v_mfma_f32_16x16x32_bf16 v[4:7], v[148:151], v[216:219], v[4:7]
	v_mfma_f32_16x16x32_bf16 v[0:3], v[172:175], v[216:219], v[0:3]
	s_barrier
	s_setprio 0
	s_add_i32 s58, 0, 0x18000
	s_add_i32 s59, 0, 0x1c000
	v_add_u32_e32 v140, s58, v189
	v_add_u32_e32 v172, s59, v189
	ds_read_b128 v[128:131], v140
	ds_read_b128 v[132:135], v140 offset:1024
	ds_read_b128 v[136:139], v140 offset:2048
	ds_read_b128 v[140:143], v140 offset:3072
	ds_read_b128 v[144:147], v172
	ds_read_b128 v[148:151], v172 offset:1024
	ds_read_b128 v[168:171], v172 offset:2048
	ds_read_b128 v[172:175], v172 offset:3072
	s_add_u32 s26, s34, 0xb0000
	s_addc_u32 s27, s35, 0
	s_mov_b32 m0, s41
	v_lshl_add_u64 v[226:227], s[26:27], 0, v[152:153]
	ds_read_b128 v[176:179], v193 offset:32768
	ds_read_b128 v[180:183], v193 offset:33792
	ds_read_b128 v[196:199], v193 offset:34816
	ds_read_b128 v[200:203], v193 offset:35840
	ds_read_b128 v[204:207], v193 offset:36864
	ds_read_b128 v[208:211], v193 offset:37888
	ds_read_b128 v[212:215], v193 offset:38912
	ds_read_b128 v[216:219], v193 offset:39936
	global_load_lds_dwordx4 v[226:227], off
	v_lshl_add_u64 v[226:227], s[26:27], 0, v[156:157]
	s_mov_b32 m0, s42
	s_nop 0
	global_load_lds_dwordx4 v[226:227], off
	s_waitcnt vmcnt(8)
	s_waitcnt lgkmcnt(0)
	s_barrier
	s_setprio 1
	s_waitcnt lgkmcnt(0)
	v_mfma_f32_16x16x32_bf16 v[124:127], v[128:131], v[176:179], v[124:127]
	v_mfma_f32_16x16x32_bf16 v[120:123], v[136:139], v[176:179], v[120:123]
	v_mfma_f32_16x16x32_bf16 v[108:111], v[128:131], v[196:199], v[108:111]
	v_mfma_f32_16x16x32_bf16 v[104:107], v[136:139], v[196:199], v[104:107]
	v_mfma_f32_16x16x32_bf16 v[92:95], v[128:131], v[204:207], v[92:95]
	v_mfma_f32_16x16x32_bf16 v[88:91], v[136:139], v[204:207], v[88:91]
	v_mfma_f32_16x16x32_bf16 v[76:79], v[128:131], v[212:215], v[76:79]
	v_mfma_f32_16x16x32_bf16 v[72:75], v[136:139], v[212:215], v[72:75]
	v_mfma_f32_16x16x32_bf16 v[124:127], v[132:135], v[180:183], v[124:127]
	v_mfma_f32_16x16x32_bf16 v[120:123], v[140:143], v[180:183], v[120:123]
	v_mfma_f32_16x16x32_bf16 v[108:111], v[132:135], v[200:203], v[108:111]
	v_mfma_f32_16x16x32_bf16 v[104:107], v[140:143], v[200:203], v[104:107]
	v_mfma_f32_16x16x32_bf16 v[92:95], v[132:135], v[208:211], v[92:95]
	v_mfma_f32_16x16x32_bf16 v[88:91], v[140:143], v[208:211], v[88:91]
	v_mfma_f32_16x16x32_bf16 v[76:79], v[132:135], v[216:219], v[76:79]
	v_mfma_f32_16x16x32_bf16 v[72:75], v[140:143], v[216:219], v[72:75]
	s_setprio 0
	s_setprio 1
	v_mfma_f32_16x16x32_bf16 v[116:119], v[144:147], v[176:179], v[116:119]
	v_mfma_f32_16x16x32_bf16 v[112:115], v[168:171], v[176:179], v[112:115]
	v_mfma_f32_16x16x32_bf16 v[100:103], v[144:147], v[196:199], v[100:103]
	v_mfma_f32_16x16x32_bf16 v[96:99], v[168:171], v[196:199], v[96:99]
	v_mfma_f32_16x16x32_bf16 v[84:87], v[144:147], v[204:207], v[84:87]
	v_mfma_f32_16x16x32_bf16 v[80:83], v[168:171], v[204:207], v[80:83]
	v_mfma_f32_16x16x32_bf16 v[68:71], v[144:147], v[212:215], v[68:71]
	v_mfma_f32_16x16x32_bf16 v[64:67], v[168:171], v[212:215], v[64:67]
	v_mfma_f32_16x16x32_bf16 v[116:119], v[148:151], v[180:183], v[116:119]
	v_mfma_f32_16x16x32_bf16 v[112:115], v[172:175], v[180:183], v[112:115]
	v_mfma_f32_16x16x32_bf16 v[100:103], v[148:151], v[200:203], v[100:103]
	v_mfma_f32_16x16x32_bf16 v[96:99], v[172:175], v[200:203], v[96:99]
	v_mfma_f32_16x16x32_bf16 v[84:87], v[148:151], v[208:211], v[84:87]
	v_mfma_f32_16x16x32_bf16 v[80:83], v[172:175], v[208:211], v[80:83]
	v_mfma_f32_16x16x32_bf16 v[68:71], v[148:151], v[216:219], v[68:71]
	v_mfma_f32_16x16x32_bf16 v[64:67], v[172:175], v[216:219], v[64:67]
	s_barrier
; #define PG8_STAGE(bufoff, gbase, voff) do { _Pragma("unroll") for (int _i = 0; _i < 2; ++_i) \
;         __builtin_amdgcn_global_load_lds((const unsigned*)((const char*)(gbase) + (voff)[_i]), (PG8_LAS unsigned*)(lds + (bufoff) + ldsw + _i * 8192), 16, 0, 0); } while (0)
; #define PG8_LDA(dst, b, h) do { _Pragma("unroll") for (int m = 0; m < 4; ++m) _Pragma("unroll") for (int k = 0; k < 2; ++k) dst[m][k] = *(const PG8_LAS bf16x8*)(lds + PG8_SA(b, h) + aoff + m * 2048 + k * 1024); } while (0)
; #define PG8_MMA(ai, bj, At, Bt) do { __builtin_amdgcn_s_setprio(1); _Pragma("unroll") for (int m = 0; m < 4; ++m) _Pragma("unroll") for (int n = 0; n < 2; ++n) _Pragma("unroll") for (int k = 0; k < 2; ++k) \
;         acc[ai][bj][m][n] = __builtin_amdgcn_mfma_f32_16x16x32_bf16(Bt[n][k], At[m][k], acc[ai][bj][m][n], 0, 0, 0); __builtin_amdgcn_s_setprio(0); } while (0)
; #define PG8_WAIT_V(n) asm volatile("s_waitcnt vmcnt(" #n ")" ::: "memory")
; #define PG8_WAIT_L(n) asm volatile("s_waitcnt lgkmcnt(" #n ")" ::: "memory")
; #define PG8_BAR __builtin_amdgcn_s_barrier()
; #define PG8_SCHED __builtin_amdgcn_sched_barrier(0)
; template <class Epi, class Sched, bool ALIGN_EPI = false, bool SP2 = false>
; __device__ __forceinline__ void gemm_phase(PG8_LAS unsigned char* lds, const Gemm g, const Sched& S, const Epi& E) {
;     ...
;             PG8_LDA(At, 1, 1); PG8_STAGE(PG8_SB(1, 0), b3, voffB); PG8_STAGE(PG8_SB(1, 1), b3 + hstepB, voffB); PG8_STAGE(PG8_SA(1, 0), a3, voffA);
;             PG8_WAIT_V(8); PG8_WAIT_L(0); PG8_BAR; PG8_MMA(1, 0, At, B0); PG8_MMA(1, 1, At, B1); PG8_BAR; PG8_SCHED;
	s_setprio 0
	s_add_i32 s26, s58, s38
	v_lshl_add_u64 v[184:185], v[184:185], 0, s[14:15]
	s_mov_b32 m0, s26
	ds_read_b128 v[176:179], v193 offset:49152
	ds_read_b128 v[180:183], v193 offset:50176
	ds_read_b128 v[196:199], v193 offset:51200
	ds_read_b128 v[200:203], v193 offset:52224
	ds_read_b128 v[204:207], v193 offset:53248
	ds_read_b128 v[208:211], v193 offset:54272
	ds_read_b128 v[212:215], v193 offset:55296
	ds_read_b128 v[216:219], v193 offset:56320
	global_load_lds_dwordx4 v[184:185], off
	s_add_i32 m0, s26, 0x2000
	s_add_u32 s26, s30, 0xb0080
	v_lshl_add_u64 v[184:185], v[220:221], 0, s[14:15]
	s_addc_u32 s27, s31, 0
	s_add_i32 s30, s59, s38
	global_load_lds_dwordx4 v[184:185], off
	v_lshl_add_u64 v[184:185], s[26:27], 0, v[154:155]
	s_mov_b32 m0, s30
	s_nop 0
	global_load_lds_dwordx4 v[184:185], off
	v_lshl_add_u64 v[184:185], s[26:27], 0, v[158:159]
	s_add_i32 m0, s30, 0x2000
	s_nop 0
	global_load_lds_dwordx4 v[184:185], off
	v_lshl_add_u64 v[184:185], v[222:223], 0, s[14:15]
	s_mov_b32 m0, s44
	s_nop 0
	global_load_lds_dwordx4 v[184:185], off
	v_lshl_add_u64 v[184:185], v[224:225], 0, s[14:15]
	s_mov_b32 m0, s45
	s_nop 0
	global_load_lds_dwordx4 v[184:185], off
	s_waitcnt vmcnt(8)
	s_waitcnt lgkmcnt(0)
	s_barrier
	s_setprio 1
	s_waitcnt lgkmcnt(0)
	v_mfma_f32_16x16x32_bf16 v[60:63], v[128:131], v[176:179], v[60:63]
	v_mfma_f32_16x16x32_bf16 v[56:59], v[136:139], v[176:179], v[56:59]
	v_mfma_f32_16x16x32_bf16 v[44:47], v[128:131], v[196:199], v[44:47]
	v_mfma_f32_16x16x32_bf16 v[40:43], v[136:139], v[196:199], v[40:43]
	v_mfma_f32_16x16x32_bf16 v[28:31], v[128:131], v[204:207], v[28:31]
	v_mfma_f32_16x16x32_bf16 v[24:27], v[136:139], v[204:207], v[24:27]
	v_mfma_f32_16x16x32_bf16 v[12:15], v[128:131], v[212:215], v[12:15]
	v_mfma_f32_16x16x32_bf16 v[8:11], v[136:139], v[212:215], v[8:11]
	v_mfma_f32_16x16x32_bf16 v[60:63], v[132:135], v[180:183], v[60:63]
	v_mfma_f32_16x16x32_bf16 v[56:59], v[140:143], v[180:183], v[56:59]
	v_mfma_f32_16x16x32_bf16 v[44:47], v[132:135], v[200:203], v[44:47]
	v_mfma_f32_16x16x32_bf16 v[40:43], v[140:143], v[200:203], v[40:43]
	v_mfma_f32_16x16x32_bf16 v[28:31], v[132:135], v[208:211], v[28:31]
	v_mfma_f32_16x16x32_bf16 v[24:27], v[140:143], v[208:211], v[24:27]
	v_mfma_f32_16x16x32_bf16 v[12:15], v[132:135], v[216:219], v[12:15]
	v_mfma_f32_16x16x32_bf16 v[8:11], v[140:143], v[216:219], v[8:11]
	s_setprio 0
	s_setprio 1
	v_mfma_f32_16x16x32_bf16 v[52:55], v[144:147], v[176:179], v[52:55]
	v_mfma_f32_16x16x32_bf16 v[48:51], v[168:171], v[176:179], v[48:51]
	v_mfma_f32_16x16x32_bf16 v[36:39], v[144:147], v[196:199], v[36:39]
	v_mfma_f32_16x16x32_bf16 v[32:35], v[168:171], v[196:199], v[32:35]
	v_mfma_f32_16x16x32_bf16 v[20:23], v[144:147], v[204:207], v[20:23]
	v_mfma_f32_16x16x32_bf16 v[16:19], v[168:171], v[204:207], v[16:19]
	v_mfma_f32_16x16x32_bf16 v[4:7], v[144:147], v[212:215], v[4:7]
	v_mfma_f32_16x16x32_bf16 v[0:3], v[168:171], v[212:215], v[0:3]
	v_mfma_f32_16x16x32_bf16 v[52:55], v[148:151], v[180:183], v[52:55]
	v_mfma_f32_16x16x32_bf16 v[48:51], v[172:175], v[180:183], v[48:51]
	v_mfma_f32_16x16x32_bf16 v[36:39], v[148:151], v[200:203], v[36:39]
	v_mfma_f32_16x16x32_bf16 v[32:35], v[172:175], v[200:203], v[32:35]
	v_mfma_f32_16x16x32_bf16 v[20:23], v[148:151], v[208:211], v[20:23]
	v_mfma_f32_16x16x32_bf16 v[16:19], v[172:175], v[208:211], v[16:19]
	v_mfma_f32_16x16x32_bf16 v[4:7], v[148:151], v[216:219], v[4:7]
	v_mfma_f32_16x16x32_bf16 v[0:3], v[172:175], v[216:219], v[0:3]
	s_barrier
	s_setprio 0
	s_add_i32 s72, s72, 2
	s_add_u32 s70, s70, 0x100
	s_addc_u32 s71, s71, 0
	s_cmp_gt_u32 s72, 41
	s_mov_b64 s[26:27], s[28:29]
	s_cbranch_scc0 .LBB0_318
	s_and_b64 vcc, exec, s[20:21]
	s_cbranch_vccz .LBB0_321
	s_barrier

; #define PG8_STAGE(bufoff, gbase, voff) do { _Pragma("unroll") for (int _i = 0; _i < 2; ++_i) \
;         __builtin_amdgcn_global_load_lds((const unsigned*)((const char*)(gbase) + (voff)[_i]), (PG8_LAS unsigned*)(lds + (bufoff) + ldsw + _i * 8192), 16, 0, 0); } while (0)
; #define PG8_LDA(dst, b, h) do { _Pragma("unroll") for (int m = 0; m < 4; ++m) _Pragma("unroll") for (int k = 0; k < 2; ++k) dst[m][k] = *(const PG8_LAS bf16x8*)(lds + PG8_SA(b, h) + aoff + m * 2048 + k * 1024); } while (0)
; #define PG8_LDB(dst, b, h) do { _Pragma("unroll") for (int n = 0; n < 2; ++n) _Pragma("unroll") for (int k = 0; k < 2; ++k) dst[n][k] = *(const PG8_LAS bf16x8*)(lds + PG8_SB(b, h) + boff + n * 2048 + k * 1024); } while (0)
; #define PG8_MMA(ai, bj, At, Bt) do { __builtin_amdgcn_s_setprio(1); _Pragma("unroll") for (int m = 0; m < 4; ++m) _Pragma("unroll") for (int n = 0; n < 2; ++n) _Pragma("unroll") for (int k = 0; k < 2; ++k) \
;         acc[ai][bj][m][n] = __builtin_amdgcn_mfma_f32_16x16x32_bf16(Bt[n][k], At[m][k], acc[ai][bj][m][n], 0, 0, 0); __builtin_amdgcn_s_setprio(0); } while (0)
; #define PG8_WAIT_V(n) asm volatile("s_waitcnt vmcnt(" #n ")" ::: "memory")
; #define PG8_WAIT_L(n) asm volatile("s_waitcnt lgkmcnt(" #n ")" ::: "memory")
; #define PG8_BAR __builtin_amdgcn_s_barrier()
; #define PG8_SCHED __builtin_amdgcn_sched_barrier(0)
; template <class Epi, class Sched, bool ALIGN_EPI = false, bool SP2 = false>
; __device__ __forceinline__ void gemm_phase(PG8_LAS unsigned char* lds, const Gemm g, const Sched& S, const Epi& E) {
;     ...
;             PG8_LDB(B0, 0, 0); PG8_LDB(B1, 0, 1); PG8_SCHED; PG8_LDA(At, 0, 0); PG8_STAGE(PG8_SA(1, 1), a1 + hstepA, voffA);
;             PG8_WAIT_V(8); PG8_WAIT_L(0); PG8_BAR; PG8_MMA(0, 0, At, B0); PG8_MMA(0, 1, At, B1); PG8_BAR; PG8_SCHED;
;             PG8_LDA(At, 0, 1); PG8_STAGE(PG8_SB(0, 0), b2, voffB); PG8_STAGE(PG8_SB(0, 1), b2 + hstepB, voffB); PG8_STAGE(PG8_SA(0, 0), a2, voffA);
.LBB0_404:
	ds_read_b128 v[152:155], v165
	ds_read_b128 v[156:159], v165 offset:1024
	ds_read_b128 v[178:181], v165 offset:2048
	ds_read_b128 v[182:185], v165 offset:3072
	ds_read_b128 v[188:191], v166
	ds_read_b128 v[192:195], v166 offset:1024
	ds_read_b128 v[196:199], v166 offset:2048
	ds_read_b128 v[200:203], v166 offset:3072
	s_add_u32 s46, s14, 0xfffc0080
	s_addc_u32 s47, s15, -1
	s_cmp_eq_u32 s91, 12
	s_cselect_b32 s49, s11, s47
	s_cselect_b32 s48, s13, s46
	s_cselect_b32 s47, s39, s67
	s_cselect_b32 s46, s41, s66
	v_lshl_add_u64 v[160:161], s[14:15], 0, v[144:145]
	s_add_i32 m0, s71, 0xc000
	ds_read_b128 v[204:207], v167
	ds_read_b128 v[208:211], v167 offset:1024
	ds_read_b128 v[212:215], v167 offset:2048
	ds_read_b128 v[216:219], v167 offset:3072
	ds_read_b128 v[220:223], v167 offset:4096
	ds_read_b128 v[224:227], v167 offset:5120
	ds_read_b128 v[228:231], v167 offset:6144
	ds_read_b128 v[232:235], v167 offset:7168
	global_load_lds_dwordx4 v[160:161], off
	v_lshl_add_u64 v[160:161], s[14:15], 0, v[146:147]
	s_add_i32 m0, s71, 0xe000
	s_nop 0
	global_load_lds_dwordx4 v[160:161], off
	s_waitcnt vmcnt(8)
	s_waitcnt lgkmcnt(0)
	s_barrier
	s_setprio 1
	s_waitcnt lgkmcnt(0)
	v_mfma_f32_16x16x32_bf16 v[124:127], v[152:155], v[204:207], v[124:127]
	v_mfma_f32_16x16x32_bf16 v[120:123], v[178:181], v[204:207], v[120:123]
	v_mfma_f32_16x16x32_bf16 v[108:111], v[152:155], v[212:215], v[108:111]
	v_mfma_f32_16x16x32_bf16 v[104:107], v[178:181], v[212:215], v[104:107]
	v_mfma_f32_16x16x32_bf16 v[92:95], v[152:155], v[220:223], v[92:95]
	v_mfma_f32_16x16x32_bf16 v[88:91], v[178:181], v[220:223], v[88:91]
	v_mfma_f32_16x16x32_bf16 v[76:79], v[152:155], v[228:231], v[76:79]
	v_mfma_f32_16x16x32_bf16 v[72:75], v[178:181], v[228:231], v[72:75]
	v_mfma_f32_16x16x32_bf16 v[124:127], v[156:159], v[208:211], v[124:127]
	v_mfma_f32_16x16x32_bf16 v[120:123], v[182:185], v[208:211], v[120:123]
	v_mfma_f32_16x16x32_bf16 v[108:111], v[156:159], v[216:219], v[108:111]
	v_mfma_f32_16x16x32_bf16 v[104:107], v[182:185], v[216:219], v[104:107]
	v_mfma_f32_16x16x32_bf16 v[92:95], v[156:159], v[224:227], v[92:95]
	v_mfma_f32_16x16x32_bf16 v[88:91], v[182:185], v[224:227], v[88:91]
	v_mfma_f32_16x16x32_bf16 v[76:79], v[156:159], v[232:235], v[76:79]
	v_mfma_f32_16x16x32_bf16 v[72:75], v[182:185], v[232:235], v[72:75]
	s_setprio 0
	s_setprio 1
	v_mfma_f32_16x16x32_bf16 v[116:119], v[188:191], v[204:207], v[116:119]
	v_mfma_f32_16x16x32_bf16 v[112:115], v[196:199], v[204:207], v[112:115]
	v_mfma_f32_16x16x32_bf16 v[100:103], v[188:191], v[212:215], v[100:103]
	v_mfma_f32_16x16x32_bf16 v[96:99], v[196:199], v[212:215], v[96:99]
	v_mfma_f32_16x16x32_bf16 v[84:87], v[188:191], v[220:223], v[84:87]
	v_mfma_f32_16x16x32_bf16 v[80:83], v[196:199], v[220:223], v[80:83]
	v_mfma_f32_16x16x32_bf16 v[68:71], v[188:191], v[228:231], v[68:71]
	v_mfma_f32_16x16x32_bf16 v[64:67], v[196:199], v[228:231], v[64:67]
	v_mfma_f32_16x16x32_bf16 v[116:119], v[192:195], v[208:211], v[116:119]
	v_mfma_f32_16x16x32_bf16 v[112:115], v[200:203], v[208:211], v[112:115]
	v_mfma_f32_16x16x32_bf16 v[100:103], v[192:195], v[216:219], v[100:103]
	v_mfma_f32_16x16x32_bf16 v[96:99], v[200:203], v[216:219], v[96:99]
	v_mfma_f32_16x16x32_bf16 v[84:87], v[192:195], v[224:227], v[84:87]
	v_mfma_f32_16x16x32_bf16 v[80:83], v[200:203], v[224:227], v[80:83]
	v_mfma_f32_16x16x32_bf16 v[68:71], v[192:195], v[232:235], v[68:71]
	v_mfma_f32_16x16x32_bf16 v[64:67], v[200:203], v[232:235], v[64:67]
	s_barrier
	s_setprio 0
	s_add_i32 s58, s83, s70
	v_lshl_add_u64 v[160:161], s[46:47], 0, v[130:131]
	s_mov_b32 m0, s58
	ds_read_b128 v[204:207], v167 offset:16384
	ds_read_b128 v[208:211], v167 offset:17408
	ds_read_b128 v[212:215], v167 offset:18432
	ds_read_b128 v[216:219], v167 offset:19456
	ds_read_b128 v[220:223], v167 offset:20480
	ds_read_b128 v[224:227], v167 offset:21504
	ds_read_b128 v[228:231], v167 offset:22528
	ds_read_b128 v[232:235], v167 offset:23552
	global_load_lds_dwordx4 v[160:161], off
	s_add_i32 m0, s58, 0x2000
	s_add_u32 s58, s46, 0x40000
	v_lshl_add_u64 v[236:237], s[46:47], 0, v[134:135]
	s_addc_u32 s59, s47, 0
	s_add_i32 s92, s84, s70
	global_load_lds_dwordx4 v[236:237], off
	v_lshl_add_u64 v[238:239], s[58:59], 0, v[130:131]
	s_mov_b32 m0, s92
	v_lshl_add_u64 v[240:241], s[48:49], 0, v[132:133]
	global_load_lds_dwordx4 v[238:239], off
	v_lshl_add_u64 v[238:239], s[58:59], 0, v[134:135]
	s_add_i32 m0, s92, 0x2000
	s_nop 0
	global_load_lds_dwordx4 v[238:239], off
	v_lshl_add_u64 v[238:239], s[48:49], 0, v[128:129]
	s_mov_b32 m0, s71
	s_nop 0
	global_load_lds_dwordx4 v[238:239], off
	s_mov_b32 m0, s72
	s_nop 0
	global_load_lds_dwordx4 v[240:241], off
	s_waitcnt vmcnt(8)
	s_waitcnt lgkmcnt(0)
	s_barrier
; #define PG8_STAGE(bufoff, gbase, voff) do { _Pragma("unroll") for (int _i = 0; _i < 2; ++_i) \
;         __builtin_amdgcn_global_load_lds((const unsigned*)((const char*)(gbase) + (voff)[_i]), (PG8_LAS unsigned*)(lds + (bufoff) + ldsw + _i * 8192), 16, 0, 0); } while (0)
; #define PG8_LDA(dst, b, h) do { _Pragma("unroll") for (int m = 0; m < 4; ++m) _Pragma("unroll") for (int k = 0; k < 2; ++k) dst[m][k] = *(const PG8_LAS bf16x8*)(lds + PG8_SA(b, h) + aoff + m * 2048 + k * 1024); } while (0)
; #define PG8_LDB(dst, b, h) do { _Pragma("unroll") for (int n = 0; n < 2; ++n) _Pragma("unroll") for (int k = 0; k < 2; ++k) dst[n][k] = *(const PG8_LAS bf16x8*)(lds + PG8_SB(b, h) + boff + n * 2048 + k * 1024); } while (0)
; #define PG8_MMA(ai, bj, At, Bt) do { __builtin_amdgcn_s_setprio(1); _Pragma("unroll") for (int m = 0; m < 4; ++m) _Pragma("unroll") for (int n = 0; n < 2; ++n) _Pragma("unroll") for (int k = 0; k < 2; ++k) \
;         acc[ai][bj][m][n] = __builtin_amdgcn_mfma_f32_16x16x32_bf16(Bt[n][k], At[m][k], acc[ai][bj][m][n], 0, 0, 0); __builtin_amdgcn_s_setprio(0); } while (0)
; #define PG8_WAIT_V(n) asm volatile("s_waitcnt vmcnt(" #n ")" ::: "memory")
; #define PG8_WAIT_L(n) asm volatile("s_waitcnt lgkmcnt(" #n ")" ::: "memory")
; #define PG8_BAR __builtin_amdgcn_s_barrier()
; #define PG8_SCHED __builtin_amdgcn_sched_barrier(0)
; template <class Epi, class Sched, bool ALIGN_EPI = false, bool SP2 = false>
; __device__ __forceinline__ void gemm_phase(PG8_LAS unsigned char* lds, const Gemm g, const Sched& S, const Epi& E) {
;     ...
;             PG8_WAIT_V(8); PG8_WAIT_L(0); PG8_BAR; PG8_MMA(1, 0, At, B0); PG8_MMA(1, 1, At, B1); PG8_BAR; PG8_SCHED;
;             PG8_LDB(B0, 1, 0); PG8_LDB(B1, 1, 1); PG8_SCHED; PG8_LDA(At, 1, 0); PG8_STAGE(PG8_SA(0, 1), a2 + hstepA, voffA);
;             PG8_WAIT_V(8); PG8_WAIT_L(0); PG8_BAR; PG8_MMA(0, 0, At, B0); PG8_MMA(0, 1, At, B1); PG8_BAR; PG8_SCHED;
	s_setprio 1
	s_waitcnt lgkmcnt(0)
	v_mfma_f32_16x16x32_bf16 v[60:63], v[152:155], v[204:207], v[60:63]
	v_mfma_f32_16x16x32_bf16 v[56:59], v[178:181], v[204:207], v[56:59]
	v_mfma_f32_16x16x32_bf16 v[44:47], v[152:155], v[212:215], v[44:47]
	v_mfma_f32_16x16x32_bf16 v[40:43], v[178:181], v[212:215], v[40:43]
	v_mfma_f32_16x16x32_bf16 v[28:31], v[152:155], v[220:223], v[28:31]
	v_mfma_f32_16x16x32_bf16 v[24:27], v[178:181], v[220:223], v[24:27]
	v_mfma_f32_16x16x32_bf16 v[12:15], v[152:155], v[228:231], v[12:15]
	v_mfma_f32_16x16x32_bf16 v[8:11], v[178:181], v[228:231], v[8:11]
	v_mfma_f32_16x16x32_bf16 v[60:63], v[156:159], v[208:211], v[60:63]
	v_mfma_f32_16x16x32_bf16 v[56:59], v[182:185], v[208:211], v[56:59]
	v_mfma_f32_16x16x32_bf16 v[44:47], v[156:159], v[216:219], v[44:47]
	v_mfma_f32_16x16x32_bf16 v[40:43], v[182:185], v[216:219], v[40:43]
	v_mfma_f32_16x16x32_bf16 v[28:31], v[156:159], v[224:227], v[28:31]
	v_mfma_f32_16x16x32_bf16 v[24:27], v[182:185], v[224:227], v[24:27]
	v_mfma_f32_16x16x32_bf16 v[12:15], v[156:159], v[232:235], v[12:15]
	v_mfma_f32_16x16x32_bf16 v[8:11], v[182:185], v[232:235], v[8:11]
	s_setprio 0
	s_setprio 1
	v_mfma_f32_16x16x32_bf16 v[52:55], v[188:191], v[204:207], v[52:55]
	v_mfma_f32_16x16x32_bf16 v[48:51], v[196:199], v[204:207], v[48:51]
	v_mfma_f32_16x16x32_bf16 v[36:39], v[188:191], v[212:215], v[36:39]
	v_mfma_f32_16x16x32_bf16 v[32:35], v[196:199], v[212:215], v[32:35]
	v_mfma_f32_16x16x32_bf16 v[20:23], v[188:191], v[220:223], v[20:23]
	v_mfma_f32_16x16x32_bf16 v[16:19], v[196:199], v[220:223], v[16:19]
	v_mfma_f32_16x16x32_bf16 v[4:7], v[188:191], v[228:231], v[4:7]
	v_mfma_f32_16x16x32_bf16 v[0:3], v[196:199], v[228:231], v[0:3]
	v_mfma_f32_16x16x32_bf16 v[52:55], v[192:195], v[208:211], v[52:55]
	v_mfma_f32_16x16x32_bf16 v[48:51], v[200:203], v[208:211], v[48:51]
	v_mfma_f32_16x16x32_bf16 v[36:39], v[192:195], v[216:219], v[36:39]
	v_mfma_f32_16x16x32_bf16 v[32:35], v[200:203], v[216:219], v[32:35]
	v_mfma_f32_16x16x32_bf16 v[20:23], v[192:195], v[224:227], v[20:23]
	v_mfma_f32_16x16x32_bf16 v[16:19], v[200:203], v[224:227], v[16:19]
	v_mfma_f32_16x16x32_bf16 v[4:7], v[192:195], v[232:235], v[4:7]
	v_mfma_f32_16x16x32_bf16 v[0:3], v[200:203], v[232:235], v[0:3]
	s_barrier
	s_setprio 0
	s_add_i32 s58, 0, 0x18000
	v_add_u32_e32 v136, s58, v163
	s_add_i32 s59, 0, 0x1c000
	ds_read_b128 v[152:155], v136
	ds_read_b128 v[156:159], v136 offset:1024
	ds_read_b128 v[178:181], v136 offset:2048
	ds_read_b128 v[182:185], v136 offset:3072
	v_add_u32_e32 v136, s59, v163
	ds_read_b128 v[188:191], v136
	ds_read_b128 v[192:195], v136 offset:1024
	ds_read_b128 v[196:199], v136 offset:2048
	ds_read_b128 v[200:203], v136 offset:3072
	s_add_u32 s48, s48, 0x40000
	s_addc_u32 s49, s49, 0
	s_mov_b32 m0, s73
	v_lshl_add_u64 v[242:243], s[48:49], 0, v[128:129]
	ds_read_b128 v[204:207], v167 offset:32768
	ds_read_b128 v[208:211], v167 offset:33792
	ds_read_b128 v[212:215], v167 offset:34816
	ds_read_b128 v[216:219], v167 offset:35840
	ds_read_b128 v[220:223], v167 offset:36864
	ds_read_b128 v[224:227], v167 offset:37888
	ds_read_b128 v[228:231], v167 offset:38912
	ds_read_b128 v[232:235], v167 offset:39936
	global_load_lds_dwordx4 v[242:243], off
	v_lshl_add_u64 v[242:243], s[48:49], 0, v[132:133]
	s_mov_b32 m0, s74
	s_nop 0
	global_load_lds_dwordx4 v[242:243], off
	s_waitcnt vmcnt(8)
	s_waitcnt lgkmcnt(0)
	s_barrier
	s_setprio 1
	s_waitcnt lgkmcnt(0)
	v_mfma_f32_16x16x32_bf16 v[124:127], v[152:155], v[204:207], v[124:127]
	v_mfma_f32_16x16x32_bf16 v[120:123], v[178:181], v[204:207], v[120:123]
	v_mfma_f32_16x16x32_bf16 v[108:111], v[152:155], v[212:215], v[108:111]
	v_mfma_f32_16x16x32_bf16 v[104:107], v[178:181], v[212:215], v[104:107]
	v_mfma_f32_16x16x32_bf16 v[92:95], v[152:155], v[220:223], v[92:95]
	v_mfma_f32_16x16x32_bf16 v[88:91], v[178:181], v[220:223], v[88:91]
	v_mfma_f32_16x16x32_bf16 v[76:79], v[152:155], v[228:231], v[76:79]
	v_mfma_f32_16x16x32_bf16 v[72:75], v[178:181], v[228:231], v[72:75]
	v_mfma_f32_16x16x32_bf16 v[124:127], v[156:159], v[208:211], v[124:127]
	v_mfma_f32_16x16x32_bf16 v[120:123], v[182:185], v[208:211], v[120:123]
	v_mfma_f32_16x16x32_bf16 v[108:111], v[156:159], v[216:219], v[108:111]
	v_mfma_f32_16x16x32_bf16 v[104:107], v[182:185], v[216:219], v[104:107]
	v_mfma_f32_16x16x32_bf16 v[92:95], v[156:159], v[224:227], v[92:95]
	v_mfma_f32_16x16x32_bf16 v[88:91], v[182:185], v[224:227], v[88:91]
	v_mfma_f32_16x16x32_bf16 v[76:79], v[156:159], v[232:235], v[76:79]
	v_mfma_f32_16x16x32_bf16 v[72:75], v[182:185], v[232:235], v[72:75]
	s_setprio 0
	s_setprio 1
	v_mfma_f32_16x16x32_bf16 v[116:119], v[188:191], v[204:207], v[116:119]
	v_mfma_f32_16x16x32_bf16 v[112:115], v[196:199], v[204:207], v[112:115]
	v_mfma_f32_16x16x32_bf16 v[100:103], v[188:191], v[212:215], v[100:103]
	v_mfma_f32_16x16x32_bf16 v[96:99], v[196:199], v[212:215], v[96:99]
	v_mfma_f32_16x16x32_bf16 v[84:87], v[188:191], v[220:223], v[84:87]
	v_mfma_f32_16x16x32_bf16 v[80:83], v[196:199], v[220:223], v[80:83]
	v_mfma_f32_16x16x32_bf16 v[68:71], v[188:191], v[228:231], v[68:71]
	v_mfma_f32_16x16x32_bf16 v[64:67], v[196:199], v[228:231], v[64:67]
	v_mfma_f32_16x16x32_bf16 v[116:119], v[192:195], v[208:211], v[116:119]
	v_mfma_f32_16x16x32_bf16 v[112:115], v[200:203], v[208:211], v[112:115]
	v_mfma_f32_16x16x32_bf16 v[100:103], v[192:195], v[216:219], v[100:103]
	v_mfma_f32_16x16x32_bf16 v[96:99], v[200:203], v[216:219], v[96:99]
	v_mfma_f32_16x16x32_bf16 v[84:87], v[192:195], v[224:227], v[84:87]
	v_mfma_f32_16x16x32_bf16 v[80:83], v[200:203], v[224:227], v[80:83]
	v_mfma_f32_16x16x32_bf16 v[68:71], v[192:195], v[232:235], v[68:71]
	v_mfma_f32_16x16x32_bf16 v[64:67], v[200:203], v[232:235], v[64:67]
	s_barrier
; #define PG8_STAGE(bufoff, gbase, voff) do { _Pragma("unroll") for (int _i = 0; _i < 2; ++_i) \
;         __builtin_amdgcn_global_load_lds((const unsigned*)((const char*)(gbase) + (voff)[_i]), (PG8_LAS unsigned*)(lds + (bufoff) + ldsw + _i * 8192), 16, 0, 0); } while (0)
; #define PG8_LDA(dst, b, h) do { _Pragma("unroll") for (int m = 0; m < 4; ++m) _Pragma("unroll") for (int k = 0; k < 2; ++k) dst[m][k] = *(const PG8_LAS bf16x8*)(lds + PG8_SA(b, h) + aoff + m * 2048 + k * 1024); } while (0)
; #define PG8_MMA(ai, bj, At, Bt) do { __builtin_amdgcn_s_setprio(1); _Pragma("unroll") for (int m = 0; m < 4; ++m) _Pragma("unroll") for (int n = 0; n < 2; ++n) _Pragma("unroll") for (int k = 0; k < 2; ++k) \
;         acc[ai][bj][m][n] = __builtin_amdgcn_mfma_f32_16x16x32_bf16(Bt[n][k], At[m][k], acc[ai][bj][m][n], 0, 0, 0); __builtin_amdgcn_s_setprio(0); } while (0)
; #define PG8_WAIT_V(n) asm volatile("s_waitcnt vmcnt(" #n ")" ::: "memory")
; #define PG8_WAIT_L(n) asm volatile("s_waitcnt lgkmcnt(" #n ")" ::: "memory")
; #define PG8_BAR __builtin_amdgcn_s_barrier()
; #define PG8_SCHED __builtin_amdgcn_sched_barrier(0)
; template <class Epi, class Sched, bool ALIGN_EPI = false, bool SP2 = false>
; __device__ __forceinline__ void gemm_phase(PG8_LAS unsigned char* lds, const Gemm g, const Sched& S, const Epi& E) {
;     ...
;             PG8_LDA(At, 1, 1); PG8_STAGE(PG8_SB(1, 0), b3, voffB); PG8_STAGE(PG8_SB(1, 1), b3 + hstepB, voffB); PG8_STAGE(PG8_SA(1, 0), a3, voffA);
;             PG8_WAIT_V(8); PG8_WAIT_L(0); PG8_BAR; PG8_MMA(1, 0, At, B0); PG8_MMA(1, 1, At, B1); PG8_BAR; PG8_SCHED;
	s_setprio 0
	s_add_i32 s48, s58, s70
	v_lshl_add_u64 v[160:161], v[160:161], 0, s[30:31]
	s_mov_b32 m0, s48
	ds_read_b128 v[204:207], v167 offset:49152
	ds_read_b128 v[208:211], v167 offset:50176
	ds_read_b128 v[212:215], v167 offset:51200
	ds_read_b128 v[216:219], v167 offset:52224
	ds_read_b128 v[220:223], v167 offset:53248
	ds_read_b128 v[224:227], v167 offset:54272
	ds_read_b128 v[228:231], v167 offset:55296
	ds_read_b128 v[232:235], v167 offset:56320
	global_load_lds_dwordx4 v[160:161], off
	s_add_i32 m0, s48, 0x2000
	s_add_u32 s46, s46, 0x40080
	v_lshl_add_u64 v[160:161], v[236:237], 0, s[30:31]
	s_addc_u32 s47, s47, 0
	s_add_i32 s48, s59, s70
	global_load_lds_dwordx4 v[160:161], off
	v_lshl_add_u64 v[160:161], s[46:47], 0, v[130:131]
	s_mov_b32 m0, s48
	s_nop 0
	global_load_lds_dwordx4 v[160:161], off
	v_lshl_add_u64 v[160:161], s[46:47], 0, v[134:135]
	s_add_i32 m0, s48, 0x2000
	s_nop 0
	global_load_lds_dwordx4 v[160:161], off
	v_lshl_add_u64 v[160:161], v[238:239], 0, s[30:31]
	s_mov_b32 m0, s76
	s_nop 0
	global_load_lds_dwordx4 v[160:161], off
	v_lshl_add_u64 v[160:161], v[240:241], 0, s[30:31]
	s_mov_b32 m0, s77
	s_nop 0
	global_load_lds_dwordx4 v[160:161], off
	s_waitcnt vmcnt(8)
	s_waitcnt lgkmcnt(0)
	s_barrier
	s_setprio 1
	s_waitcnt lgkmcnt(0)
	v_mfma_f32_16x16x32_bf16 v[60:63], v[152:155], v[204:207], v[60:63]
	v_mfma_f32_16x16x32_bf16 v[56:59], v[178:181], v[204:207], v[56:59]
	v_mfma_f32_16x16x32_bf16 v[44:47], v[152:155], v[212:215], v[44:47]
	v_mfma_f32_16x16x32_bf16 v[40:43], v[178:181], v[212:215], v[40:43]
	v_mfma_f32_16x16x32_bf16 v[28:31], v[152:155], v[220:223], v[28:31]
	v_mfma_f32_16x16x32_bf16 v[24:27], v[178:181], v[220:223], v[24:27]
	v_mfma_f32_16x16x32_bf16 v[12:15], v[152:155], v[228:231], v[12:15]
	v_mfma_f32_16x16x32_bf16 v[8:11], v[178:181], v[228:231], v[8:11]
	v_mfma_f32_16x16x32_bf16 v[60:63], v[156:159], v[208:211], v[60:63]
	v_mfma_f32_16x16x32_bf16 v[56:59], v[182:185], v[208:211], v[56:59]
	v_mfma_f32_16x16x32_bf16 v[44:47], v[156:159], v[216:219], v[44:47]
	v_mfma_f32_16x16x32_bf16 v[40:43], v[182:185], v[216:219], v[40:43]
	v_mfma_f32_16x16x32_bf16 v[28:31], v[156:159], v[224:227], v[28:31]
	v_mfma_f32_16x16x32_bf16 v[24:27], v[182:185], v[224:227], v[24:27]
	v_mfma_f32_16x16x32_bf16 v[12:15], v[156:159], v[232:235], v[12:15]
	v_mfma_f32_16x16x32_bf16 v[8:11], v[182:185], v[232:235], v[8:11]
	s_setprio 0
	s_setprio 1
	v_mfma_f32_16x16x32_bf16 v[52:55], v[188:191], v[204:207], v[52:55]
	v_mfma_f32_16x16x32_bf16 v[48:51], v[196:199], v[204:207], v[48:51]
	v_mfma_f32_16x16x32_bf16 v[36:39], v[188:191], v[212:215], v[36:39]
	v_mfma_f32_16x16x32_bf16 v[32:35], v[196:199], v[212:215], v[32:35]
	v_mfma_f32_16x16x32_bf16 v[20:23], v[188:191], v[220:223], v[20:23]
	v_mfma_f32_16x16x32_bf16 v[16:19], v[196:199], v[220:223], v[16:19]
	v_mfma_f32_16x16x32_bf16 v[4:7], v[188:191], v[228:231], v[4:7]
	v_mfma_f32_16x16x32_bf16 v[0:3], v[196:199], v[228:231], v[0:3]
	v_mfma_f32_16x16x32_bf16 v[52:55], v[192:195], v[208:211], v[52:55]
	v_mfma_f32_16x16x32_bf16 v[48:51], v[200:203], v[208:211], v[48:51]
	v_mfma_f32_16x16x32_bf16 v[36:39], v[192:195], v[216:219], v[36:39]
	v_mfma_f32_16x16x32_bf16 v[32:35], v[200:203], v[216:219], v[32:35]
	v_mfma_f32_16x16x32_bf16 v[20:23], v[192:195], v[224:227], v[20:23]
	v_mfma_f32_16x16x32_bf16 v[16:19], v[200:203], v[224:227], v[16:19]
	v_mfma_f32_16x16x32_bf16 v[4:7], v[192:195], v[232:235], v[4:7]
	v_mfma_f32_16x16x32_bf16 v[0:3], v[200:203], v[232:235], v[0:3]
	s_barrier
	s_setprio 0
	s_add_i32 s91, s91, 2
	s_add_u32 s14, s14, 0x100
	s_addc_u32 s15, s15, 0
	s_add_u32 s66, s66, 0x100
	s_addc_u32 s67, s67, 0
	s_cmp_gt_u32 s91, 13
	s_cbranch_scc0 .LBB0_404
	s_and_b64 vcc, exec, s[34:35]
	s_cbranch_vccz .LBB0_407
	s_barrier

; #define PG8_STAGE(bufoff, gbase, voff) do { _Pragma("unroll") for (int _i = 0; _i < 2; ++_i) \
;         __builtin_amdgcn_global_load_lds((const unsigned*)((const char*)(gbase) + (voff)[_i]), (PG8_LAS unsigned*)(lds + (bufoff) + ldsw + _i * 8192), 16, 0, 0); } while (0)
; #define PG8_LDA(dst, b, h) do { _Pragma("unroll") for (int m = 0; m < 4; ++m) _Pragma("unroll") for (int k = 0; k < 2; ++k) dst[m][k] = *(const PG8_LAS bf16x8*)(lds + PG8_SA(b, h) + aoff + m * 2048 + k * 1024); } while (0)
; #define PG8_LDB(dst, b, h) do { _Pragma("unroll") for (int n = 0; n < 2; ++n) _Pragma("unroll") for (int k = 0; k < 2; ++k) dst[n][k] = *(const PG8_LAS bf16x8*)(lds + PG8_SB(b, h) + boff + n * 2048 + k * 1024); } while (0)
; #define PG8_MMA(ai, bj, At, Bt) do { __builtin_amdgcn_s_setprio(1); _Pragma("unroll") for (int m = 0; m < 4; ++m) _Pragma("unroll") for (int n = 0; n < 2; ++n) _Pragma("unroll") for (int k = 0; k < 2; ++k) \
;         acc[ai][bj][m][n] = __builtin_amdgcn_mfma_f32_16x16x32_bf16(Bt[n][k], At[m][k], acc[ai][bj][m][n], 0, 0, 0); __builtin_amdgcn_s_setprio(0); } while (0)
; #define PG8_WAIT_V(n) asm volatile("s_waitcnt vmcnt(" #n ")" ::: "memory")
; #define PG8_WAIT_L(n) asm volatile("s_waitcnt lgkmcnt(" #n ")" ::: "memory")
; #define PG8_BAR __builtin_amdgcn_s_barrier()
; #define PG8_SCHED __builtin_amdgcn_sched_barrier(0)
; template <class Epi, class Sched, bool ALIGN_EPI = false, bool SP2 = false>
; __device__ __forceinline__ void gemm_phase(PG8_LAS unsigned char* lds, const Gemm g, const Sched& S, const Epi& E) {
;     ...
;             PG8_LDB(B0, 0, 0); PG8_LDB(B1, 0, 1); PG8_SCHED; PG8_LDA(At, 0, 0); PG8_STAGE(PG8_SA(1, 1), a1 + hstepA, voffA);
;             PG8_WAIT_V(8); PG8_WAIT_L(0); PG8_BAR; PG8_MMA(0, 0, At, B0); PG8_MMA(0, 1, At, B1); PG8_BAR; PG8_SCHED;
;             PG8_LDA(At, 0, 1); PG8_STAGE(PG8_SB(0, 0), b2, voffB); PG8_STAGE(PG8_SB(0, 1), b2 + hstepB, voffB); PG8_STAGE(PG8_SA(0, 0), a2, voffA);
.LBB0_524:
	ds_read_b128 v[144:147], v153
	ds_read_b128 v[158:161], v153 offset:1024
	ds_read_b128 v[162:165], v153 offset:2048
	ds_read_b128 v[166:169], v153 offset:3072
	ds_read_b128 v[170:173], v154
	ds_read_b128 v[174:177], v154 offset:1024
	ds_read_b128 v[178:181], v154 offset:2048
	ds_read_b128 v[182:185], v154 offset:3072
	s_add_u32 s30, s28, 0x100
	s_addc_u32 s31, s29, 0
	s_cmp_eq_u32 s76, 2
	s_cselect_b32 s37, s9, s31
	s_cselect_b32 s36, s8, s30
	s_cselect_b32 s35, s25, s75
	s_cselect_b32 s34, s24, s74
	v_lshl_add_u64 v[148:149], s[28:29], 0, v[136:137]
	s_add_i32 m0, s42, 0xc000
	ds_read_b128 v[188:191], v155
	ds_read_b128 v[192:195], v155 offset:1024
	ds_read_b128 v[196:199], v155 offset:2048
	ds_read_b128 v[200:203], v155 offset:3072
	ds_read_b128 v[204:207], v155 offset:4096
	ds_read_b128 v[208:211], v155 offset:5120
	ds_read_b128 v[212:215], v155 offset:6144
	ds_read_b128 v[216:219], v155 offset:7168
	global_load_lds_dwordx4 v[148:149], off
	v_lshl_add_u64 v[148:149], s[28:29], 0, v[138:139]
	s_add_i32 m0, s42, 0xe000
	s_nop 0
	global_load_lds_dwordx4 v[148:149], off
	s_waitcnt vmcnt(8)
	s_waitcnt lgkmcnt(0)
	s_barrier
	s_setprio 1
	s_waitcnt lgkmcnt(0)
	v_mfma_f32_16x16x32_bf16 v[124:127], v[144:147], v[188:191], v[124:127]
	v_mfma_f32_16x16x32_bf16 v[120:123], v[162:165], v[188:191], v[120:123]
	v_mfma_f32_16x16x32_bf16 v[108:111], v[144:147], v[196:199], v[108:111]
	v_mfma_f32_16x16x32_bf16 v[104:107], v[162:165], v[196:199], v[104:107]
	v_mfma_f32_16x16x32_bf16 v[92:95], v[144:147], v[204:207], v[92:95]
	v_mfma_f32_16x16x32_bf16 v[88:91], v[162:165], v[204:207], v[88:91]
	v_mfma_f32_16x16x32_bf16 v[76:79], v[144:147], v[212:215], v[76:79]
	v_mfma_f32_16x16x32_bf16 v[72:75], v[162:165], v[212:215], v[72:75]
	v_mfma_f32_16x16x32_bf16 v[124:127], v[158:161], v[192:195], v[124:127]
	v_mfma_f32_16x16x32_bf16 v[120:123], v[166:169], v[192:195], v[120:123]
	v_mfma_f32_16x16x32_bf16 v[108:111], v[158:161], v[200:203], v[108:111]
	v_mfma_f32_16x16x32_bf16 v[104:107], v[166:169], v[200:203], v[104:107]
	v_mfma_f32_16x16x32_bf16 v[92:95], v[158:161], v[208:211], v[92:95]
	v_mfma_f32_16x16x32_bf16 v[88:91], v[166:169], v[208:211], v[88:91]
	v_mfma_f32_16x16x32_bf16 v[76:79], v[158:161], v[216:219], v[76:79]
	v_mfma_f32_16x16x32_bf16 v[72:75], v[166:169], v[216:219], v[72:75]
	s_setprio 0
	s_setprio 1
	v_mfma_f32_16x16x32_bf16 v[116:119], v[170:173], v[188:191], v[116:119]
	v_mfma_f32_16x16x32_bf16 v[112:115], v[178:181], v[188:191], v[112:115]
	v_mfma_f32_16x16x32_bf16 v[100:103], v[170:173], v[196:199], v[100:103]
	v_mfma_f32_16x16x32_bf16 v[96:99], v[178:181], v[196:199], v[96:99]
	v_mfma_f32_16x16x32_bf16 v[84:87], v[170:173], v[204:207], v[84:87]
	v_mfma_f32_16x16x32_bf16 v[80:83], v[178:181], v[204:207], v[80:83]
	v_mfma_f32_16x16x32_bf16 v[68:71], v[170:173], v[212:215], v[68:71]
	v_mfma_f32_16x16x32_bf16 v[64:67], v[178:181], v[212:215], v[64:67]
	v_mfma_f32_16x16x32_bf16 v[116:119], v[174:177], v[192:195], v[116:119]
	v_mfma_f32_16x16x32_bf16 v[112:115], v[182:185], v[192:195], v[112:115]
	v_mfma_f32_16x16x32_bf16 v[100:103], v[174:177], v[200:203], v[100:103]
	v_mfma_f32_16x16x32_bf16 v[96:99], v[182:185], v[200:203], v[96:99]
	v_mfma_f32_16x16x32_bf16 v[84:87], v[174:177], v[208:211], v[84:87]
	v_mfma_f32_16x16x32_bf16 v[80:83], v[182:185], v[208:211], v[80:83]
	v_mfma_f32_16x16x32_bf16 v[68:71], v[174:177], v[216:219], v[68:71]
	v_mfma_f32_16x16x32_bf16 v[64:67], v[182:185], v[216:219], v[64:67]
	s_barrier
	s_setprio 0
	s_add_i32 s28, s66, s40
	v_lshl_add_u64 v[148:149], s[34:35], 0, v[132:133]
	s_mov_b32 m0, s28
	ds_read_b128 v[188:191], v155 offset:16384
	ds_read_b128 v[192:195], v155 offset:17408
	ds_read_b128 v[196:199], v155 offset:18432
	ds_read_b128 v[200:203], v155 offset:19456
	ds_read_b128 v[204:207], v155 offset:20480
	ds_read_b128 v[208:211], v155 offset:21504
	ds_read_b128 v[212:215], v155 offset:22528
	ds_read_b128 v[216:219], v155 offset:23552
	global_load_lds_dwordx4 v[148:149], off
	s_add_i32 m0, s28, 0x2000
	s_add_u32 s28, s34, 0x18000
	v_lshl_add_u64 v[220:221], s[34:35], 0, v[128:129]
	s_addc_u32 s29, s35, 0
	s_add_i32 s58, s67, s40
	global_load_lds_dwordx4 v[220:221], off
	v_lshl_add_u64 v[222:223], s[28:29], 0, v[132:133]
	s_mov_b32 m0, s58
	v_lshl_add_u64 v[224:225], s[36:37], 0, v[130:131]
	global_load_lds_dwordx4 v[222:223], off
	v_lshl_add_u64 v[222:223], s[28:29], 0, v[128:129]
	s_add_i32 m0, s58, 0x2000
	s_nop 0
	global_load_lds_dwordx4 v[222:223], off
	v_lshl_add_u64 v[222:223], s[36:37], 0, v[134:135]
	s_mov_b32 m0, s42
	s_nop 0
	global_load_lds_dwordx4 v[222:223], off
	s_mov_b32 m0, s43
	s_nop 0
	global_load_lds_dwordx4 v[224:225], off
	s_waitcnt vmcnt(8)
	s_waitcnt lgkmcnt(0)
	s_barrier
; #define PG8_STAGE(bufoff, gbase, voff) do { _Pragma("unroll") for (int _i = 0; _i < 2; ++_i) \
;         __builtin_amdgcn_global_load_lds((const unsigned*)((const char*)(gbase) + (voff)[_i]), (PG8_LAS unsigned*)(lds + (bufoff) + ldsw + _i * 8192), 16, 0, 0); } while (0)
; #define PG8_LDA(dst, b, h) do { _Pragma("unroll") for (int m = 0; m < 4; ++m) _Pragma("unroll") for (int k = 0; k < 2; ++k) dst[m][k] = *(const PG8_LAS bf16x8*)(lds + PG8_SA(b, h) + aoff + m * 2048 + k * 1024); } while (0)
; #define PG8_LDB(dst, b, h) do { _Pragma("unroll") for (int n = 0; n < 2; ++n) _Pragma("unroll") for (int k = 0; k < 2; ++k) dst[n][k] = *(const PG8_LAS bf16x8*)(lds + PG8_SB(b, h) + boff + n * 2048 + k * 1024); } while (0)
; #define PG8_MMA(ai, bj, At, Bt) do { __builtin_amdgcn_s_setprio(1); _Pragma("unroll") for (int m = 0; m < 4; ++m) _Pragma("unroll") for (int n = 0; n < 2; ++n) _Pragma("unroll") for (int k = 0; k < 2; ++k) \
;         acc[ai][bj][m][n] = __builtin_amdgcn_mfma_f32_16x16x32_bf16(Bt[n][k], At[m][k], acc[ai][bj][m][n], 0, 0, 0); __builtin_amdgcn_s_setprio(0); } while (0)
; #define PG8_WAIT_V(n) asm volatile("s_waitcnt vmcnt(" #n ")" ::: "memory")
; #define PG8_WAIT_L(n) asm volatile("s_waitcnt lgkmcnt(" #n ")" ::: "memory")
; #define PG8_BAR __builtin_amdgcn_s_barrier()
; #define PG8_SCHED __builtin_amdgcn_sched_barrier(0)
; template <class Epi, class Sched, bool ALIGN_EPI = false, bool SP2 = false>
; __device__ __forceinline__ void gemm_phase(PG8_LAS unsigned char* lds, const Gemm g, const Sched& S, const Epi& E) {
;     ...
;             PG8_WAIT_V(8); PG8_WAIT_L(0); PG8_BAR; PG8_MMA(1, 0, At, B0); PG8_MMA(1, 1, At, B1); PG8_BAR; PG8_SCHED;
;             PG8_LDB(B0, 1, 0); PG8_LDB(B1, 1, 1); PG8_SCHED; PG8_LDA(At, 1, 0); PG8_STAGE(PG8_SA(0, 1), a2 + hstepA, voffA);
;             PG8_WAIT_V(8); PG8_WAIT_L(0); PG8_BAR; PG8_MMA(0, 0, At, B0); PG8_MMA(0, 1, At, B1); PG8_BAR; PG8_SCHED;
	s_setprio 1
	s_waitcnt lgkmcnt(0)
	v_mfma_f32_16x16x32_bf16 v[60:63], v[144:147], v[188:191], v[60:63]
	v_mfma_f32_16x16x32_bf16 v[56:59], v[162:165], v[188:191], v[56:59]
	v_mfma_f32_16x16x32_bf16 v[44:47], v[144:147], v[196:199], v[44:47]
	v_mfma_f32_16x16x32_bf16 v[40:43], v[162:165], v[196:199], v[40:43]
	v_mfma_f32_16x16x32_bf16 v[28:31], v[144:147], v[204:207], v[28:31]
	v_mfma_f32_16x16x32_bf16 v[24:27], v[162:165], v[204:207], v[24:27]
	v_mfma_f32_16x16x32_bf16 v[12:15], v[144:147], v[212:215], v[12:15]
	v_mfma_f32_16x16x32_bf16 v[8:11], v[162:165], v[212:215], v[8:11]
	v_mfma_f32_16x16x32_bf16 v[60:63], v[158:161], v[192:195], v[60:63]
	v_mfma_f32_16x16x32_bf16 v[56:59], v[166:169], v[192:195], v[56:59]
	v_mfma_f32_16x16x32_bf16 v[44:47], v[158:161], v[200:203], v[44:47]
	v_mfma_f32_16x16x32_bf16 v[40:43], v[166:169], v[200:203], v[40:43]
	v_mfma_f32_16x16x32_bf16 v[28:31], v[158:161], v[208:211], v[28:31]
	v_mfma_f32_16x16x32_bf16 v[24:27], v[166:169], v[208:211], v[24:27]
	v_mfma_f32_16x16x32_bf16 v[12:15], v[158:161], v[216:219], v[12:15]
	v_mfma_f32_16x16x32_bf16 v[8:11], v[166:169], v[216:219], v[8:11]
	s_setprio 0
	s_setprio 1
	v_mfma_f32_16x16x32_bf16 v[52:55], v[170:173], v[188:191], v[52:55]
	v_mfma_f32_16x16x32_bf16 v[48:51], v[178:181], v[188:191], v[48:51]
	v_mfma_f32_16x16x32_bf16 v[36:39], v[170:173], v[196:199], v[36:39]
	v_mfma_f32_16x16x32_bf16 v[32:35], v[178:181], v[196:199], v[32:35]
	v_mfma_f32_16x16x32_bf16 v[20:23], v[170:173], v[204:207], v[20:23]
	v_mfma_f32_16x16x32_bf16 v[16:19], v[178:181], v[204:207], v[16:19]
	v_mfma_f32_16x16x32_bf16 v[4:7], v[170:173], v[212:215], v[4:7]
	v_mfma_f32_16x16x32_bf16 v[0:3], v[178:181], v[212:215], v[0:3]
	v_mfma_f32_16x16x32_bf16 v[52:55], v[174:177], v[192:195], v[52:55]
	v_mfma_f32_16x16x32_bf16 v[48:51], v[182:185], v[192:195], v[48:51]
	v_mfma_f32_16x16x32_bf16 v[36:39], v[174:177], v[200:203], v[36:39]
	v_mfma_f32_16x16x32_bf16 v[32:35], v[182:185], v[200:203], v[32:35]
	v_mfma_f32_16x16x32_bf16 v[20:23], v[174:177], v[208:211], v[20:23]
	v_mfma_f32_16x16x32_bf16 v[16:19], v[182:185], v[208:211], v[16:19]
	v_mfma_f32_16x16x32_bf16 v[4:7], v[174:177], v[216:219], v[4:7]
	v_mfma_f32_16x16x32_bf16 v[0:3], v[182:185], v[216:219], v[0:3]
	s_barrier
	s_setprio 0
	s_add_i32 s58, 0, 0x18000
	v_add_u32_e32 v157, s58, v151
	s_add_i32 s59, 0, 0x1c000
	ds_read_b128 v[144:147], v157
	ds_read_b128 v[158:161], v157 offset:1024
	ds_read_b128 v[162:165], v157 offset:2048
	ds_read_b128 v[166:169], v157 offset:3072
	v_add_u32_e32 v157, s59, v151
	ds_read_b128 v[170:173], v157
	ds_read_b128 v[174:177], v157 offset:1024
	ds_read_b128 v[178:181], v157 offset:2048
	ds_read_b128 v[182:185], v157 offset:3072
	s_add_u32 s28, s36, 0x30000
	s_addc_u32 s29, s37, 0
	s_mov_b32 m0, s44
	v_lshl_add_u64 v[226:227], s[28:29], 0, v[134:135]
	ds_read_b128 v[188:191], v155 offset:32768
	ds_read_b128 v[192:195], v155 offset:33792
	ds_read_b128 v[196:199], v155 offset:34816
	ds_read_b128 v[200:203], v155 offset:35840
	ds_read_b128 v[204:207], v155 offset:36864
	ds_read_b128 v[208:211], v155 offset:37888
	ds_read_b128 v[212:215], v155 offset:38912
	ds_read_b128 v[216:219], v155 offset:39936
	global_load_lds_dwordx4 v[226:227], off
	v_lshl_add_u64 v[226:227], s[28:29], 0, v[130:131]
	s_mov_b32 m0, s45
	s_nop 0
	global_load_lds_dwordx4 v[226:227], off
	s_waitcnt vmcnt(8)
	s_waitcnt lgkmcnt(0)
	s_barrier
	s_setprio 1
	s_waitcnt lgkmcnt(0)
	v_mfma_f32_16x16x32_bf16 v[124:127], v[144:147], v[188:191], v[124:127]
	v_mfma_f32_16x16x32_bf16 v[120:123], v[162:165], v[188:191], v[120:123]
	v_mfma_f32_16x16x32_bf16 v[108:111], v[144:147], v[196:199], v[108:111]
	v_mfma_f32_16x16x32_bf16 v[104:107], v[162:165], v[196:199], v[104:107]
	v_mfma_f32_16x16x32_bf16 v[92:95], v[144:147], v[204:207], v[92:95]
	v_mfma_f32_16x16x32_bf16 v[88:91], v[162:165], v[204:207], v[88:91]
	v_mfma_f32_16x16x32_bf16 v[76:79], v[144:147], v[212:215], v[76:79]
	v_mfma_f32_16x16x32_bf16 v[72:75], v[162:165], v[212:215], v[72:75]
	v_mfma_f32_16x16x32_bf16 v[124:127], v[158:161], v[192:195], v[124:127]
	v_mfma_f32_16x16x32_bf16 v[120:123], v[166:169], v[192:195], v[120:123]
	v_mfma_f32_16x16x32_bf16 v[108:111], v[158:161], v[200:203], v[108:111]
	v_mfma_f32_16x16x32_bf16 v[104:107], v[166:169], v[200:203], v[104:107]
	v_mfma_f32_16x16x32_bf16 v[92:95], v[158:161], v[208:211], v[92:95]
	v_mfma_f32_16x16x32_bf16 v[88:91], v[166:169], v[208:211], v[88:91]
	v_mfma_f32_16x16x32_bf16 v[76:79], v[158:161], v[216:219], v[76:79]
	v_mfma_f32_16x16x32_bf16 v[72:75], v[166:169], v[216:219], v[72:75]
	s_setprio 0
	s_setprio 1
	v_mfma_f32_16x16x32_bf16 v[116:119], v[170:173], v[188:191], v[116:119]
	v_mfma_f32_16x16x32_bf16 v[112:115], v[178:181], v[188:191], v[112:115]
	v_mfma_f32_16x16x32_bf16 v[100:103], v[170:173], v[196:199], v[100:103]
	v_mfma_f32_16x16x32_bf16 v[96:99], v[178:181], v[196:199], v[96:99]
	v_mfma_f32_16x16x32_bf16 v[84:87], v[170:173], v[204:207], v[84:87]
	v_mfma_f32_16x16x32_bf16 v[80:83], v[178:181], v[204:207], v[80:83]
	v_mfma_f32_16x16x32_bf16 v[68:71], v[170:173], v[212:215], v[68:71]
	v_mfma_f32_16x16x32_bf16 v[64:67], v[178:181], v[212:215], v[64:67]
	v_mfma_f32_16x16x32_bf16 v[116:119], v[174:177], v[192:195], v[116:119]
	v_mfma_f32_16x16x32_bf16 v[112:115], v[182:185], v[192:195], v[112:115]
	v_mfma_f32_16x16x32_bf16 v[100:103], v[174:177], v[200:203], v[100:103]
	v_mfma_f32_16x16x32_bf16 v[96:99], v[182:185], v[200:203], v[96:99]
	v_mfma_f32_16x16x32_bf16 v[84:87], v[174:177], v[208:211], v[84:87]
	v_mfma_f32_16x16x32_bf16 v[80:83], v[182:185], v[208:211], v[80:83]
	v_mfma_f32_16x16x32_bf16 v[68:71], v[174:177], v[216:219], v[68:71]
	v_mfma_f32_16x16x32_bf16 v[64:67], v[182:185], v[216:219], v[64:67]
	s_barrier
; #define PG8_STAGE(bufoff, gbase, voff) do { _Pragma("unroll") for (int _i = 0; _i < 2; ++_i) \
;         __builtin_amdgcn_global_load_lds((const unsigned*)((const char*)(gbase) + (voff)[_i]), (PG8_LAS unsigned*)(lds + (bufoff) + ldsw + _i * 8192), 16, 0, 0); } while (0)
; #define PG8_LDA(dst, b, h) do { _Pragma("unroll") for (int m = 0; m < 4; ++m) _Pragma("unroll") for (int k = 0; k < 2; ++k) dst[m][k] = *(const PG8_LAS bf16x8*)(lds + PG8_SA(b, h) + aoff + m * 2048 + k * 1024); } while (0)
; #define PG8_MMA(ai, bj, At, Bt) do { __builtin_amdgcn_s_setprio(1); _Pragma("unroll") for (int m = 0; m < 4; ++m) _Pragma("unroll") for (int n = 0; n < 2; ++n) _Pragma("unroll") for (int k = 0; k < 2; ++k) \
;         acc[ai][bj][m][n] = __builtin_amdgcn_mfma_f32_16x16x32_bf16(Bt[n][k], At[m][k], acc[ai][bj][m][n], 0, 0, 0); __builtin_amdgcn_s_setprio(0); } while (0)
; #define PG8_WAIT_V(n) asm volatile("s_waitcnt vmcnt(" #n ")" ::: "memory")
; #define PG8_WAIT_L(n) asm volatile("s_waitcnt lgkmcnt(" #n ")" ::: "memory")
; #define PG8_BAR __builtin_amdgcn_s_barrier()
; #define PG8_SCHED __builtin_amdgcn_sched_barrier(0)
; template <class Epi, class Sched, bool ALIGN_EPI = false, bool SP2 = false>
; __device__ __forceinline__ void gemm_phase(PG8_LAS unsigned char* lds, const Gemm g, const Sched& S, const Epi& E) {
;     ...
;             PG8_LDA(At, 1, 1); PG8_STAGE(PG8_SB(1, 0), b3, voffB); PG8_STAGE(PG8_SB(1, 1), b3 + hstepB, voffB); PG8_STAGE(PG8_SA(1, 0), a3, voffA);
;             PG8_WAIT_V(8); PG8_WAIT_L(0); PG8_BAR; PG8_MMA(1, 0, At, B0); PG8_MMA(1, 1, At, B1); PG8_BAR; PG8_SCHED;
	s_setprio 0
	s_add_i32 s28, s58, s40
	v_lshl_add_u64 v[148:149], v[148:149], 0, s[12:13]
	s_mov_b32 m0, s28
	ds_read_b128 v[188:191], v155 offset:49152
	ds_read_b128 v[192:195], v155 offset:50176
	ds_read_b128 v[196:199], v155 offset:51200
	ds_read_b128 v[200:203], v155 offset:52224
	ds_read_b128 v[204:207], v155 offset:53248
	ds_read_b128 v[208:211], v155 offset:54272
	ds_read_b128 v[212:215], v155 offset:55296
	ds_read_b128 v[216:219], v155 offset:56320
	global_load_lds_dwordx4 v[148:149], off
	s_add_i32 m0, s28, 0x2000
	s_add_u32 s28, s34, 0x18080
	v_lshl_add_u64 v[148:149], v[220:221], 0, s[12:13]
	s_addc_u32 s29, s35, 0
	s_add_i32 s34, s59, s40
	global_load_lds_dwordx4 v[148:149], off
	v_lshl_add_u64 v[148:149], s[28:29], 0, v[132:133]
	s_mov_b32 m0, s34
	s_nop 0
	global_load_lds_dwordx4 v[148:149], off
	v_lshl_add_u64 v[148:149], s[28:29], 0, v[128:129]
	s_add_i32 m0, s34, 0x2000
	s_nop 0
	global_load_lds_dwordx4 v[148:149], off
	v_lshl_add_u64 v[148:149], v[222:223], 0, s[12:13]
	s_mov_b32 m0, s47
	s_nop 0
	global_load_lds_dwordx4 v[148:149], off
	v_lshl_add_u64 v[148:149], v[224:225], 0, s[12:13]
	s_mov_b32 m0, s48
	s_nop 0
	global_load_lds_dwordx4 v[148:149], off
	s_waitcnt vmcnt(8)
	s_waitcnt lgkmcnt(0)
	s_barrier
	s_setprio 1
	s_waitcnt lgkmcnt(0)
	v_mfma_f32_16x16x32_bf16 v[60:63], v[144:147], v[188:191], v[60:63]
	v_mfma_f32_16x16x32_bf16 v[56:59], v[162:165], v[188:191], v[56:59]
	v_mfma_f32_16x16x32_bf16 v[44:47], v[144:147], v[196:199], v[44:47]
	v_mfma_f32_16x16x32_bf16 v[40:43], v[162:165], v[196:199], v[40:43]
	v_mfma_f32_16x16x32_bf16 v[28:31], v[144:147], v[204:207], v[28:31]
	v_mfma_f32_16x16x32_bf16 v[24:27], v[162:165], v[204:207], v[24:27]
	v_mfma_f32_16x16x32_bf16 v[12:15], v[144:147], v[212:215], v[12:15]
	v_mfma_f32_16x16x32_bf16 v[8:11], v[162:165], v[212:215], v[8:11]
	v_mfma_f32_16x16x32_bf16 v[60:63], v[158:161], v[192:195], v[60:63]
	v_mfma_f32_16x16x32_bf16 v[56:59], v[166:169], v[192:195], v[56:59]
	v_mfma_f32_16x16x32_bf16 v[44:47], v[158:161], v[200:203], v[44:47]
	v_mfma_f32_16x16x32_bf16 v[40:43], v[166:169], v[200:203], v[40:43]
	v_mfma_f32_16x16x32_bf16 v[28:31], v[158:161], v[208:211], v[28:31]
	v_mfma_f32_16x16x32_bf16 v[24:27], v[166:169], v[208:211], v[24:27]
	v_mfma_f32_16x16x32_bf16 v[12:15], v[158:161], v[216:219], v[12:15]
	v_mfma_f32_16x16x32_bf16 v[8:11], v[166:169], v[216:219], v[8:11]
	s_setprio 0
	s_setprio 1
	v_mfma_f32_16x16x32_bf16 v[52:55], v[170:173], v[188:191], v[52:55]
	v_mfma_f32_16x16x32_bf16 v[48:51], v[178:181], v[188:191], v[48:51]
	v_mfma_f32_16x16x32_bf16 v[36:39], v[170:173], v[196:199], v[36:39]
	v_mfma_f32_16x16x32_bf16 v[32:35], v[178:181], v[196:199], v[32:35]
	v_mfma_f32_16x16x32_bf16 v[20:23], v[170:173], v[204:207], v[20:23]
	v_mfma_f32_16x16x32_bf16 v[16:19], v[178:181], v[204:207], v[16:19]
	v_mfma_f32_16x16x32_bf16 v[4:7], v[170:173], v[212:215], v[4:7]
	v_mfma_f32_16x16x32_bf16 v[0:3], v[178:181], v[212:215], v[0:3]
	v_mfma_f32_16x16x32_bf16 v[52:55], v[174:177], v[192:195], v[52:55]
	v_mfma_f32_16x16x32_bf16 v[48:51], v[182:185], v[192:195], v[48:51]
	v_mfma_f32_16x16x32_bf16 v[36:39], v[174:177], v[200:203], v[36:39]
	v_mfma_f32_16x16x32_bf16 v[32:35], v[182:185], v[200:203], v[32:35]
	v_mfma_f32_16x16x32_bf16 v[20:23], v[174:177], v[208:211], v[20:23]
	v_mfma_f32_16x16x32_bf16 v[16:19], v[182:185], v[208:211], v[16:19]
	v_mfma_f32_16x16x32_bf16 v[4:7], v[174:177], v[216:219], v[4:7]
	v_mfma_f32_16x16x32_bf16 v[0:3], v[182:185], v[216:219], v[0:3]
	s_barrier
	s_setprio 0
	s_add_i32 s76, s76, 2
	s_add_u32 s74, s74, 0x100
	s_addc_u32 s75, s75, 0
	s_cmp_gt_u32 s76, 3
	s_mov_b64 s[28:29], s[30:31]
	s_cbranch_scc0 .LBB0_524
	s_and_b64 vcc, exec, s[14:15]
	s_cbranch_vccz .LBB0_527
	s_barrier

; #define PG8_STAGE(bufoff, gbase, voff) do { _Pragma("unroll") for (int _i = 0; _i < 2; ++_i) \
;         __builtin_amdgcn_global_load_lds((const unsigned*)((const char*)(gbase) + (voff)[_i]), (PG8_LAS unsigned*)(lds + (bufoff) + ldsw + _i * 8192), 16, 0, 0); } while (0)
; #define PG8_LDA(dst, b, h) do { _Pragma("unroll") for (int m = 0; m < 4; ++m) _Pragma("unroll") for (int k = 0; k < 2; ++k) dst[m][k] = *(const PG8_LAS bf16x8*)(lds + PG8_SA(b, h) + aoff + m * 2048 + k * 1024); } while (0)
; #define PG8_LDB(dst, b, h) do { _Pragma("unroll") for (int n = 0; n < 2; ++n) _Pragma("unroll") for (int k = 0; k < 2; ++k) dst[n][k] = *(const PG8_LAS bf16x8*)(lds + PG8_SB(b, h) + boff + n * 2048 + k * 1024); } while (0)
; #define PG8_MMA(ai, bj, At, Bt) do { __builtin_amdgcn_s_setprio(1); _Pragma("unroll") for (int m = 0; m < 4; ++m) _Pragma("unroll") for (int n = 0; n < 2; ++n) _Pragma("unroll") for (int k = 0; k < 2; ++k) \
;         acc[ai][bj][m][n] = __builtin_amdgcn_mfma_f32_16x16x32_bf16(Bt[n][k], At[m][k], acc[ai][bj][m][n], 0, 0, 0); __builtin_amdgcn_s_setprio(0); } while (0)
; #define PG8_WAIT_V(n) asm volatile("s_waitcnt vmcnt(" #n ")" ::: "memory")
; #define PG8_WAIT_L(n) asm volatile("s_waitcnt lgkmcnt(" #n ")" ::: "memory")
; #define PG8_BAR __builtin_amdgcn_s_barrier()
; #define PG8_SCHED __builtin_amdgcn_sched_barrier(0)
; template <class Epi, class Sched, bool ALIGN_EPI = false, bool SP2 = false>
; __device__ __forceinline__ void gemm_phase(PG8_LAS unsigned char* lds, const Gemm g, const Sched& S, const Epi& E) {
;     ...
;             PG8_LDB(B0, 0, 0); PG8_LDB(B1, 0, 1); PG8_SCHED; PG8_LDA(At, 0, 0); PG8_STAGE(PG8_SA(1, 1), a1 + hstepA, voffA);
;             PG8_WAIT_V(8); PG8_WAIT_L(0); PG8_BAR; PG8_MMA(0, 0, At, B0); PG8_MMA(0, 1, At, B1); PG8_BAR; PG8_SCHED;
;             PG8_LDA(At, 0, 1); PG8_STAGE(PG8_SB(0, 0), b2, voffB); PG8_STAGE(PG8_SB(0, 1), b2 + hstepB, voffB); PG8_STAGE(PG8_SA(0, 0), a2, voffA);
.LBB0_542:
	s_add_u32 s39, s34, s38
	s_addc_u32 s44, s35, 0
	s_add_u32 s42, s39, 0x100
	s_addc_u32 s43, s44, 0
	s_and_b64 s[40:41], s[36:37], exec
	s_cselect_b32 s41, s27, s43
	s_cselect_b32 s40, s26, s42
	s_add_u32 s38, s30, s38
	s_addc_u32 s42, s31, 0
	s_add_u32 s38, s38, 0x100
	s_addc_u32 s42, s42, 0
	s_and_b64 s[36:37], s[36:37], exec
	s_cselect_b32 s43, s25, s42
	s_cselect_b32 s42, s89, s38
	s_add_u32 s46, s39, 0x30080
	ds_read_b128 v[140:143], v149
	ds_read_b128 v[154:157], v149 offset:1024
	ds_read_b128 v[158:161], v149 offset:2048
	ds_read_b128 v[162:165], v149 offset:3072
	ds_read_b128 v[166:169], v150
	ds_read_b128 v[170:173], v150 offset:1024
	ds_read_b128 v[174:177], v150 offset:2048
	ds_read_b128 v[178:181], v150 offset:3072
	s_addc_u32 s47, s44, 0
	s_add_i32 vcc_hi, s78, s68
	s_add_i32 m0, s70, 0xc000
	s_add_i32 s58, s70, 0xe000
	s_add_i32 s96, vcc_hi, 0x2000
	s_add_u32 s44, s42, 0x10000
	s_addc_u32 s45, s43, 0
	s_add_i32 vcc_lo, s79, s68
	s_add_i32 s97, vcc_lo, 0x2000
	s_add_i32 s95, 0, 0x18000
	s_add_i32 s94, 0, 0x1c000
	s_add_u32 s38, s40, 0x30000
	s_addc_u32 s39, s41, 0
	s_add_i32 s93, s95, s68
	s_add_i32 s91, s93, 0x2000
	s_add_u32 s36, s42, 0x10080
	s_addc_u32 s37, s43, 0
	s_add_i32 s92, s94, s68
	s_add_i32 s90, s92, 0x2000
	v_lshl_add_u64 v[144:145], s[46:47], 0, v[134:135]
	ds_read_b128 v[182:185], v151
	ds_read_b128 v[188:191], v151 offset:1024
	ds_read_b128 v[192:195], v151 offset:2048
	ds_read_b128 v[196:199], v151 offset:3072
	ds_read_b128 v[200:203], v151 offset:4096
	ds_read_b128 v[204:207], v151 offset:5120
	ds_read_b128 v[208:211], v151 offset:6144
	ds_read_b128 v[212:215], v151 offset:7168
	global_load_lds_dwordx4 v[144:145], off
	v_lshl_add_u64 v[144:145], s[46:47], 0, v[130:131]
	s_mov_b32 m0, s58
	s_nop 0
	global_load_lds_dwordx4 v[144:145], off
	s_waitcnt vmcnt(8)
	s_waitcnt lgkmcnt(0)
	s_barrier
	s_setprio 1
	s_waitcnt lgkmcnt(0)
	v_mfma_f32_16x16x32_bf16 v[124:127], v[140:143], v[182:185], v[124:127]
	v_mfma_f32_16x16x32_bf16 v[120:123], v[158:161], v[182:185], v[120:123]
	v_mfma_f32_16x16x32_bf16 v[108:111], v[140:143], v[192:195], v[108:111]
	v_mfma_f32_16x16x32_bf16 v[104:107], v[158:161], v[192:195], v[104:107]
	v_mfma_f32_16x16x32_bf16 v[92:95], v[140:143], v[200:203], v[92:95]
	v_mfma_f32_16x16x32_bf16 v[88:91], v[158:161], v[200:203], v[88:91]
	v_mfma_f32_16x16x32_bf16 v[76:79], v[140:143], v[208:211], v[76:79]
	v_mfma_f32_16x16x32_bf16 v[72:75], v[158:161], v[208:211], v[72:75]
	v_mfma_f32_16x16x32_bf16 v[124:127], v[154:157], v[188:191], v[124:127]
	v_mfma_f32_16x16x32_bf16 v[120:123], v[162:165], v[188:191], v[120:123]
	v_mfma_f32_16x16x32_bf16 v[108:111], v[154:157], v[196:199], v[108:111]
	v_mfma_f32_16x16x32_bf16 v[104:107], v[162:165], v[196:199], v[104:107]
	v_mfma_f32_16x16x32_bf16 v[92:95], v[154:157], v[204:207], v[92:95]
	v_mfma_f32_16x16x32_bf16 v[88:91], v[162:165], v[204:207], v[88:91]
	v_mfma_f32_16x16x32_bf16 v[76:79], v[154:157], v[212:215], v[76:79]
	v_mfma_f32_16x16x32_bf16 v[72:75], v[162:165], v[212:215], v[72:75]
	s_setprio 0
	s_setprio 1
	v_mfma_f32_16x16x32_bf16 v[116:119], v[166:169], v[182:185], v[116:119]
	v_mfma_f32_16x16x32_bf16 v[112:115], v[174:177], v[182:185], v[112:115]
	v_mfma_f32_16x16x32_bf16 v[100:103], v[166:169], v[192:195], v[100:103]
	v_mfma_f32_16x16x32_bf16 v[96:99], v[174:177], v[192:195], v[96:99]
	v_mfma_f32_16x16x32_bf16 v[84:87], v[166:169], v[200:203], v[84:87]
	v_mfma_f32_16x16x32_bf16 v[80:83], v[174:177], v[200:203], v[80:83]
	v_mfma_f32_16x16x32_bf16 v[68:71], v[166:169], v[208:211], v[68:71]
	v_mfma_f32_16x16x32_bf16 v[64:67], v[174:177], v[208:211], v[64:67]
	v_mfma_f32_16x16x32_bf16 v[116:119], v[170:173], v[188:191], v[116:119]
	v_mfma_f32_16x16x32_bf16 v[112:115], v[178:181], v[188:191], v[112:115]
	v_mfma_f32_16x16x32_bf16 v[100:103], v[170:173], v[196:199], v[100:103]
	v_mfma_f32_16x16x32_bf16 v[96:99], v[178:181], v[196:199], v[96:99]
	v_mfma_f32_16x16x32_bf16 v[84:87], v[170:173], v[204:207], v[84:87]
	v_mfma_f32_16x16x32_bf16 v[80:83], v[178:181], v[204:207], v[80:83]
	v_mfma_f32_16x16x32_bf16 v[68:71], v[170:173], v[212:215], v[68:71]
	v_mfma_f32_16x16x32_bf16 v[64:67], v[178:181], v[212:215], v[64:67]
	s_barrier
	s_setprio 0
	s_mov_b32 m0, vcc_hi
	v_lshl_add_u64 v[144:145], s[42:43], 0, v[132:133]
	ds_read_b128 v[182:185], v151 offset:16384
	ds_read_b128 v[188:191], v151 offset:17408
	ds_read_b128 v[192:195], v151 offset:18432
	ds_read_b128 v[196:199], v151 offset:19456
	ds_read_b128 v[200:203], v151 offset:20480
	ds_read_b128 v[204:207], v151 offset:21504
	ds_read_b128 v[208:211], v151 offset:22528
	ds_read_b128 v[212:215], v151 offset:23552
	global_load_lds_dwordx4 v[144:145], off
	v_lshl_add_u64 v[216:217], s[42:43], 0, v[128:129]
	s_mov_b32 m0, s96
	v_lshl_add_u64 v[218:219], s[44:45], 0, v[132:133]
	global_load_lds_dwordx4 v[216:217], off
	s_mov_b32 m0, vcc_lo
	v_lshl_add_u64 v[220:221], s[40:41], 0, v[130:131]
	global_load_lds_dwordx4 v[218:219], off
	v_lshl_add_u64 v[218:219], s[44:45], 0, v[128:129]
	s_mov_b32 m0, s97
	s_nop 0
	global_load_lds_dwordx4 v[218:219], off
	v_lshl_add_u64 v[218:219], s[40:41], 0, v[134:135]
	s_mov_b32 m0, s70
	s_nop 0
	global_load_lds_dwordx4 v[218:219], off
	s_mov_b32 m0, s71
	s_nop 0
	global_load_lds_dwordx4 v[220:221], off
	s_waitcnt vmcnt(8)
	s_waitcnt lgkmcnt(0)
	s_barrier
; #define PG8_STAGE(bufoff, gbase, voff) do { _Pragma("unroll") for (int _i = 0; _i < 2; ++_i) \
;         __builtin_amdgcn_global_load_lds((const unsigned*)((const char*)(gbase) + (voff)[_i]), (PG8_LAS unsigned*)(lds + (bufoff) + ldsw + _i * 8192), 16, 0, 0); } while (0)
; #define PG8_LDA(dst, b, h) do { _Pragma("unroll") for (int m = 0; m < 4; ++m) _Pragma("unroll") for (int k = 0; k < 2; ++k) dst[m][k] = *(const PG8_LAS bf16x8*)(lds + PG8_SA(b, h) + aoff + m * 2048 + k * 1024); } while (0)
; #define PG8_LDB(dst, b, h) do { _Pragma("unroll") for (int n = 0; n < 2; ++n) _Pragma("unroll") for (int k = 0; k < 2; ++k) dst[n][k] = *(const PG8_LAS bf16x8*)(lds + PG8_SB(b, h) + boff + n * 2048 + k * 1024); } while (0)
; #define PG8_MMA(ai, bj, At, Bt) do { __builtin_amdgcn_s_setprio(1); _Pragma("unroll") for (int m = 0; m < 4; ++m) _Pragma("unroll") for (int n = 0; n < 2; ++n) _Pragma("unroll") for (int k = 0; k < 2; ++k) \
;         acc[ai][bj][m][n] = __builtin_amdgcn_mfma_f32_16x16x32_bf16(Bt[n][k], At[m][k], acc[ai][bj][m][n], 0, 0, 0); __builtin_amdgcn_s_setprio(0); } while (0)
; #define PG8_WAIT_V(n) asm volatile("s_waitcnt vmcnt(" #n ")" ::: "memory")
; #define PG8_WAIT_L(n) asm volatile("s_waitcnt lgkmcnt(" #n ")" ::: "memory")
; #define PG8_BAR __builtin_amdgcn_s_barrier()
; #define PG8_SCHED __builtin_amdgcn_sched_barrier(0)
; template <class Epi, class Sched, bool ALIGN_EPI = false, bool SP2 = false>
; __device__ __forceinline__ void gemm_phase(PG8_LAS unsigned char* lds, const Gemm g, const Sched& S, const Epi& E) {
;     ...
;             PG8_WAIT_V(8); PG8_WAIT_L(0); PG8_BAR; PG8_MMA(1, 0, At, B0); PG8_MMA(1, 1, At, B1); PG8_BAR; PG8_SCHED;
;             PG8_LDB(B0, 1, 0); PG8_LDB(B1, 1, 1); PG8_SCHED; PG8_LDA(At, 1, 0); PG8_STAGE(PG8_SA(0, 1), a2 + hstepA, voffA);
;             PG8_WAIT_V(8); PG8_WAIT_L(0); PG8_BAR; PG8_MMA(0, 0, At, B0); PG8_MMA(0, 1, At, B1); PG8_BAR; PG8_SCHED;
	s_setprio 1
	s_waitcnt lgkmcnt(0)
	v_mfma_f32_16x16x32_bf16 v[60:63], v[140:143], v[182:185], v[60:63]
	v_mfma_f32_16x16x32_bf16 v[56:59], v[158:161], v[182:185], v[56:59]
	v_mfma_f32_16x16x32_bf16 v[44:47], v[140:143], v[192:195], v[44:47]
	v_mfma_f32_16x16x32_bf16 v[40:43], v[158:161], v[192:195], v[40:43]
	v_mfma_f32_16x16x32_bf16 v[28:31], v[140:143], v[200:203], v[28:31]
	v_mfma_f32_16x16x32_bf16 v[24:27], v[158:161], v[200:203], v[24:27]
	v_mfma_f32_16x16x32_bf16 v[12:15], v[140:143], v[208:211], v[12:15]
	v_mfma_f32_16x16x32_bf16 v[8:11], v[158:161], v[208:211], v[8:11]
	v_mfma_f32_16x16x32_bf16 v[60:63], v[154:157], v[188:191], v[60:63]
	v_mfma_f32_16x16x32_bf16 v[56:59], v[162:165], v[188:191], v[56:59]
	v_mfma_f32_16x16x32_bf16 v[44:47], v[154:157], v[196:199], v[44:47]
	v_mfma_f32_16x16x32_bf16 v[40:43], v[162:165], v[196:199], v[40:43]
	v_mfma_f32_16x16x32_bf16 v[28:31], v[154:157], v[204:207], v[28:31]
	v_mfma_f32_16x16x32_bf16 v[24:27], v[162:165], v[204:207], v[24:27]
	v_mfma_f32_16x16x32_bf16 v[12:15], v[154:157], v[212:215], v[12:15]
	v_mfma_f32_16x16x32_bf16 v[8:11], v[162:165], v[212:215], v[8:11]
	s_setprio 0
	s_setprio 1
	v_mfma_f32_16x16x32_bf16 v[52:55], v[166:169], v[182:185], v[52:55]
	v_mfma_f32_16x16x32_bf16 v[48:51], v[174:177], v[182:185], v[48:51]
	v_mfma_f32_16x16x32_bf16 v[36:39], v[166:169], v[192:195], v[36:39]
	v_mfma_f32_16x16x32_bf16 v[32:35], v[174:177], v[192:195], v[32:35]
	v_mfma_f32_16x16x32_bf16 v[20:23], v[166:169], v[200:203], v[20:23]
	v_mfma_f32_16x16x32_bf16 v[16:19], v[174:177], v[200:203], v[16:19]
	v_mfma_f32_16x16x32_bf16 v[4:7], v[166:169], v[208:211], v[4:7]
	v_mfma_f32_16x16x32_bf16 v[0:3], v[174:177], v[208:211], v[0:3]
	v_mfma_f32_16x16x32_bf16 v[52:55], v[170:173], v[188:191], v[52:55]
	v_mfma_f32_16x16x32_bf16 v[48:51], v[178:181], v[188:191], v[48:51]
	v_mfma_f32_16x16x32_bf16 v[36:39], v[170:173], v[196:199], v[36:39]
	v_mfma_f32_16x16x32_bf16 v[32:35], v[178:181], v[196:199], v[32:35]
	v_mfma_f32_16x16x32_bf16 v[20:23], v[170:173], v[204:207], v[20:23]
	v_mfma_f32_16x16x32_bf16 v[16:19], v[178:181], v[204:207], v[16:19]
	v_mfma_f32_16x16x32_bf16 v[4:7], v[170:173], v[212:215], v[4:7]
	v_mfma_f32_16x16x32_bf16 v[0:3], v[178:181], v[212:215], v[0:3]
	s_barrier
	s_setprio 0
	v_add_u32_e32 v153, s95, v147
	ds_read_b128 v[140:143], v153
	ds_read_b128 v[154:157], v153 offset:1024
	ds_read_b128 v[158:161], v153 offset:2048
	ds_read_b128 v[162:165], v153 offset:3072
	v_add_u32_e32 v153, s94, v147
	ds_read_b128 v[166:169], v153
	ds_read_b128 v[170:173], v153 offset:1024
	ds_read_b128 v[174:177], v153 offset:2048
	ds_read_b128 v[178:181], v153 offset:3072
	s_mov_b32 m0, s72
	v_lshl_add_u64 v[222:223], s[38:39], 0, v[134:135]
	ds_read_b128 v[182:185], v151 offset:32768
	ds_read_b128 v[188:191], v151 offset:33792
	ds_read_b128 v[192:195], v151 offset:34816
	ds_read_b128 v[196:199], v151 offset:35840
	ds_read_b128 v[200:203], v151 offset:36864
	ds_read_b128 v[204:207], v151 offset:37888
	ds_read_b128 v[208:211], v151 offset:38912
	ds_read_b128 v[212:215], v151 offset:39936
	global_load_lds_dwordx4 v[222:223], off
	v_lshl_add_u64 v[222:223], s[38:39], 0, v[130:131]
	s_mov_b32 m0, s73
	s_nop 0
	global_load_lds_dwordx4 v[222:223], off
	s_waitcnt vmcnt(8)
	s_waitcnt lgkmcnt(0)
	s_barrier
	s_setprio 1
	s_waitcnt lgkmcnt(0)
	v_mfma_f32_16x16x32_bf16 v[124:127], v[140:143], v[182:185], v[124:127]
	v_mfma_f32_16x16x32_bf16 v[120:123], v[158:161], v[182:185], v[120:123]
	v_mfma_f32_16x16x32_bf16 v[108:111], v[140:143], v[192:195], v[108:111]
	v_mfma_f32_16x16x32_bf16 v[104:107], v[158:161], v[192:195], v[104:107]
	v_mfma_f32_16x16x32_bf16 v[92:95], v[140:143], v[200:203], v[92:95]
	v_mfma_f32_16x16x32_bf16 v[88:91], v[158:161], v[200:203], v[88:91]
	v_mfma_f32_16x16x32_bf16 v[76:79], v[140:143], v[208:211], v[76:79]
	v_mfma_f32_16x16x32_bf16 v[72:75], v[158:161], v[208:211], v[72:75]
	v_mfma_f32_16x16x32_bf16 v[124:127], v[154:157], v[188:191], v[124:127]
	v_mfma_f32_16x16x32_bf16 v[120:123], v[162:165], v[188:191], v[120:123]
	v_mfma_f32_16x16x32_bf16 v[108:111], v[154:157], v[196:199], v[108:111]
	v_mfma_f32_16x16x32_bf16 v[104:107], v[162:165], v[196:199], v[104:107]
	v_mfma_f32_16x16x32_bf16 v[92:95], v[154:157], v[204:207], v[92:95]
	v_mfma_f32_16x16x32_bf16 v[88:91], v[162:165], v[204:207], v[88:91]
	v_mfma_f32_16x16x32_bf16 v[76:79], v[154:157], v[212:215], v[76:79]
	v_mfma_f32_16x16x32_bf16 v[72:75], v[162:165], v[212:215], v[72:75]
	s_setprio 0
	s_setprio 1
	v_mfma_f32_16x16x32_bf16 v[116:119], v[166:169], v[182:185], v[116:119]
	v_mfma_f32_16x16x32_bf16 v[112:115], v[174:177], v[182:185], v[112:115]
	v_mfma_f32_16x16x32_bf16 v[100:103], v[166:169], v[192:195], v[100:103]
	v_mfma_f32_16x16x32_bf16 v[96:99], v[174:177], v[192:195], v[96:99]
	v_mfma_f32_16x16x32_bf16 v[84:87], v[166:169], v[200:203], v[84:87]
	v_mfma_f32_16x16x32_bf16 v[80:83], v[174:177], v[200:203], v[80:83]
	v_mfma_f32_16x16x32_bf16 v[68:71], v[166:169], v[208:211], v[68:71]
	v_mfma_f32_16x16x32_bf16 v[64:67], v[174:177], v[208:211], v[64:67]
	v_mfma_f32_16x16x32_bf16 v[116:119], v[170:173], v[188:191], v[116:119]
	v_mfma_f32_16x16x32_bf16 v[112:115], v[178:181], v[188:191], v[112:115]
	v_mfma_f32_16x16x32_bf16 v[100:103], v[170:173], v[196:199], v[100:103]
	v_mfma_f32_16x16x32_bf16 v[96:99], v[178:181], v[196:199], v[96:99]
	v_mfma_f32_16x16x32_bf16 v[84:87], v[170:173], v[204:207], v[84:87]
	v_mfma_f32_16x16x32_bf16 v[80:83], v[178:181], v[204:207], v[80:83]
	v_mfma_f32_16x16x32_bf16 v[68:71], v[170:173], v[212:215], v[68:71]
	v_mfma_f32_16x16x32_bf16 v[64:67], v[178:181], v[212:215], v[64:67]
	s_barrier
; #define PG8_STAGE(bufoff, gbase, voff) do { _Pragma("unroll") for (int _i = 0; _i < 2; ++_i) \
;         __builtin_amdgcn_global_load_lds((const unsigned*)((const char*)(gbase) + (voff)[_i]), (PG8_LAS unsigned*)(lds + (bufoff) + ldsw + _i * 8192), 16, 0, 0); } while (0)
; #define PG8_LDA(dst, b, h) do { _Pragma("unroll") for (int m = 0; m < 4; ++m) _Pragma("unroll") for (int k = 0; k < 2; ++k) dst[m][k] = *(const PG8_LAS bf16x8*)(lds + PG8_SA(b, h) + aoff + m * 2048 + k * 1024); } while (0)
; #define PG8_MMA(ai, bj, At, Bt) do { __builtin_amdgcn_s_setprio(1); _Pragma("unroll") for (int m = 0; m < 4; ++m) _Pragma("unroll") for (int n = 0; n < 2; ++n) _Pragma("unroll") for (int k = 0; k < 2; ++k) \
;         acc[ai][bj][m][n] = __builtin_amdgcn_mfma_f32_16x16x32_bf16(Bt[n][k], At[m][k], acc[ai][bj][m][n], 0, 0, 0); __builtin_amdgcn_s_setprio(0); } while (0)
; #define PG8_WAIT_V(n) asm volatile("s_waitcnt vmcnt(" #n ")" ::: "memory")
; #define PG8_WAIT_L(n) asm volatile("s_waitcnt lgkmcnt(" #n ")" ::: "memory")
; #define PG8_BAR __builtin_amdgcn_s_barrier()
; #define PG8_SCHED __builtin_amdgcn_sched_barrier(0)
; template <class Epi, class Sched, bool ALIGN_EPI = false, bool SP2 = false>
; __device__ __forceinline__ void gemm_phase(PG8_LAS unsigned char* lds, const Gemm g, const Sched& S, const Epi& E) {
;     ...
;             PG8_LDA(At, 1, 1); PG8_STAGE(PG8_SB(1, 0), b3, voffB); PG8_STAGE(PG8_SB(1, 1), b3 + hstepB, voffB); PG8_STAGE(PG8_SA(1, 0), a3, voffA);
;             PG8_WAIT_V(8); PG8_WAIT_L(0); PG8_BAR; PG8_MMA(1, 0, At, B0); PG8_MMA(1, 1, At, B1); PG8_BAR; PG8_SCHED;
	s_setprio 0
	s_mov_b32 m0, s93
	v_lshl_add_u64 v[144:145], v[144:145], 0, s[12:13]
	ds_read_b128 v[182:185], v151 offset:49152
	ds_read_b128 v[188:191], v151 offset:50176
	ds_read_b128 v[192:195], v151 offset:51200
	ds_read_b128 v[196:199], v151 offset:52224
	ds_read_b128 v[200:203], v151 offset:53248
	ds_read_b128 v[204:207], v151 offset:54272
	ds_read_b128 v[208:211], v151 offset:55296
	ds_read_b128 v[212:215], v151 offset:56320
	global_load_lds_dwordx4 v[144:145], off
	v_lshl_add_u64 v[144:145], v[216:217], 0, s[12:13]
	s_mov_b32 m0, s91
	s_nop 0
	global_load_lds_dwordx4 v[144:145], off
	v_lshl_add_u64 v[144:145], s[36:37], 0, v[132:133]
	s_mov_b32 m0, s92
	s_nop 0
	global_load_lds_dwordx4 v[144:145], off
	v_lshl_add_u64 v[144:145], s[36:37], 0, v[128:129]
	s_mov_b32 m0, s90
	s_nop 0
	global_load_lds_dwordx4 v[144:145], off
	v_lshl_add_u64 v[144:145], v[218:219], 0, s[12:13]
	s_mov_b32 m0, s75
	s_nop 0
	global_load_lds_dwordx4 v[144:145], off
	v_lshl_add_u64 v[144:145], v[220:221], 0, s[12:13]
	s_mov_b32 m0, s76
	s_nop 0
	global_load_lds_dwordx4 v[144:145], off
	s_waitcnt vmcnt(8)
	s_waitcnt lgkmcnt(0)
	s_barrier
	s_setprio 1
	s_waitcnt lgkmcnt(0)
	v_mfma_f32_16x16x32_bf16 v[60:63], v[140:143], v[182:185], v[60:63]
	v_mfma_f32_16x16x32_bf16 v[56:59], v[158:161], v[182:185], v[56:59]
	v_mfma_f32_16x16x32_bf16 v[44:47], v[140:143], v[192:195], v[44:47]
	v_mfma_f32_16x16x32_bf16 v[40:43], v[158:161], v[192:195], v[40:43]
	v_mfma_f32_16x16x32_bf16 v[28:31], v[140:143], v[200:203], v[28:31]
	v_mfma_f32_16x16x32_bf16 v[24:27], v[158:161], v[200:203], v[24:27]
	v_mfma_f32_16x16x32_bf16 v[12:15], v[140:143], v[208:211], v[12:15]
	v_mfma_f32_16x16x32_bf16 v[8:11], v[158:161], v[208:211], v[8:11]
	v_mfma_f32_16x16x32_bf16 v[60:63], v[154:157], v[188:191], v[60:63]
	v_mfma_f32_16x16x32_bf16 v[56:59], v[162:165], v[188:191], v[56:59]
	v_mfma_f32_16x16x32_bf16 v[44:47], v[154:157], v[196:199], v[44:47]
	v_mfma_f32_16x16x32_bf16 v[40:43], v[162:165], v[196:199], v[40:43]
	v_mfma_f32_16x16x32_bf16 v[28:31], v[154:157], v[204:207], v[28:31]
	v_mfma_f32_16x16x32_bf16 v[24:27], v[162:165], v[204:207], v[24:27]
	v_mfma_f32_16x16x32_bf16 v[12:15], v[154:157], v[212:215], v[12:15]
	v_mfma_f32_16x16x32_bf16 v[8:11], v[162:165], v[212:215], v[8:11]
	s_setprio 0
	s_setprio 1
	v_mfma_f32_16x16x32_bf16 v[52:55], v[166:169], v[182:185], v[52:55]
	v_mfma_f32_16x16x32_bf16 v[48:51], v[174:177], v[182:185], v[48:51]
	v_mfma_f32_16x16x32_bf16 v[36:39], v[166:169], v[192:195], v[36:39]
	v_mfma_f32_16x16x32_bf16 v[32:35], v[174:177], v[192:195], v[32:35]
	v_mfma_f32_16x16x32_bf16 v[20:23], v[166:169], v[200:203], v[20:23]
	v_mfma_f32_16x16x32_bf16 v[16:19], v[174:177], v[200:203], v[16:19]
	v_mfma_f32_16x16x32_bf16 v[4:7], v[166:169], v[208:211], v[4:7]
	v_mfma_f32_16x16x32_bf16 v[0:3], v[174:177], v[208:211], v[0:3]
	v_mfma_f32_16x16x32_bf16 v[52:55], v[170:173], v[188:191], v[52:55]
	v_mfma_f32_16x16x32_bf16 v[48:51], v[178:181], v[188:191], v[48:51]
	v_mfma_f32_16x16x32_bf16 v[36:39], v[170:173], v[196:199], v[36:39]
	v_mfma_f32_16x16x32_bf16 v[32:35], v[178:181], v[196:199], v[32:35]
	v_mfma_f32_16x16x32_bf16 v[20:23], v[170:173], v[204:207], v[20:23]
	v_mfma_f32_16x16x32_bf16 v[16:19], v[178:181], v[204:207], v[16:19]
	v_mfma_f32_16x16x32_bf16 v[4:7], v[170:173], v[212:215], v[4:7]
	v_mfma_f32_16x16x32_bf16 v[0:3], v[178:181], v[212:215], v[0:3]
	s_barrier
	s_setprio 0
	s_movk_i32 s38, 0x100
	s_andn2_b64 vcc, exec, s[8:9]
	s_mov_b64 s[36:37], -1
	s_mov_b64 s[8:9], 0
	s_cbranch_vccz .LBB0_542
	s_and_b64 vcc, exec, s[14:15]
	s_cbranch_vccz .LBB0_545
	s_barrier

; __device__ __forceinline__ int v_st(int k, int c) { const int kk = (k & ~0xC) | ((k & 4) << 1) | ((k & 8) >> 1); return ((kk >> 3) * 4 + (c >> 5)) * 512 + ((kk & 7) * 32 + (c & 31)) * 2; }
; __device__ __forceinline__ int v_rd_base(int lane) { return ((lane & 3) << 3) | (((lane >> 2) & 3) << 6) | (((lane >> 4) & 1) << 5) | (((lane >> 5) & 1) << 8); }
; #define SLOAD(i, k0) do { sr_[i].v = *reinterpret_cast<const bf16x8*>(vp + (long)(k0) * LDV); sr_[i].k = *reinterpret_cast<const bf16x8*>(kp + (long)(k0) * LDKN); \
;     if (has_r) sr_[i].r = *reinterpret_cast<const bf16x8*>(rp + (long)(k0) * LDKR); } while (0)
; __device__ __forceinline__ void attn_unit(const bf16_t* __restrict__ Qb, const bf16_t* __restrict__ KNh, const bf16_t* __restrict__ KRb, const bf16_t* __restrict__ Vh, ...
;     ...
;   float m_ref = 0.f; f32x16 o[2] = {}; f32x16 osum = {}; f32x16 negm = {}; asm volatile("" : "+v"(negm)); bf16x8 qr[6];
;   const int srow = tid >> 3, sch = tid & 7, srow2 = tid >> 2, sch2 = tid & 3;
;   const bf16_t* kp = KNh + (long)srow * LDKN + 8 * sch; const bf16_t* vp = Vh + (long)srow * LDV + 8 * sch; const bf16_t* rp = KRb + (long)(srow2 & 63) * LDKR + 8 * sch2;
;   const int kst = KSWZ(srow, 16 * sch), vst = v_st(srow, 8 * sch), rst = KSWZ(srow2 & 63, 128 + 16 * sch2);
;   const bool has_r = wid < 4;
;   constexpr int BUF = SHM_V;
;   const int vb0 = (int)(uintptr_t)V_lds + v_rd_base(lane);
;   struct { bf16x8 v, k, r; } sr_[2];
;     ...
;   constexpr int SE = 0, SO = 1;
;   const int NT = seq / KVBLK;
;   SLOAD(SE, 0); SLOAD(SO, KVBLK);
.LBB0_709:
	s_ashr_i32 s9, s8, 31
	s_lshl_b64 s[38:39], s[8:9], 10
	s_add_u32 s6, s81, s38
	s_addc_u32 s7, s82, s39
	s_lshl_b32 s30, s36, 7
	s_add_u32 s6, s6, s30
	s_addc_u32 s7, s7, 0
	s_lshl_b64 s[40:41], s[8:9], 6
	s_add_u32 s28, s20, s40
	s_addc_u32 s29, s21, s41
	v_mov_b32_e32 v96, v186
	s_add_u32 s9, s83, s38
	s_addc_u32 s31, s84, s39
	v_ashrrev_i32_e32 v40, 3, v96
	v_ashrrev_i32_e32 v41, 31, v40
	v_lshlrev_b32_e32 v34, 3, v96
	s_add_u32 s30, s9, s30
	v_lshlrev_b64 v[56:57], 10, v[40:41]
	v_and_b32_e32 v41, 56, v34
	s_addc_u32 s31, s31, 0
	v_lshl_add_u64 v[32:33], s[6:7], 0, v[56:57]
	v_lshlrev_b32_e32 v176, 1, v41
	v_mov_b64_e32 v[30:31], 0
	v_lshl_add_u64 v[60:61], v[32:33], 0, v[176:177]
	v_lshl_add_u64 v[32:33], s[30:31], 0, v[56:57]
	v_mov_b64_e32 v[28:29], 0
	v_mov_b64_e32 v[26:27], 0
	v_mov_b64_e32 v[24:25], 0
	v_mov_b64_e32 v[22:23], 0
	v_mov_b64_e32 v[20:21], 0
	v_mov_b64_e32 v[18:19], 0
	v_mov_b64_e32 v[16:17], 0
	v_lshl_add_u64 v[62:63], v[32:33], 0, v[176:177]
	global_load_dwordx4 v[36:39], v[62:63], off
	global_load_dwordx4 v[32:35], v[60:61], off
	v_readfirstlane_b32 s37, v96
	s_ashr_i32 s9, s37, 6
	v_bfe_u32 v43, v96, 2, 6
	v_lshlrev_b32_e32 v44, 6, v43
	v_mov_b32_e32 v45, v177
	s_cmp_lt_i32 s9, 4
	v_and_b32_e32 v42, 3, v96
	v_lshl_add_u64 v[44:45], s[28:29], 0, v[44:45]
	s_cselect_b64 s[28:29], -1, 0
	s_cmp_gt_i32 s9, 3
	v_lshlrev_b32_e32 v58, 4, v42
	v_mov_b32_e32 v59, v177
	s_cselect_b64 s[34:35], -1, 0
	v_lshl_add_u64 v[80:81], v[44:45], 0, v[58:59]
	s_and_b64 vcc, exec, s[34:35]
	s_cbranch_vccnz .LBB0_711
	global_load_dwordx4 v[132:135], v[80:81], off

; __device__ __forceinline__ unsigned cvtpk(float lo, float hi) { unsigned r; asm volatile("v_cvt_pk_bf16_f32 %0, %1, %2" : "=v"(r) : "v"(lo), "v"(hi)); return r; }
; __device__ __forceinline__ int v_st(int k, int c) { const int kk = (k & ~0xC) | ((k & 4) << 1) | ((k & 8) >> 1); return ((kk >> 3) * 4 + (c >> 5)) * 512 + ((kk & 7) * 32 + (c & 31)) * 2; }
; __device__ __forceinline__ void attn_unit(const bf16_t* __restrict__ Qb, const bf16_t* __restrict__ KNh, const bf16_t* __restrict__ KRb, const bf16_t* __restrict__ Vh, ...
;     ...
;   const int srow = tid >> 3, sch = tid & 7, srow2 = tid >> 2, sch2 = tid & 3;
;   const bf16_t* kp = KNh + (long)srow * LDKN + 8 * sch; const bf16_t* vp = Vh + (long)srow * LDV + 8 * sch; const bf16_t* rp = KRb + (long)(srow2 & 63) * LDKR + 8 * sch2;
;   const int kst = KSWZ(srow, 16 * sch), vst = v_st(srow, 8 * sch), rst = KSWZ(srow2 & 63, 128 + 16 * sch2);
;   const bool has_r = wid < 4;
;   constexpr int BUF = SHM_V;
;   const int vb0 = (int)(uintptr_t)V_lds + v_rd_base(lane);
;   struct { bf16x8 v, k, r; } sr_[2];
;     ...
;   constexpr int SE = 0, SO = 1;
;   const int NT = seq / KVBLK;
;   SLOAD(SE, 0); SLOAD(SO, KVBLK);
;   const bf16_t* Qw = Qb + (long)(wid * QBLK + r32) * LDQ + hi * 8;
; #pragma unroll
;   for (int d0 = 0; d0 < 6; ++d0) qr[d0] = *reinterpret_cast<const bf16x8*>(Qw + d0 * 16);
;   {
;     const int pos = row_pos(qrow0 + wid * QBLK + r32); const float* cp = ropec + pos * 16 + 8 * hi; const float* sp = ropes + pos * 16 + 8 * hi;
;     unsigned w1[4], w2[4];
; #pragma unroll
;     for (int e = 0; e < 8; e += 2) { float o1[2], o2[2];
; #pragma unroll
;       for (int f = 0; f < 2; ++f) { const float x1 = __uint_as_float(((unsigned)(unsigned short)qr[4][e + f]) << 16), x2 = __uint_as_float(((unsigned)(unsigned short)qr[5][e + f]) << 16); const float c = cp[e + f], s = sp[e + f];
;         o1[f] = x1 * c - x2 * s; o2[f] = x1 * s + x2 * c; }
;       w1[e >> 1] = cvtpk(o1[0], o1[1]); w2[e >> 1] = cvtpk(o2[0], o2[1]); }
;     u32x4 v1 = {w1[0], w1[1], w1[2], w1[3]}, v2 = {w2[0], w2[1], w2[2], w2[3]}; qr[4] = *reinterpret_cast<bf16x8*>(&v1); qr[5] = *reinterpret_cast<bf16x8*>(&v2); }
;     ...
;   f32x16 pA0, pA1, pB0, pB1; float alA, alB; bf16x8 pa0, pa1, pa2, pa3;
;   int o_prev = 2 * BUF, o_cur = 0, o_next = BUF;
;   asm volatile("s_waitcnt vmcnt(0)" ::: "memory"); SWRITE(0, SE); __syncthreads();
.LBB0_713:
	s_lshl_b32 s10, s10, 8
	s_add_i32 s30, s10, s8
	s_mul_i32 s10, s30, 0x600
	s_mul_hi_i32 s8, s30, 0x600
	s_add_u32 s31, s52, s10
	s_mul_i32 s10, s36, 0x60
	s_addc_u32 s8, s53, s8
	s_lshl_b64 s[28:29], s[10:11], 1
	s_add_u32 s58, s31, s28
	s_addc_u32 s59, s8, s29
	v_and_b32_e32 v189, 31, v96
	s_lshl_b32 s28, s9, 5
	v_or_b32_e32 v46, s28, v189
	v_mov_b64_e32 v[44:45], s[58:59]
	v_mad_i64_i32 v[44:45], s[8:9], v46, s49, v[44:45]
	s_add_i32 s8, s28, s30
	v_bfe_u32 v190, v96, 5, 1
	v_add_u32_e32 v70, s8, v189
	v_and_b32_e32 v59, 48, v176
	v_lshlrev_b32_e32 v176, 4, v190
	v_cmp_gt_i32_e32 vcc, s47, v70
	v_lshl_add_u64 v[68:69], v[44:45], 0, v[176:177]
	global_load_dwordx4 v[44:47], v[68:69], off offset:128
	global_load_dwordx4 v[64:67], v[68:69], off offset:160
	v_cndmask_b32_e32 v71, v185, v188, vcc
	v_and_b32_e32 v70, v71, v70
	v_lshlrev_b32_e32 v70, 6, v70
	v_mov_b32_e32 v71, v177
	v_lshl_add_u64 v[72:73], s[16:17], 0, v[70:71]
	v_and_b32_e32 v74, 32, v96
	v_mov_b32_e32 v75, v177
	v_lshl_add_u64 v[72:73], v[72:73], 0, v[74:75]
	v_lshl_add_u64 v[70:71], s[18:19], 0, v[70:71]
	v_lshl_add_u64 v[70:71], v[70:71], 0, v[74:75]
	global_load_dwordx2 v[74:75], v[72:73], off
	global_load_dwordx2 v[76:77], v[70:71], off
	global_load_dwordx4 v[156:159], v[68:69], off
	global_load_dwordx4 v[152:155], v[68:69], off offset:32
	global_load_dwordx4 v[148:151], v[68:69], off offset:64
	global_load_dwordx4 v[136:139], v[68:69], off offset:96
	v_lshrrev_b32_e32 v41, 5, v41
	v_lshlrev_b32_e32 v43, 8, v43
	v_lshl_or_b32 v42, v42, 4, v184
	s_and_b64 vcc, exec, s[6:7]
	s_waitcnt vmcnt(7)
	v_lshlrev_b32_e32 v68, 16, v44
	s_waitcnt vmcnt(6)
	v_lshlrev_b32_e32 v69, 16, v64
	v_and_b32_e32 v79, 0xffff0000, v64
	v_and_b32_e32 v78, 0xffff0000, v44
	s_waitcnt vmcnt(5)
	v_mov_b32_e32 v82, v74
	s_waitcnt vmcnt(4)
	v_mov_b32_e32 v83, v76
	v_mov_b32_e32 v84, v76
	v_mov_b32_e32 v85, v74
	v_mov_b32_e32 v76, v75
	v_mov_b32_e32 v74, v77
	v_pk_mul_f32 v[82:83], v[82:83], v[68:69]
	v_pk_mul_f32 v[68:69], v[84:85], v[68:69]
	v_pk_mul_f32 v[76:77], v[76:77], v[78:79]
	v_pk_mul_f32 v[74:75], v[74:75], v[78:79]
	v_add_f32_e32 v64, v68, v69
	v_sub_f32_e32 v68, v76, v77
	v_add_f32_e32 v69, v74, v75
	v_sub_f32_e32 v44, v82, v83
	v_cvt_pk_bf16_f32 v140, v44, v68
	v_cvt_pk_bf16_f32 v128, v64, v69
	global_load_dwordx2 v[68:69], v[70:71], off offset:8
	global_load_dwordx2 v[74:75], v[72:73], off offset:8
	v_lshlrev_b32_e32 v77, 16, v45
	v_lshlrev_b32_e32 v76, 16, v65
	v_and_b32_e32 v45, 0xffff0000, v45
	v_and_b32_e32 v44, 0xffff0000, v65
	s_waitcnt vmcnt(1)
	v_mov_b32_e32 v64, v68
	s_waitcnt vmcnt(0)
	v_mov_b32_e32 v65, v74
	v_mov_b32_e32 v78, v74
	v_mov_b32_e32 v79, v68
	v_mov_b32_e32 v74, v69
	v_mov_b32_e32 v68, v75
	v_pk_mul_f32 v[64:65], v[64:65], v[76:77]
	v_pk_mul_f32 v[76:77], v[78:79], v[76:77]
	v_pk_mul_f32 v[74:75], v[74:75], v[44:45]
	v_pk_mul_f32 v[44:45], v[68:69], v[44:45]
	v_sub_f32_e32 v64, v65, v64
	v_add_f32_e32 v65, v76, v77
	v_add_f32_e32 v44, v44, v45
	v_sub_f32_e32 v68, v75, v74
	v_cvt_pk_bf16_f32 v141, v64, v68
	v_cvt_pk_bf16_f32 v129, v65, v44
	global_load_dwordx2 v[44:45], v[70:71], off offset:16
	global_load_dwordx2 v[64:65], v[72:73], off offset:16
	v_and_b32_e32 v75, 0xffff0000, v46
	v_and_b32_e32 v74, 0xffff0000, v66
	v_lshlrev_b32_e32 v69, 16, v46
	v_lshlrev_b32_e32 v68, 16, v66
	s_waitcnt vmcnt(1)
	v_mov_b32_e32 v76, v44
	s_waitcnt vmcnt(0)
	v_mov_b32_e32 v77, v64
	v_mov_b32_e32 v78, v64
	v_mov_b32_e32 v79, v44
	v_mov_b32_e32 v64, v45
	v_mov_b32_e32 v44, v65
	v_pk_mul_f32 v[64:65], v[64:65], v[74:75]
	v_pk_mul_f32 v[44:45], v[44:45], v[74:75]
	v_pk_mul_f32 v[76:77], v[76:77], v[68:69]
	v_pk_mul_f32 v[68:69], v[78:79], v[68:69]
	v_sub_f32_e32 v64, v65, v64
	v_add_f32_e32 v44, v44, v45
	v_sub_f32_e32 v46, v77, v76
	v_add_f32_e32 v66, v68, v69
	v_cvt_pk_bf16_f32 v142, v46, v64
	v_cvt_pk_bf16_f32 v130, v66, v44
	global_load_dwordx2 v[44:45], v[70:71], off offset:24
	global_load_dwordx2 v[64:65], v[72:73], off offset:24
	v_xor_b32_e32 v68, v40, v96
	v_and_b32_e32 v69, 0xfffff0, v40
	v_lshlrev_b32_e32 v70, 1, v40
	v_lshlrev_b32_e32 v66, 8, v40
	v_lshrrev_b32_e32 v71, 1, v40
	v_and_b32_e32 v40, 3, v40
	v_lshlrev_b32_e32 v68, 4, v68
	v_and_or_b32 v69, v70, 8, v69
	v_lshrrev_b32_e32 v46, 2, v96
	v_and_or_b32 v40, v71, 4, v40
	v_and_or_b32 v194, v68, s70, v66
	v_lshrrev_b32_e32 v254, 4, v66
	v_and_b32_e32 v254, 0x80, v254
	v_or_b32_e32 v194, v194, v254
	v_lshrrev_b32_e32 v66, 1, v69
	v_lshlrev_b32_e32 v46, 4, v46
	v_lshl_or_b32 v40, v40, 6, v59
	v_or_b32_e32 v41, v66, v41
	v_and_b32_e32 v46, 0xf0, v46
	v_lshl_or_b32 v40, v41, 9, v40
	v_bitop3_b32 v195, v42, v43, v46 bitop3:0xde
	v_add_u32_e32 v196, 0, v40
	v_lshlrev_b32_e32 v41, 16, v47
	v_lshlrev_b32_e32 v40, 16, v67
	v_and_b32_e32 v43, 0xffff0000, v47
	v_and_b32_e32 v42, 0xffff0000, v67
	v_add_u32_e32 v82, 0, v194
	v_add_u32_e32 v59, 0, v195
	s_waitcnt vmcnt(1)
	v_mov_b32_e32 v46, v44
	s_waitcnt vmcnt(0)
	v_mov_b32_e32 v47, v64
	v_mov_b32_e32 v66, v64
	v_mov_b32_e32 v67, v44
	v_mov_b32_e32 v64, v45
	v_mov_b32_e32 v44, v65
	v_pk_mul_f32 v[46:47], v[46:47], v[40:41]
	v_pk_mul_f32 v[40:41], v[66:67], v[40:41]
	v_pk_mul_f32 v[64:65], v[64:65], v[42:43]
	v_pk_mul_f32 v[42:43], v[44:45], v[42:43]
	v_sub_f32_e32 v44, v47, v46
	v_add_f32_e32 v40, v40, v41
	v_sub_f32_e32 v41, v65, v64
	v_add_f32_e32 v42, v42, v43
	v_cvt_pk_bf16_f32 v143, v44, v41
	v_cvt_pk_bf16_f32 v131, v40, v42
	s_waitcnt vmcnt(0)
	ds_write_b128 v196, v[36:39]
	ds_write_b128 v82, v[32:35] offset:49152
	s_cbranch_vccnz .LBB0_715
	ds_write_b128 v59, v[132:135] offset:49152
; template <bool FIRST> __device__ __forceinline__ void partialSM(f32x16& p0, f32x16& p1, float& m_ref, f32x16& negm, float& alpha) {
;   constexpr float THR2 = THR * 1.4426950408889634f;
;   float pmax = p0[0];
; #pragma unroll
;   for (int r = 1; r < 16; ++r) pmax = fmaxf(pmax, p0[r]);
; #pragma unroll
;   for (int r = 0; r < 16; ++r) pmax = fmaxf(pmax, p1[r]);
;   { auto rr = __builtin_amdgcn_permlane32_swap(__float_as_uint(pmax), __float_as_uint(pmax), false, false);
;     pmax = fmaxf(__uint_as_float(rr[0]), __uint_as_float(rr[1])); }
;   alpha = 1.f;
;   if (FIRST || !__builtin_expect(__all(pmax <= THR2), 1)) {
;     const float dl = FIRST ? pmax : fmaxf(pmax, 0.f);
;     m_ref += dl; alpha = FIRST ? 1.f : __builtin_amdgcn_exp2f(-dl);
; #pragma unroll
;     for (int r = 0; r < 16; ++r) { p0[r] -= dl; p1[r] -= dl; }
; #pragma unroll
;     for (int r = 0; r < 16; ++r) negm[r] = -m_ref;
;     asm volatile("" : "+v"(negm));
; __device__ __forceinline__ void qkt(f32x16& p0, f32x16& p1, const bf16_t* Ks, const bf16x8* qr, const f32x16& negm, int r32, int hi) {
; #pragma unroll
;   for (int d0 = 0; d0 < 6; ++d0) { int cb = (d0 * 16 + hi * 8) * 2;
;     bf16x8 b0 = *reinterpret_cast<const bf16x8*>((const char*)Ks + KSWZ(r32, cb));
;     bf16x8 b1 = *reinterpret_cast<const bf16x8*>((const char*)Ks + KSWZ(32 + r32, cb));
;     if (d0 == 0) { p0 = __builtin_amdgcn_mfma_f32_32x32x16_bf16(b0, qr[0], negm, 0, 0, 0); p1 = __builtin_amdgcn_mfma_f32_32x32x16_bf16(b1, qr[0], negm, 0, 0, 0); }
;     else { p0 = __builtin_amdgcn_mfma_f32_32x32x16_bf16(b0, qr[d0], p0, 0, 0, 0); p1 = __builtin_amdgcn_mfma_f32_32x32x16_bf16(b1, qr[d0], p1, 0, 0, 0); } }
.LBB0_715:
	v_lshlrev_b32_e32 v32, 4, v189
	v_lshlrev_b32_e32 v68, 8, v189
	v_and_b32_e32 v69, 0xf0, v32
	v_bitop3_b32 v197, v176, v68, v69 bitop3:0xde
	v_add_u32_e32 v70, 0, v197
	s_waitcnt lgkmcnt(0)
	s_barrier
	ds_read_b128 v[64:67], v70 offset:49152
	v_or_b32_e32 v71, 0xa0, v176
	v_bitop3_b32 v202, v71, v68, v69 bitop3:0xde
	v_add_co_u32_e32 v62, vcc, 0x20000, v62
	s_waitcnt lgkmcnt(0)
	v_mfma_f32_32x32x16_bf16 v[32:47], v[64:67], v[156:159], v[16:31]
	ds_read_b128 v[64:67], v70 offset:57344
	v_or_b32_e32 v70, 32, v176
	v_bitop3_b32 v198, v70, v68, v69 bitop3:0xde
	v_add_u32_e32 v70, 0, v198
	v_addc_co_u32_e32 v63, vcc, 0, v63, vcc
	v_add_co_u32_e32 v60, vcc, 0x20000, v60
	s_waitcnt lgkmcnt(0)
	v_mfma_f32_32x32x16_bf16 v[16:31], v[64:67], v[156:159], v[16:31]
	ds_read_b128 v[64:67], v70 offset:49152
	v_addc_co_u32_e32 v61, vcc, 0, v61, vcc
	s_and_b64 vcc, exec, s[6:7]
	s_waitcnt lgkmcnt(0)
	v_mfma_f32_32x32x16_bf16 v[32:47], v[64:67], v[152:155], v[32:47]
	ds_read_b128 v[64:67], v70 offset:57344
	v_or_b32_e32 v70, 64, v176
	v_bitop3_b32 v199, v70, v68, v69 bitop3:0xde
	v_add_u32_e32 v70, 0, v199
	s_waitcnt lgkmcnt(0)
	v_mfma_f32_32x32x16_bf16 v[16:31], v[64:67], v[152:155], v[16:31]
	ds_read_b128 v[64:67], v70 offset:49152
	s_waitcnt lgkmcnt(0)
	v_mfma_f32_32x32x16_bf16 v[32:47], v[64:67], v[148:151], v[32:47]
	ds_read_b128 v[64:67], v70 offset:57344
	v_or_b32_e32 v70, 0x60, v176
	v_bitop3_b32 v200, v70, v68, v69 bitop3:0xde
	v_add_u32_e32 v70, 0, v200
	s_waitcnt lgkmcnt(0)
	v_mfma_f32_32x32x16_bf16 v[16:31], v[64:67], v[148:151], v[16:31]
	ds_read_b128 v[64:67], v70 offset:49152
	s_waitcnt lgkmcnt(0)
	v_mfma_f32_32x32x16_bf16 v[32:47], v[64:67], v[136:139], v[32:47]
	ds_read_b128 v[64:67], v70 offset:57344
	v_or_b32_e32 v70, 0x80, v176
	v_bitop3_b32 v201, v70, v68, v69 bitop3:0xde
	v_add_u32_e32 v70, 0, v201
	v_add_u32_e32 v68, 0, v202
	s_waitcnt lgkmcnt(0)
	v_mfma_f32_32x32x16_bf16 v[16:31], v[64:67], v[136:139], v[16:31]
	ds_read_b128 v[64:67], v70 offset:49152
	s_waitcnt lgkmcnt(0)
	v_mfma_f32_32x32x16_bf16 v[32:47], v[64:67], v[140:143], v[32:47]
	ds_read_b128 v[64:67], v68 offset:49152
	s_waitcnt lgkmcnt(0)
	v_mfma_f32_32x32x16_bf16 v[32:47], v[64:67], v[128:131], v[32:47]
	ds_read_b128 v[64:67], v70 offset:57344
	ds_read_b128 v[68:71], v68 offset:57344
	s_waitcnt lgkmcnt(1)
	v_mfma_f32_32x32x16_bf16 v[16:31], v[64:67], v[140:143], v[16:31]
	s_nop 7
	v_max_f32_e32 v72, v33, v33
	v_max_f32_e32 v73, v32, v32
	v_max_f32_e32 v72, v73, v72
	v_max3_f32 v64, v72, v34, v35
	v_max3_f32 v64, v64, v36, v37
	v_max3_f32 v64, v64, v38, v39
	v_max3_f32 v64, v64, v40, v41
	s_waitcnt lgkmcnt(0)
	v_mfma_f32_32x32x16_bf16 v[16:31], v[68:71], v[128:131], v[16:31]
	v_max3_f32 v64, v64, v42, v43
	v_max3_f32 v64, v64, v44, v45
	v_max3_f32 v64, v64, v46, v47
	s_nop 8
	v_max3_f32 v64, v64, v16, v17
	v_max3_f32 v64, v64, v18, v19
	v_max3_f32 v64, v64, v20, v21
	v_max3_f32 v64, v64, v22, v23
	v_max3_f32 v64, v64, v24, v25
	v_max3_f32 v64, v64, v26, v27
	v_max3_f32 v64, v64, v28, v29
	v_max3_f32 v64, v64, v30, v31
	v_mov_b32_e32 v65, v64
	s_nop 1
	v_permlane32_swap_b32_e32 v64, v65
	v_max_f32_e32 v65, v65, v65
	v_max_f32_e32 v64, v64, v64
	v_max_f32_e32 v97, v64, v65
	v_add_f32_e32 v191, 0, v97
	v_xor_b32_e32 v64, 0x80000000, v191
	v_mov_b32_e32 v65, v64
	v_mov_b32_e32 v66, v64
	v_mov_b32_e32 v67, v64
	v_mov_b32_e32 v68, v64
	v_mov_b32_e32 v69, v64
	v_mov_b32_e32 v70, v64
	v_mov_b32_e32 v71, v64
	v_mov_b32_e32 v72, v64
	v_mov_b32_e32 v73, v64
	v_mov_b32_e32 v74, v64
	v_mov_b32_e32 v75, v64
	v_mov_b32_e32 v76, v64
	v_mov_b32_e32 v77, v64
	v_mov_b32_e32 v78, v64
	v_mov_b32_e32 v79, v64
	global_load_dwordx4 v[160:163], v[62:63], off
	global_load_dwordx4 v[164:167], v[60:61], off
	s_cbranch_vccnz .LBB0_753
	v_add_co_u32_e32 v60, vcc, 0x2000, v80
	s_nop 1
	v_addc_co_u32_e32 v61, vcc, 0, v81, vcc
	global_load_dwordx4 v[132:135], v[60:61], off
	s_mov_b64 s[8:9], -1
	s_and_b64 vcc, exec, s[34:35]
	s_cbranch_vccnz .LBB0_754

; #define SBAR() __builtin_amdgcn_sched_barrier(0)
; #define SLOAD(i, k0) do { sr_[i].v = *reinterpret_cast<const bf16x8*>(vp + (long)(k0) * LDV); sr_[i].k = *reinterpret_cast<const bf16x8*>(kp + (long)(k0) * LDKN); \
;     if (has_r) sr_[i].r = *reinterpret_cast<const bf16x8*>(rp + (long)(k0) * LDKR); } while (0)
; template <bool FIRST> __device__ __forceinline__ void partialSM(f32x16& p0, f32x16& p1, float& m_ref, f32x16& negm, float& alpha) {
;     ...
;   if (FIRST || !__builtin_expect(__all(pmax <= THR2), 1)) {
;     const float dl = FIRST ? pmax : fmaxf(pmax, 0.f);
;     m_ref += dl; alpha = FIRST ? 1.f : __builtin_amdgcn_exp2f(-dl);
; #pragma unroll
;     for (int r = 0; r < 16; ++r) { p0[r] -= dl; p1[r] -= dl; }
; #pragma unroll
;     for (int r = 0; r < 16; ++r) negm[r] = -m_ref;
;     asm volatile("" : "+v"(negm));
;   }
; #pragma unroll
;   for (int r = 0; r < 16; ++r) p0[r] = __builtin_amdgcn_exp2f(p0[r]);
; __device__ __forceinline__ void attn_unit(const bf16_t* __restrict__ Qb, const bf16_t* __restrict__ KNh, const bf16_t* __restrict__ KRb, const bf16_t* __restrict__ Vh, ...
;     ...
;   for (int j = 1; j + 1 < NT; j += 2) {
;     SBAR(); qkt(pB0, pB1, (bf16_t*)((char*)K_lds + o_cur), qr, negm, r32, hi);
;     finishSM(pA0, pA1, pa0, pa1, pa2, pa3); SBAR();
;     SLOAD(SO, (j + 2) * KVBLK); SBAR();
.LBB0_721:
	s_and_b32 s8, s37, 0x3fffffc0
	v_and_b32_e32 v48, 63, v96
	s_lshl_b32 s8, s8, 2
	v_sub_f32_e32 v81, v17, v97
	s_add_i32 s29, s8, 0
	v_lshlrev_b32_e32 v17, 4, v48
	s_lshl_b32 s10, s36, 6
	s_ashr_i32 s31, s30, 31
	v_sub_f32_e32 v82, v18, v97
	v_sub_f32_e32 v80, v16, v97
	s_add_i32 s29, s29, 0x18000
	v_lshlrev_b32_e32 v16, 3, v48
	v_and_b32_e32 v17, 0xc0, v17
	v_lshlrev_b32_e32 v18, 1, v48
	v_and_or_b32 v17, v16, 24, v17
	v_and_b32_e32 v18, 32, v18
	v_and_b32_e32 v16, 0x100, v16
	s_cmp_lg_u32 0, -1
	v_or3_b32 v16, v17, v18, v16
	s_cselect_b32 s8, 0, 0
	s_mov_b32 s37, s11
	v_add_u32_e32 v203, s8, v16
	v_lshlrev_b32_e32 v16, 4, v96
	s_lshl_b64 s[36:37], s[36:37], 7
	v_sub_f32_e32 v32, v32, v97
	v_sub_f32_e32 v33, v33, v97
	v_sub_f32_e32 v34, v34, v97
	v_sub_f32_e32 v35, v35, v97
	v_sub_f32_e32 v36, v36, v97
	v_sub_f32_e32 v37, v37, v97
	v_sub_f32_e32 v38, v38, v97
	v_sub_f32_e32 v39, v39, v97
	v_sub_f32_e32 v40, v40, v97
	v_sub_f32_e32 v41, v41, v97
	v_sub_f32_e32 v42, v42, v97
	v_sub_f32_e32 v43, v43, v97
	v_sub_f32_e32 v44, v44, v97
	v_sub_f32_e32 v45, v45, v97
	v_sub_f32_e32 v46, v46, v97
	v_sub_f32_e32 v47, v47, v97
	v_and_b32_e32 v16, 0xfc0, v16
	v_mov_b32_e32 v17, v177
	s_add_u32 s36, s36, s38
	v_exp_f32_e32 v0, v32
	v_exp_f32_e32 v1, v33
	v_exp_f32_e32 v2, v34
	v_exp_f32_e32 v3, v35
	v_exp_f32_e32 v4, v36
	v_exp_f32_e32 v5, v37
	v_exp_f32_e32 v6, v38
	v_exp_f32_e32 v7, v39
	v_exp_f32_e32 v8, v40
	v_exp_f32_e32 v9, v41
	v_exp_f32_e32 v10, v42
	v_exp_f32_e32 v11, v43
	v_exp_f32_e32 v12, v44
	v_exp_f32_e32 v13, v45
	v_exp_f32_e32 v14, v46
	v_exp_f32_e32 v15, v47
	v_lshl_add_u64 v[16:17], s[40:41], 0, v[16:17]
	v_mov_b32_e32 v59, v177
	s_addc_u32 s37, s37, s39
	v_sub_f32_e32 v95, v31, v97
	v_sub_f32_e32 v94, v30, v97
	v_lshl_add_u64 v[178:179], v[16:17], 0, v[58:59]
	v_lshl_add_u64 v[180:181], s[36:37], 0, v[56:57]
	v_and_b32_e32 v16, 7, v96
	v_mov_b32_e32 v30, v177
	v_mov_b32_e32 v31, v177
	v_sub_f32_e32 v93, v29, v97
	v_sub_f32_e32 v92, v28, v97
	v_sub_f32_e32 v91, v27, v97
	v_sub_f32_e32 v90, v26, v97
	v_sub_f32_e32 v89, v25, v97
	v_sub_f32_e32 v88, v24, v97
	v_sub_f32_e32 v87, v23, v97
	v_sub_f32_e32 v86, v22, v97
	v_sub_f32_e32 v85, v21, v97
	v_sub_f32_e32 v84, v20, v97
	v_sub_f32_e32 v83, v19, v97
	v_cmp_gt_u32_e64 s[8:9], 32, v48
	v_lshl_or_b32 v180, v16, 4, v180
	v_mov_b32_e32 v16, v177
	v_mov_b32_e32 v17, v177
	v_mov_b32_e32 v18, v177
	v_mov_b32_e32 v19, v177
	v_mov_b32_e32 v20, v177
	v_mov_b32_e32 v21, v177
	v_mov_b32_e32 v22, v177
	v_mov_b32_e32 v23, v177
	v_mov_b32_e32 v24, v177
	v_mov_b32_e32 v25, v177
	v_mov_b32_e32 v26, v177
	v_mov_b32_e32 v27, v177
	v_mov_b32_e32 v28, v177
	v_mov_b32_e32 v29, v177
	v_mov_b64_e32 v[46:47], v[30:31]
	v_mov_b64_e32 v[62:63], v[30:31]
	s_mov_b32 s67, 4
	s_mov_b32 s77, 0
	v_lshl_add_u32 v192, v189, 2, s29
	s_movk_i32 s41, 0x4000
	s_mov_b32 s36, 0x8000
	v_mov_b64_e32 v[44:45], v[28:29]
	v_mov_b64_e32 v[42:43], v[26:27]
	v_mov_b64_e32 v[40:41], v[24:25]
	v_mov_b64_e32 v[38:39], v[22:23]
	v_mov_b64_e32 v[36:37], v[20:21]
	v_mov_b64_e32 v[34:35], v[18:19]
	v_mov_b64_e32 v[32:33], v[16:17]
	v_mov_b64_e32 v[60:61], v[28:29]
	v_mov_b64_e32 v[58:59], v[26:27]
	v_mov_b64_e32 v[56:57], v[24:25]
	v_mov_b64_e32 v[54:55], v[22:23]
	v_mov_b64_e32 v[52:53], v[20:21]
	v_mov_b64_e32 v[50:51], v[18:19]
	v_mov_b64_e32 v[48:49], v[16:17]
	s_waitcnt lgkmcnt(0)
	s_barrier
.LBB0_722:
	s_mov_b32 s40, s36
	s_add_i32 s36, s41, 0
	v_add_u32_e32 v100, s36, v197
	ds_read_b128 v[96:99], v100 offset:49152
	ds_read_b128 v[210:213], v100 offset:57344
	v_add_u32_e32 v193, s36, v198
	v_lshl_add_u64 v[182:183], s[52:53], 0, v[180:181]
	v_add_co_u32_e32 v168, vcc, 0xf030000, v182
	s_nop 1
	v_addc_co_u32_e32 v169, vcc, 0, v183, vcc
	v_add_co_u32_e32 v170, vcc, 0x9030000, v182
	s_nop 1
	v_addc_co_u32_e32 v171, vcc, 0, v183, vcc
	global_load_dwordx4 v[172:175], v[168:169], off
	s_nop 0
	global_load_dwordx4 v[168:171], v[170:171], off
	s_and_b64 vcc, exec, s[6:7]
	s_cbranch_vccnz .Lattn_h1_norope
	v_lshl_add_u64 v[144:145], s[52:53], 0, v[178:179]
	v_add_co_u32_e32 v144, vcc, 0x15003000, v144
	s_nop 1
	v_addc_co_u32_e32 v145, vcc, 0, v145, vcc
	global_load_dwordx4 v[144:147], v[144:145], off
; #define SBAR() __builtin_amdgcn_sched_barrier(0)
; #define SLOAD(i, k0) do { sr_[i].v = *reinterpret_cast<const bf16x8*>(vp + (long)(k0) * LDV); sr_[i].k = *reinterpret_cast<const bf16x8*>(kp + (long)(k0) * LDKN); \
;     if (has_r) sr_[i].r = *reinterpret_cast<const bf16x8*>(rp + (long)(k0) * LDKR); } while (0)
; template <int D0> __device__ __forceinline__ void pv_one(f32x16& od, int vb, bf16x8 pa0, bf16x8 pa1, bf16x8 pa2, bf16x8 pa3) {
;   const s16x4 l0 = tr_read<v_rd_off(D0, 0, 0)>(vb), h0 = tr_read<v_rd_off(D0, 0, 1)>(vb), l1 = tr_read<v_rd_off(D0, 1, 0)>(vb), h1 = tr_read<v_rd_off(D0, 1, 1)>(vb);
;   const s16x4 l2 = tr_read<v_rd_off(D0, 2, 0)>(vb), h2 = tr_read<v_rd_off(D0, 2, 1)>(vb), l3 = tr_read<v_rd_off(D0, 3, 0)>(vb), h3 = tr_read<v_rd_off(D0, 3, 1)>(vb);
;   asm volatile("s_waitcnt lgkmcnt(0)" ::: "memory"); SBAR();
;     ...
;   od = __builtin_amdgcn_mfma_f32_32x32x16_bf16(pa0, PK(l0, h0), od, 0, 0, 0);
;   od = __builtin_amdgcn_mfma_f32_32x32x16_bf16(pa1, PK(l1, h1), od, 0, 0, 0);
;   od = __builtin_amdgcn_mfma_f32_32x32x16_bf16(pa2, PK(l2, h2), od, 0, 0, 0);
;   od = __builtin_amdgcn_mfma_f32_32x32x16_bf16(pa3, PK(l3, h3), od, 0, 0, 0);
;     ...
; }
; __device__ __forceinline__ void pv_d0(f32x16* o, f32x16& osum, int vb, bf16x8 pa0, bf16x8 pa1, bf16x8 pa2, bf16x8 pa3) {
;   pv_one<0>(o[0], vb, pa0, pa1, pa2, pa3); pv_one<1>(o[1], vb, pa0, pa1, pa2, pa3);
;   const short one = (short)0x3F80; const bf16x8 ones = {one, one, one, one, one, one, one, one};
;   osum = __builtin_amdgcn_mfma_f32_32x32x16_bf16(pa0, ones, osum, 0, 0, 0); osum = __builtin_amdgcn_mfma_f32_32x32x16_bf16(pa1, ones, osum, 0, 0, 0);
;   osum = __builtin_amdgcn_mfma_f32_32x32x16_bf16(pa2, ones, osum, 0, 0, 0); osum = __builtin_amdgcn_mfma_f32_32x32x16_bf16(pa3, ones, osum, 0, 0, 0);
; __device__ __forceinline__ void attn_unit(const bf16_t* __restrict__ Qb, const bf16_t* __restrict__ KNh, const bf16_t* __restrict__ KRb, const bf16_t* __restrict__ Vh, ...
;     ...
;     SBAR(); qkt(pB0, pB1, (bf16_t*)((char*)K_lds + o_cur), qr, negm, r32, hi);
;     finishSM(pA0, pA1, pa0, pa1, pa2, pa3); SBAR();
;     SLOAD(SO, (j + 2) * KVBLK); SBAR();
;     pv_d0(o, osum, vb0 + o_prev, pa0, pa1, pa2, pa3); partialSM<false>(pB0, pB1, m_ref, negm, alB);
.Lattn_h1_norope:
	v_exp_f32_e32 v87, v87
	v_exp_f32_e32 v88, v88
	v_exp_f32_e32 v89, v89
	v_exp_f32_e32 v90, v90
	v_exp_f32_e32 v91, v91
	v_exp_f32_e32 v238, v81
	s_waitcnt lgkmcnt(1)
	v_mfma_f32_32x32x16_bf16 v[112:127], v[96:99], v[156:159], v[64:79]
	v_exp_f32_e32 v239, v82
	v_exp_f32_e32 v240, v83
	v_exp_f32_e32 v241, v84
	s_waitcnt lgkmcnt(0)
	v_mfma_f32_32x32x16_bf16 v[96:111], v[210:213], v[156:159], v[64:79]
	ds_read_b128 v[210:213], v193 offset:49152
	s_waitcnt lgkmcnt(0)
	v_mfma_f32_32x32x16_bf16 v[112:127], v[210:213], v[152:155], v[112:127]
	ds_read_b128 v[210:213], v193 offset:57344
	v_add_u32_e32 v193, s36, v199
	ds_read_b128 v[214:217], v193 offset:57344
	ds_read_b128 v[218:221], v193 offset:49152
	v_add_u32_e32 v193, s36, v200
	s_waitcnt lgkmcnt(2)
	v_mfma_f32_32x32x16_bf16 v[96:111], v[210:213], v[152:155], v[96:111]
	ds_read_b128 v[210:213], v193 offset:57344
	ds_read_b128 v[222:225], v193 offset:49152
	v_add_u32_e32 v193, s36, v201
	ds_read_b128 v[226:229], v193 offset:57344
	ds_read_b128 v[230:233], v193 offset:49152
	v_add_u32_e32 v193, s36, v202
	s_waitcnt lgkmcnt(4)
	v_mfma_f32_32x32x16_bf16 v[112:127], v[218:221], v[148:151], v[112:127]
	ds_read_b128 v[218:221], v193 offset:57344
	ds_read_b128 v[234:237], v193 offset:49152
	v_exp_f32_e32 v193, v80
	v_mfma_f32_32x32x16_bf16 v[96:111], v[214:217], v[148:151], v[96:111]
	v_exp_f32_e32 v214, v85
	v_exp_f32_e32 v215, v86
	v_exp_f32_e32 v216, v92
	v_exp_f32_e32 v217, v93
	v_cvt_pk_bf16_f32 v92, v0, v1
	v_cvt_pk_bf16_f32 v93, v2, v3
	s_waitcnt lgkmcnt(4)
	v_mfma_f32_32x32x16_bf16 v[112:127], v[222:225], v[136:139], v[112:127]
	v_exp_f32_e32 v222, v94
	v_exp_f32_e32 v223, v95
	v_cvt_pk_bf16_f32 v94, v4, v5
	v_cvt_pk_bf16_f32 v95, v6, v7
	v_cvt_pk_bf16_f32 v80, v8, v9
	v_cvt_pk_bf16_f32 v81, v10, v11
	v_cvt_pk_bf16_f32 v82, v12, v13
	v_mfma_f32_32x32x16_bf16 v[96:111], v[210:213], v[136:139], v[96:111]
	v_cvt_pk_bf16_f32 v83, v14, v15
	v_cvt_pk_bf16_f32 v84, v193, v238
	v_cvt_pk_bf16_f32 v85, v239, v240
	v_cvt_pk_bf16_f32 v86, v241, v214
	v_cvt_pk_bf16_f32 v87, v215, v87
	v_cvt_pk_bf16_f32 v88, v88, v89
	v_cvt_pk_bf16_f32 v89, v90, v91
	s_waitcnt lgkmcnt(2)
	v_mfma_f32_32x32x16_bf16 v[112:127], v[230:233], v[140:143], v[112:127]
	v_cvt_pk_bf16_f32 v90, v216, v217
	v_cvt_pk_bf16_f32 v91, v222, v223
	v_permlane32_swap_b32_e32 v92, v94
	v_permlane32_swap_b32_e32 v93, v95
	v_permlane32_swap_b32_e32 v80, v82
	v_mfma_f32_32x32x16_bf16 v[96:111], v[226:229], v[140:143], v[96:111]
	v_permlane32_swap_b32_e32 v81, v83
	v_permlane32_swap_b32_e32 v84, v86
	v_permlane32_swap_b32_e32 v85, v87
	v_permlane32_swap_b32_e32 v88, v90
	s_waitcnt lgkmcnt(0)
	v_mfma_f32_32x32x16_bf16 v[112:127], v[234:237], v[128:131], v[112:127]
	v_permlane32_swap_b32_e32 v89, v91
	v_mfma_f32_32x32x16_bf16 v[96:111], v[218:221], v[128:131], v[96:111]
.LBB0_724:
	v_add_u32_e32 v193, s77, v203
	ds_read_b64_tr_b16 v[204:205], v193 offset:0
	ds_read_b64_tr_b16 v[206:207], v193 offset:0x800
	ds_read_b64_tr_b16 v[208:209], v193 offset:0x1000
	ds_read_b64_tr_b16 v[210:211], v193 offset:0x1800
	ds_read_b64_tr_b16 v[212:213], v193 offset:0x2000
	ds_read_b64_tr_b16 v[214:215], v193 offset:0x2800
	ds_read_b64_tr_b16 v[216:217], v193 offset:0x3000
	ds_read_b64_tr_b16 v[218:219], v193 offset:0x3800
	s_waitcnt lgkmcnt(0)
	s_nop 0
	v_mfma_f32_32x32x16_bf16 v[16:31], v[92:95], v[204:207], v[16:31]
	ds_read_b64_tr_b16 v[204:205], v193 offset:0x200
	ds_read_b64_tr_b16 v[206:207], v193 offset:0xa00
	v_max_f32_e32 v254, v113, v113
	v_max_f32_e32 v255, v112, v112
	v_max_f32_e32 v254, v255, v254
	v_max3_f32 v254, v254, v114, v115
	v_max3_f32 v254, v254, v116, v117
	v_mfma_f32_32x32x16_bf16 v[16:31], v[80:83], v[208:211], v[16:31]
	ds_read_b64_tr_b16 v[208:209], v193 offset:0x1200
	ds_read_b64_tr_b16 v[210:211], v193 offset:0x1a00
	v_max3_f32 v254, v254, v118, v119
	v_max3_f32 v254, v254, v120, v121
	v_max3_f32 v254, v254, v122, v123
	v_max3_f32 v254, v254, v124, v125
	v_max3_f32 v254, v254, v126, v127
	v_mfma_f32_32x32x16_bf16 v[16:31], v[84:87], v[212:215], v[16:31]
	ds_read_b64_tr_b16 v[212:213], v193 offset:0x2200
	ds_read_b64_tr_b16 v[214:215], v193 offset:0x2a00
	ds_read_b64_tr_b16 v[220:221], v193 offset:0x3200
	ds_read_b64_tr_b16 v[222:223], v193 offset:0x3a00
	v_max3_f32 v254, v254, v96, v97
	v_max3_f32 v254, v254, v98, v99
	v_max3_f32 v254, v254, v100, v101
	v_max3_f32 v254, v254, v102, v103
	v_max3_f32 v254, v254, v104, v105
	s_waitcnt lgkmcnt(0)
	v_mfma_f32_32x32x16_bf16 v[16:31], v[88:91], v[216:219], v[16:31]
	v_max3_f32 v254, v254, v106, v107
	v_max3_f32 v254, v254, v108, v109
	v_max3_f32 v254, v254, v110, v111
	v_mov_b32_e32 v255, v254
	v_mfma_f32_32x32x16_bf16 v[32:47], v[92:95], v[204:207], v[32:47]
	v_mov_b64_e32 v[206:207], s[14:15]
	v_mov_b64_e32 v[204:205], s[12:13]
	v_permlane32_swap_b32_e32 v254, v255
	v_max_f32_e32 v255, v255, v255
	v_max_f32_e32 v254, v254, v254
	v_mfma_f32_32x32x16_bf16 v[48:63], v[92:95], v[204:207], v[48:63]
	v_max_f32_e32 v255, v254, v255
	v_cmp_ge_f32_e32 vcc, s71, v255
	s_cmp_eq_u64 vcc, exec
	v_mov_b32_e32 v254, 1.0
	s_cbranch_scc0 .Lattn_adj_h1
.Lattn_cont_h1:
	v_mfma_f32_32x32x16_bf16 v[32:47], v[80:83], v[208:211], v[32:47]
	v_exp_f32_e32 v232, v112
	v_exp_f32_e32 v233, v113
	v_exp_f32_e32 v234, v114
	v_mfma_f32_32x32x16_bf16 v[48:63], v[80:83], v[204:207], v[48:63]
	v_exp_f32_e32 v235, v115
	v_exp_f32_e32 v236, v116
	v_exp_f32_e32 v237, v117
	v_mfma_f32_32x32x16_bf16 v[32:47], v[84:87], v[212:215], v[32:47]
	v_exp_f32_e32 v238, v118
	v_exp_f32_e32 v239, v119
	v_exp_f32_e32 v240, v120
	v_mfma_f32_32x32x16_bf16 v[48:63], v[84:87], v[204:207], v[48:63]
	v_exp_f32_e32 v241, v121
	v_exp_f32_e32 v242, v122
	v_exp_f32_e32 v243, v123
	v_mfma_f32_32x32x16_bf16 v[32:47], v[88:91], v[220:223], v[32:47]
	v_exp_f32_e32 v244, v124
	v_exp_f32_e32 v245, v125
	v_mfma_f32_32x32x16_bf16 v[48:63], v[88:91], v[204:207], v[48:63]
	v_exp_f32_e32 v246, v126
	v_exp_f32_e32 v247, v127
	s_mov_b64 s[36:37], -1
	s_and_b64 vcc, exec, s[34:35]
	s_cbranch_vccz .LBB0_728
.LBB0_726:
	s_waitcnt vmcnt(2)
	s_cbranch_execz .LBB0_729
	s_branch .LBB0_730
.LBB0_728:
	s_andn2_b64 vcc, exec, s[36:37]
	s_cbranch_vccnz .LBB0_730

; #define SBAR() __builtin_amdgcn_sched_barrier(0)
; #define SLOAD(i, k0) do { sr_[i].v = *reinterpret_cast<const bf16x8*>(vp + (long)(k0) * LDV); sr_[i].k = *reinterpret_cast<const bf16x8*>(kp + (long)(k0) * LDKN); \
;     if (has_r) sr_[i].r = *reinterpret_cast<const bf16x8*>(rp + (long)(k0) * LDKR); } while (0)
; #define RESC(a) do { if (__any((a) < 1.f)) { if (hi == 0) al_l[r32] = (a); asm volatile("s_waitcnt lgkmcnt(0)" ::: "memory"); \
;     _Pragma("unroll") for (int r = 0; r < 16; ++r) { const float f_ = al_l[crow(r, hi)]; o[0][r] *= f_; o[1][r] *= f_; osum[r] *= f_; } } } while (0)
; #define ROT() do { const int t_ = o_prev; o_prev = o_cur; o_cur = o_next; o_next = t_; } while (0)
; __device__ __forceinline__ void attn_unit(const bf16_t* __restrict__ Qb, const bf16_t* __restrict__ KNh, const bf16_t* __restrict__ KRb, const bf16_t* __restrict__ Vh, ...
;     ...
;     RESC(alB); __syncthreads(); ROT();
;     SBAR(); qkt(pA0, pA1, (bf16_t*)((char*)K_lds + o_cur), qr, negm, r32, hi);
;     finishSM(pB0, pB1, pa0, pa1, pa2, pa3); SBAR();
;     if (j + 3 < NT) SLOAD(SE, (j + 3) * KVBLK); SBAR();
.LBB0_732:
	v_cmp_gt_f32_e32 vcc, 1.0, v254
	s_cbranch_vccz .LBB0_736
	s_and_saveexec_b64 s[36:37], s[8:9]
	ds_write_b32 v192, v254 offset:128
	s_or_b64 exec, exec, s[36:37]
	s_waitcnt lgkmcnt(0)
	v_add_u32_e32 v92, s29, v176
	ds_read_b128 v[80:83], v92 offset:224
	ds_read_b128 v[84:87], v92 offset:192
	ds_read_b128 v[88:91], v92 offset:160
	ds_read_b128 v[92:95], v92 offset:128
	s_waitcnt lgkmcnt(3)
	v_pk_mul_f32 v[28:29], v[28:29], v[80:81]
	s_waitcnt lgkmcnt(2)
	v_pk_mul_f32 v[24:25], v[24:25], v[84:85]
	s_waitcnt lgkmcnt(1)
	v_pk_mul_f32 v[20:21], v[20:21], v[88:89]
	v_pk_mul_f32 v[30:31], v[30:31], v[82:83]
	v_pk_mul_f32 v[26:27], v[26:27], v[86:87]
	v_pk_mul_f32 v[22:23], v[22:23], v[90:91]
	s_waitcnt lgkmcnt(0)
	v_pk_mul_f32 v[18:19], v[18:19], v[94:95]
	v_pk_mul_f32 v[16:17], v[16:17], v[92:93]
	v_pk_mul_f32 v[44:45], v[44:45], v[80:81]
	v_pk_mul_f32 v[40:41], v[40:41], v[84:85]
	v_pk_mul_f32 v[36:37], v[36:37], v[88:89]
	v_pk_mul_f32 v[46:47], v[46:47], v[82:83]
	v_pk_mul_f32 v[42:43], v[42:43], v[86:87]
	v_pk_mul_f32 v[38:39], v[38:39], v[90:91]
	v_pk_mul_f32 v[34:35], v[34:35], v[94:95]
	v_pk_mul_f32 v[32:33], v[32:33], v[92:93]
	v_pk_mul_f32 v[60:61], v[60:61], v[80:81]
	v_pk_mul_f32 v[56:57], v[56:57], v[84:85]
	v_pk_mul_f32 v[52:53], v[52:53], v[88:89]
	v_pk_mul_f32 v[62:63], v[62:63], v[82:83]
	v_pk_mul_f32 v[58:59], v[58:59], v[86:87]
	v_pk_mul_f32 v[54:55], v[54:55], v[90:91]
	v_pk_mul_f32 v[50:51], v[50:51], v[94:95]
	v_pk_mul_f32 v[48:49], v[48:49], v[92:93]
.LBB0_736:
	s_waitcnt lgkmcnt(0)
	s_barrier
	v_add_u32_e32 v84, s38, v197
	ds_read_b128 v[80:83], v84 offset:49152
	ds_read_b128 v[204:207], v84 offset:57344
	v_add_u32_e32 v208, s38, v198
	v_add_u32_e32 v212, s38, v199
	v_add_u32_e32 v216, s38, v200
	v_add_u32_e32 v224, s38, v201
	v_add_u32_e32 v228, s38, v202
	s_cmp_ge_u32 s67, s66
	s_cselect_b64 s[36:37], -1, 0
	s_and_b64 vcc, exec, s[36:37]
	s_cbranch_vccnz .Lattn_h2_noload
	v_add_co_u32_e32 v160, vcc, 0xf040000, v182
	s_nop 1
	v_addc_co_u32_e32 v161, vcc, 0, v183, vcc
	v_add_co_u32_e32 v164, vcc, 0x9040000, v182
	s_nop 1
	v_addc_co_u32_e32 v165, vcc, 0, v183, vcc
	global_load_dwordx4 v[160:163], v[160:161], off
	s_nop 0
	global_load_dwordx4 v[164:167], v[164:165], off
	s_and_b64 vcc, exec, s[6:7]
	s_cbranch_vccnz .Lattn_h2_noload
	v_lshl_add_u64 v[132:133], s[52:53], 0, v[178:179]
	v_add_co_u32_e32 v132, vcc, 0x15004000, v132
	s_nop 1
	v_addc_co_u32_e32 v133, vcc, 0, v133, vcc
	global_load_dwordx4 v[132:135], v[132:133], off
.Lattn_h2_noload:
	v_exp_f32_e32 v103, v103
	v_exp_f32_e32 v104, v104
	s_waitcnt lgkmcnt(1)
	v_mfma_f32_32x32x16_bf16 v[112:127], v[80:83], v[156:159], v[64:79]
	v_exp_f32_e32 v105, v105
	v_exp_f32_e32 v106, v106
	v_exp_f32_e32 v107, v107
	v_exp_f32_e32 v248, v96
	v_exp_f32_e32 v249, v97
	v_exp_f32_e32 v250, v98
	v_exp_f32_e32 v251, v99
	s_waitcnt lgkmcnt(0)
	v_mfma_f32_32x32x16_bf16 v[80:95], v[204:207], v[156:159], v[64:79]
	ds_read_b128 v[204:207], v208 offset:49152
	v_exp_f32_e32 v252, v100
	s_waitcnt lgkmcnt(0)
	v_mfma_f32_32x32x16_bf16 v[112:127], v[204:207], v[152:155], v[112:127]
	ds_read_b128 v[204:207], v208 offset:57344
	ds_read_b128 v[208:211], v212 offset:57344
	ds_read_b128 v[212:215], v212 offset:49152
	s_waitcnt lgkmcnt(2)
	v_mfma_f32_32x32x16_bf16 v[80:95], v[204:207], v[152:155], v[80:95]
	ds_read_b128 v[204:207], v216 offset:57344
	ds_read_b128 v[216:219], v216 offset:49152
	ds_read_b128 v[220:223], v224 offset:57344
	ds_read_b128 v[224:227], v224 offset:49152
	s_waitcnt lgkmcnt(4)
	v_mfma_f32_32x32x16_bf16 v[112:127], v[212:215], v[148:151], v[112:127]
	ds_read_b128 v[212:215], v228 offset:57344
	ds_read_b128 v[228:231], v228 offset:49152
	v_mfma_f32_32x32x16_bf16 v[80:95], v[208:211], v[148:151], v[80:95]
	v_exp_f32_e32 v208, v101
	v_exp_f32_e32 v209, v102
	v_exp_f32_e32 v210, v108
	v_exp_f32_e32 v211, v109
	v_cvt_pk_bf16_f32 v108, v232, v233
	v_cvt_pk_bf16_f32 v109, v234, v235
	s_waitcnt lgkmcnt(4)
	v_mfma_f32_32x32x16_bf16 v[112:127], v[216:219], v[136:139], v[112:127]
	v_exp_f32_e32 v216, v110
	v_exp_f32_e32 v217, v111
	v_cvt_pk_bf16_f32 v110, v236, v237
	v_cvt_pk_bf16_f32 v111, v238, v239
	v_cvt_pk_bf16_f32 v96, v240, v241
	v_cvt_pk_bf16_f32 v97, v242, v243
	v_cvt_pk_bf16_f32 v98, v244, v245
	v_mfma_f32_32x32x16_bf16 v[80:95], v[204:207], v[136:139], v[80:95]
	v_cvt_pk_bf16_f32 v99, v246, v247
	v_cvt_pk_bf16_f32 v100, v248, v249
	v_cvt_pk_bf16_f32 v101, v250, v251
	v_cvt_pk_bf16_f32 v102, v252, v208
	v_cvt_pk_bf16_f32 v103, v209, v103
	v_cvt_pk_bf16_f32 v104, v104, v105
	v_cvt_pk_bf16_f32 v105, v106, v107
	s_waitcnt lgkmcnt(2)
	v_mfma_f32_32x32x16_bf16 v[112:127], v[224:227], v[140:143], v[112:127]
	v_cvt_pk_bf16_f32 v106, v210, v211
	v_cvt_pk_bf16_f32 v107, v216, v217
	v_permlane32_swap_b32_e32 v108, v110
	v_permlane32_swap_b32_e32 v109, v111
	v_permlane32_swap_b32_e32 v96, v98
	v_mfma_f32_32x32x16_bf16 v[80:95], v[220:223], v[140:143], v[80:95]
	v_permlane32_swap_b32_e32 v97, v99
	v_permlane32_swap_b32_e32 v100, v102
	v_permlane32_swap_b32_e32 v101, v103
	v_permlane32_swap_b32_e32 v104, v106
	s_waitcnt lgkmcnt(0)
	v_mfma_f32_32x32x16_bf16 v[112:127], v[228:231], v[128:131], v[112:127]
	v_permlane32_swap_b32_e32 v105, v107
	v_mfma_f32_32x32x16_bf16 v[80:95], v[212:215], v[128:131], v[80:95]
; #define SBAR() __builtin_amdgcn_sched_barrier(0)
; #define SWRITE(off, i) do { *(bf16x8*)((char*)V_lds + (off) + vst) = sr_[i].v; *(bf16x8*)((char*)K_lds + (off) + kst) = sr_[i].k; \
;     if (has_r) *(bf16x8*)((char*)K_lds + (off) + rst) = sr_[i].r; } while (0)
; #define SWAIT() do { if (has_r) asm volatile("s_waitcnt vmcnt(3)" ::: "memory"); else asm volatile("s_waitcnt vmcnt(2)" ::: "memory"); } while (0)
; template <int D0> __device__ __forceinline__ void pv_one(f32x16& od, int vb, bf16x8 pa0, bf16x8 pa1, bf16x8 pa2, bf16x8 pa3) {
;   const s16x4 l0 = tr_read<v_rd_off(D0, 0, 0)>(vb), h0 = tr_read<v_rd_off(D0, 0, 1)>(vb), l1 = tr_read<v_rd_off(D0, 1, 0)>(vb), h1 = tr_read<v_rd_off(D0, 1, 1)>(vb);
;   const s16x4 l2 = tr_read<v_rd_off(D0, 2, 0)>(vb), h2 = tr_read<v_rd_off(D0, 2, 1)>(vb), l3 = tr_read<v_rd_off(D0, 3, 0)>(vb), h3 = tr_read<v_rd_off(D0, 3, 1)>(vb);
;   asm volatile("s_waitcnt lgkmcnt(0)" ::: "memory"); SBAR();
;     ...
;   od = __builtin_amdgcn_mfma_f32_32x32x16_bf16(pa0, PK(l0, h0), od, 0, 0, 0);
;   od = __builtin_amdgcn_mfma_f32_32x32x16_bf16(pa1, PK(l1, h1), od, 0, 0, 0);
;   od = __builtin_amdgcn_mfma_f32_32x32x16_bf16(pa2, PK(l2, h2), od, 0, 0, 0);
;   od = __builtin_amdgcn_mfma_f32_32x32x16_bf16(pa3, PK(l3, h3), od, 0, 0, 0);
;     ...
; }
; __device__ __forceinline__ void pv_d0(f32x16* o, f32x16& osum, int vb, bf16x8 pa0, bf16x8 pa1, bf16x8 pa2, bf16x8 pa3) {
;   pv_one<0>(o[0], vb, pa0, pa1, pa2, pa3); pv_one<1>(o[1], vb, pa0, pa1, pa2, pa3);
;   const short one = (short)0x3F80; const bf16x8 ones = {one, one, one, one, one, one, one, one};
;   osum = __builtin_amdgcn_mfma_f32_32x32x16_bf16(pa0, ones, osum, 0, 0, 0); osum = __builtin_amdgcn_mfma_f32_32x32x16_bf16(pa1, ones, osum, 0, 0, 0);
;   osum = __builtin_amdgcn_mfma_f32_32x32x16_bf16(pa2, ones, osum, 0, 0, 0); osum = __builtin_amdgcn_mfma_f32_32x32x16_bf16(pa3, ones, osum, 0, 0, 0);
; __device__ __forceinline__ void attn_unit(const bf16_t* __restrict__ Qb, const bf16_t* __restrict__ KNh, const bf16_t* __restrict__ KRb, const bf16_t* __restrict__ Vh, ...
;     ...
;     pv_d0(o, osum, vb0 + o_prev, pa0, pa1, pa2, pa3); partialSM<false>(pA0, pA1, m_ref, negm, alA);
;     SWAIT(); SWRITE(o_next, SO);
.LBB0_739:
	v_add_u32_e32 v182, s41, v203
	ds_read_b64_tr_b16 v[204:205], v182 offset:0
	ds_read_b64_tr_b16 v[206:207], v182 offset:0x800
	ds_read_b64_tr_b16 v[208:209], v182 offset:0x1000
	ds_read_b64_tr_b16 v[210:211], v182 offset:0x1800
	ds_read_b64_tr_b16 v[212:213], v182 offset:0x2000
	ds_read_b64_tr_b16 v[214:215], v182 offset:0x2800
	ds_read_b64_tr_b16 v[216:217], v182 offset:0x3000
	ds_read_b64_tr_b16 v[218:219], v182 offset:0x3800
	s_waitcnt lgkmcnt(0)
	s_nop 0
	v_mfma_f32_32x32x16_bf16 v[16:31], v[108:111], v[204:207], v[16:31]
	ds_read_b64_tr_b16 v[204:205], v182 offset:0x200
	ds_read_b64_tr_b16 v[206:207], v182 offset:0xa00
	v_max_f32_e32 v254, v113, v113
	v_max_f32_e32 v255, v112, v112
	v_max_f32_e32 v254, v255, v254
	v_max3_f32 v254, v254, v114, v115
	v_max3_f32 v254, v254, v116, v117
	v_mfma_f32_32x32x16_bf16 v[16:31], v[96:99], v[208:211], v[16:31]
	ds_read_b64_tr_b16 v[208:209], v182 offset:0x1200
	ds_read_b64_tr_b16 v[210:211], v182 offset:0x1a00
	v_max3_f32 v254, v254, v118, v119
	v_max3_f32 v254, v254, v120, v121
	v_max3_f32 v254, v254, v122, v123
	v_max3_f32 v254, v254, v124, v125
	v_max3_f32 v254, v254, v126, v127
	v_mfma_f32_32x32x16_bf16 v[16:31], v[100:103], v[212:215], v[16:31]
	ds_read_b64_tr_b16 v[212:213], v182 offset:0x2200
	ds_read_b64_tr_b16 v[214:215], v182 offset:0x2a00
	ds_read_b64_tr_b16 v[220:221], v182 offset:0x3200
	ds_read_b64_tr_b16 v[222:223], v182 offset:0x3a00
	v_max3_f32 v254, v254, v80, v81
	v_max3_f32 v254, v254, v82, v83
	v_max3_f32 v254, v254, v84, v85
	v_max3_f32 v254, v254, v86, v87
	v_max3_f32 v254, v254, v88, v89
	s_waitcnt lgkmcnt(0)
	v_mfma_f32_32x32x16_bf16 v[16:31], v[104:107], v[216:219], v[16:31]
	v_max3_f32 v254, v254, v90, v91
	v_max3_f32 v254, v254, v92, v93
	v_max3_f32 v254, v254, v94, v95
	v_mov_b32_e32 v255, v254
	v_mfma_f32_32x32x16_bf16 v[32:47], v[108:111], v[204:207], v[32:47]
	v_mov_b64_e32 v[206:207], s[14:15]
	v_mov_b64_e32 v[204:205], s[12:13]
	v_permlane32_swap_b32_e32 v254, v255
	v_max_f32_e32 v255, v255, v255
	v_max_f32_e32 v254, v254, v254
	v_mfma_f32_32x32x16_bf16 v[48:63], v[108:111], v[204:207], v[48:63]
	v_max_f32_e32 v255, v254, v255
	v_cmp_ge_f32_e32 vcc, s71, v255
	s_cmp_eq_u64 vcc, exec
	v_mov_b32_e32 v254, 1.0
	s_cbranch_scc0 .Lattn_adj_h2
.Lattn_cont_h2:
	v_mfma_f32_32x32x16_bf16 v[32:47], v[96:99], v[208:211], v[32:47]
	v_exp_f32_e32 v0, v112
	v_exp_f32_e32 v1, v113
	v_exp_f32_e32 v2, v114
	v_mfma_f32_32x32x16_bf16 v[48:63], v[96:99], v[204:207], v[48:63]
	v_exp_f32_e32 v3, v115
	v_exp_f32_e32 v4, v116
	v_exp_f32_e32 v5, v117
	v_mfma_f32_32x32x16_bf16 v[32:47], v[100:103], v[212:215], v[32:47]
	v_exp_f32_e32 v6, v118
	v_exp_f32_e32 v7, v119
	v_exp_f32_e32 v8, v120
	v_mfma_f32_32x32x16_bf16 v[48:63], v[100:103], v[204:207], v[48:63]
	v_exp_f32_e32 v9, v121
	v_exp_f32_e32 v10, v122
	v_exp_f32_e32 v11, v123
	v_mfma_f32_32x32x16_bf16 v[32:47], v[104:107], v[220:223], v[32:47]
	v_exp_f32_e32 v12, v124
	v_exp_f32_e32 v13, v125
	v_mfma_f32_32x32x16_bf16 v[48:63], v[104:107], v[204:207], v[48:63]
	v_exp_f32_e32 v14, v126
	v_exp_f32_e32 v15, v127
	s_mov_b64 s[38:39], -1
	s_and_b64 vcc, exec, s[34:35]
	s_cbranch_vccz .LBB0_743
.LBB0_741:
	s_waitcnt vmcnt(2)
	s_cbranch_execz .LBB0_744
	s_branch .LBB0_745
.LBB0_743:
	s_andn2_b64 vcc, exec, s[38:39]
	s_cbranch_vccnz .LBB0_745

; #define SWRITE(off, i) do { *(bf16x8*)((char*)V_lds + (off) + vst) = sr_[i].v; *(bf16x8*)((char*)K_lds + (off) + kst) = sr_[i].k; \
;     if (has_r) *(bf16x8*)((char*)K_lds + (off) + rst) = sr_[i].r; } while (0)
; #define SWAIT() do { if (has_r) asm volatile("s_waitcnt vmcnt(3)" ::: "memory"); else asm volatile("s_waitcnt vmcnt(2)" ::: "memory"); } while (0)
; #define RESC(a) do { if (__any((a) < 1.f)) { if (hi == 0) al_l[r32] = (a); asm volatile("s_waitcnt lgkmcnt(0)" ::: "memory"); \
;     _Pragma("unroll") for (int r = 0; r < 16; ++r) { const float f_ = al_l[crow(r, hi)]; o[0][r] *= f_; o[1][r] *= f_; osum[r] *= f_; } } } while (0)
; #define ROT() do { const int t_ = o_prev; o_prev = o_cur; o_cur = o_next; o_next = t_; } while (0)
; template <bool FIRST> __device__ __forceinline__ void partialSM(f32x16& p0, f32x16& p1, float& m_ref, f32x16& negm, float& alpha) {
;     ...
;   if (FIRST || !__builtin_expect(__all(pmax <= THR2), 1)) {
;     const float dl = FIRST ? pmax : fmaxf(pmax, 0.f);
;     m_ref += dl; alpha = FIRST ? 1.f : __builtin_amdgcn_exp2f(-dl);
; #pragma unroll
;     for (int r = 0; r < 16; ++r) { p0[r] -= dl; p1[r] -= dl; }
; #pragma unroll
;     for (int r = 0; r < 16; ++r) negm[r] = -m_ref;
;     asm volatile("" : "+v"(negm));
; __device__ __forceinline__ void attn_unit(const bf16_t* __restrict__ Qb, const bf16_t* __restrict__ KNh, const bf16_t* __restrict__ KRb, const bf16_t* __restrict__ Vh, ...
;     ...
;     SWAIT(); SWRITE(o_next, SO);
;     RESC(alA); __syncthreads(); ROT();
.LBB0_747:
	v_cmp_gt_f32_e32 vcc, 1.0, v254
	s_cbranch_vccz .LBB0_751
	s_and_saveexec_b64 s[38:39], s[8:9]
	ds_write_b32 v192, v254 offset:128
	s_or_b64 exec, exec, s[38:39]
	s_waitcnt lgkmcnt(0)
	v_add_u32_e32 v108, s29, v176
	ds_read_b128 v[96:99], v108 offset:224
	ds_read_b128 v[100:103], v108 offset:192
	ds_read_b128 v[104:107], v108 offset:160
	ds_read_b128 v[108:111], v108 offset:128
	s_waitcnt lgkmcnt(3)
	v_pk_mul_f32 v[28:29], v[28:29], v[96:97]
	s_waitcnt lgkmcnt(2)
	v_pk_mul_f32 v[24:25], v[24:25], v[100:101]
	s_waitcnt lgkmcnt(1)
	v_pk_mul_f32 v[20:21], v[20:21], v[104:105]
	v_pk_mul_f32 v[30:31], v[30:31], v[98:99]
	v_pk_mul_f32 v[26:27], v[26:27], v[102:103]
	v_pk_mul_f32 v[22:23], v[22:23], v[106:107]
	s_waitcnt lgkmcnt(0)
	v_pk_mul_f32 v[18:19], v[18:19], v[110:111]
	v_pk_mul_f32 v[16:17], v[16:17], v[108:109]
	v_pk_mul_f32 v[44:45], v[44:45], v[96:97]
	v_pk_mul_f32 v[40:41], v[40:41], v[100:101]
	v_pk_mul_f32 v[36:37], v[36:37], v[104:105]
	v_pk_mul_f32 v[46:47], v[46:47], v[98:99]
	v_pk_mul_f32 v[42:43], v[42:43], v[102:103]
	v_pk_mul_f32 v[38:39], v[38:39], v[106:107]
	v_pk_mul_f32 v[34:35], v[34:35], v[110:111]
	v_pk_mul_f32 v[32:33], v[32:33], v[108:109]
	v_pk_mul_f32 v[60:61], v[60:61], v[96:97]
	v_pk_mul_f32 v[56:57], v[56:57], v[100:101]
	v_pk_mul_f32 v[52:53], v[52:53], v[104:105]
	v_pk_mul_f32 v[62:63], v[62:63], v[98:99]
	v_pk_mul_f32 v[58:59], v[58:59], v[102:103]
	v_pk_mul_f32 v[54:55], v[54:55], v[106:107]
	v_pk_mul_f32 v[50:51], v[50:51], v[110:111]
	v_pk_mul_f32 v[48:49], v[48:49], v[108:109]
.LBB0_751:
	v_lshl_add_u64 v[178:179], v[178:179], 0, s[24:25]
	v_lshl_add_u64 v[180:181], v[180:181], 0, s[26:27]
	s_add_i32 s67, s67, 2
	s_and_b64 vcc, exec, s[36:37]
	s_waitcnt lgkmcnt(0)
	s_barrier
	s_cbranch_vccnz .LBB0_755
	s_mov_b32 s36, s41
	s_mov_b32 s41, s77
	s_mov_b32 s77, s40
	s_branch .LBB0_722
.Lattn_adj_h1:
	v_max_f32_e32 v64, v255, v255
	v_max_f32_e32 v64, 0, v64
	v_exp_f32_e64 v254, -v64
	v_add_f32_e32 v191, v191, v64
	v_pk_add_f32 v[112:113], v[112:113], v[64:65] op_sel_hi:[1,0] neg_lo:[0,1] neg_hi:[0,1]
	v_pk_add_f32 v[114:115], v[114:115], v[64:65] op_sel_hi:[1,0] neg_lo:[0,1] neg_hi:[0,1]
	v_pk_add_f32 v[116:117], v[116:117], v[64:65] op_sel_hi:[1,0] neg_lo:[0,1] neg_hi:[0,1]
	v_pk_add_f32 v[118:119], v[118:119], v[64:65] op_sel_hi:[1,0] neg_lo:[0,1] neg_hi:[0,1]
	v_pk_add_f32 v[120:121], v[120:121], v[64:65] op_sel_hi:[1,0] neg_lo:[0,1] neg_hi:[0,1]
	v_pk_add_f32 v[122:123], v[122:123], v[64:65] op_sel_hi:[1,0] neg_lo:[0,1] neg_hi:[0,1]
	v_pk_add_f32 v[124:125], v[124:125], v[64:65] op_sel_hi:[1,0] neg_lo:[0,1] neg_hi:[0,1]
	v_pk_add_f32 v[126:127], v[126:127], v[64:65] op_sel_hi:[1,0] neg_lo:[0,1] neg_hi:[0,1]
	v_sub_f32_e32 v111, v111, v64
	v_sub_f32_e32 v110, v110, v64
	v_sub_f32_e32 v109, v109, v64
	v_sub_f32_e32 v108, v108, v64
	v_sub_f32_e32 v107, v107, v64
	v_sub_f32_e32 v106, v106, v64
	v_sub_f32_e32 v105, v105, v64
	v_sub_f32_e32 v104, v104, v64
	v_sub_f32_e32 v103, v103, v64
	v_sub_f32_e32 v102, v102, v64
	v_sub_f32_e32 v101, v101, v64
	v_sub_f32_e32 v100, v100, v64
	v_sub_f32_e32 v99, v99, v64
	v_sub_f32_e32 v98, v98, v64
	v_sub_f32_e32 v97, v97, v64
	v_sub_f32_e32 v96, v96, v64
	v_xor_b32_e32 v64, 0x80000000, v191
	v_mov_b32_e32 v65, v64
	v_mov_b32_e32 v66, v64
	v_mov_b32_e32 v67, v64
	v_mov_b32_e32 v68, v64
	v_mov_b32_e32 v69, v64
	v_mov_b32_e32 v70, v64
	v_mov_b32_e32 v71, v64
	v_mov_b32_e32 v72, v64
	v_mov_b32_e32 v73, v64
	v_mov_b32_e32 v74, v64
	v_mov_b32_e32 v75, v64
	v_mov_b32_e32 v76, v64
	v_mov_b32_e32 v77, v64
	v_mov_b32_e32 v78, v64
	v_mov_b32_e32 v79, v64
	s_branch .Lattn_cont_h1
.Lattn_adj_h2:
	v_max_f32_e32 v64, v255, v255
	v_max_f32_e32 v64, 0, v64
	v_exp_f32_e64 v254, -v64
	v_add_f32_e32 v191, v191, v64
	v_pk_add_f32 v[112:113], v[112:113], v[64:65] op_sel_hi:[1,0] neg_lo:[0,1] neg_hi:[0,1]
	v_pk_add_f32 v[114:115], v[114:115], v[64:65] op_sel_hi:[1,0] neg_lo:[0,1] neg_hi:[0,1]
	v_pk_add_f32 v[116:117], v[116:117], v[64:65] op_sel_hi:[1,0] neg_lo:[0,1] neg_hi:[0,1]
	v_pk_add_f32 v[118:119], v[118:119], v[64:65] op_sel_hi:[1,0] neg_lo:[0,1] neg_hi:[0,1]
	v_pk_add_f32 v[120:121], v[120:121], v[64:65] op_sel_hi:[1,0] neg_lo:[0,1] neg_hi:[0,1]
	v_pk_add_f32 v[122:123], v[122:123], v[64:65] op_sel_hi:[1,0] neg_lo:[0,1] neg_hi:[0,1]
	v_pk_add_f32 v[124:125], v[124:125], v[64:65] op_sel_hi:[1,0] neg_lo:[0,1] neg_hi:[0,1]
	v_pk_add_f32 v[126:127], v[126:127], v[64:65] op_sel_hi:[1,0] neg_lo:[0,1] neg_hi:[0,1]
	v_sub_f32_e32 v95, v95, v64
	v_sub_f32_e32 v94, v94, v64
	v_sub_f32_e32 v93, v93, v64
	v_sub_f32_e32 v92, v92, v64
	v_sub_f32_e32 v91, v91, v64
	v_sub_f32_e32 v90, v90, v64
	v_sub_f32_e32 v89, v89, v64
	v_sub_f32_e32 v88, v88, v64
	v_sub_f32_e32 v87, v87, v64
	v_sub_f32_e32 v86, v86, v64
	v_sub_f32_e32 v85, v85, v64
	v_sub_f32_e32 v84, v84, v64
	v_sub_f32_e32 v83, v83, v64
	v_sub_f32_e32 v82, v82, v64
	v_sub_f32_e32 v81, v81, v64
	v_sub_f32_e32 v80, v80, v64
	v_xor_b32_e32 v64, 0x80000000, v191
	v_mov_b32_e32 v65, v64
	v_mov_b32_e32 v66, v64
	v_mov_b32_e32 v67, v64
	v_mov_b32_e32 v68, v64
	v_mov_b32_e32 v69, v64
	v_mov_b32_e32 v70, v64
	v_mov_b32_e32 v71, v64
	v_mov_b32_e32 v72, v64
	v_mov_b32_e32 v73, v64
	v_mov_b32_e32 v74, v64
	v_mov_b32_e32 v75, v64
	v_mov_b32_e32 v76, v64
	v_mov_b32_e32 v77, v64
	v_mov_b32_e32 v78, v64
	v_mov_b32_e32 v79, v64
	s_branch .Lattn_cont_h2

; #define SBAR() __builtin_amdgcn_sched_barrier(0)
; #define RESC(a) do { if (__any((a) < 1.f)) { if (hi == 0) al_l[r32] = (a); asm volatile("s_waitcnt lgkmcnt(0)" ::: "memory"); \
;     _Pragma("unroll") for (int r = 0; r < 16; ++r) { const float f_ = al_l[crow(r, hi)]; o[0][r] *= f_; o[1][r] *= f_; osum[r] *= f_; } } } while (0)
; __device__ __forceinline__ void attn_unit(const bf16_t* __restrict__ Qb, const bf16_t* __restrict__ KNh, const bf16_t* __restrict__ KRb, const bf16_t* __restrict__ Vh, ...
;     ...
;   SBAR(); qkt(pB0, pB1, (bf16_t*)((char*)K_lds + o_cur), qr, negm, r32, hi);
;   finishSM(pA0, pA1, pa0, pa1, pa2, pa3); SBAR();
;   pv_d0(o, osum, vb0 + o_prev, pa0, pa1, pa2, pa3); partialSM<false>(pB0, pB1, m_ref, negm, alB);
;   RESC(alB);
;   finishSM(pB0, pB1, pa0, pa1, pa2, pa3); SBAR();
;   pv_d0(o, osum, vb0 + o_cur, pa0, pa1, pa2, pa3);
.LBB0_755:
	v_exp_f32_e32 v183, v112
	v_exp_f32_e32 v207, v113
	v_exp_f32_e32 v204, v114
	v_exp_f32_e32 v208, v115
	v_exp_f32_e32 v205, v116
	v_exp_f32_e32 v209, v117
	v_exp_f32_e32 v182, v118
	v_exp_f32_e32 v206, v119
	v_exp_f32_e32 v171, v120
	v_exp_f32_e32 v174, v121
	v_exp_f32_e32 v172, v122
	v_exp_f32_e32 v175, v123
	v_exp_f32_e32 v169, v124
	v_exp_f32_e32 v173, v125
	v_exp_f32_e32 v168, v126
	v_exp_f32_e32 v170, v127
	v_add_u32_e32 v116, s58, v197
	ds_read_b128 v[112:115], v116 offset:49152
	v_add_u32_e32 v120, s58, v199
	v_add_u32_e32 v124, s58, v200
	v_add_u32_e32 v144, s58, v201
	v_exp_f32_e32 v95, v95
	v_exp_f32_e32 v160, v84
	s_waitcnt lgkmcnt(0)
	v_mfma_f32_32x32x16_bf16 v[96:111], v[112:115], v[156:159], v[64:79]
	ds_read_b128 v[112:115], v116 offset:57344
	v_add_u32_e32 v116, s58, v198
	s_waitcnt lgkmcnt(0)
	v_mfma_f32_32x32x16_bf16 v[64:79], v[112:115], v[156:159], v[64:79]
	ds_read_b128 v[112:115], v116 offset:49152
	v_exp_f32_e32 v156, v80
	v_exp_f32_e32 v157, v81
	v_exp_f32_e32 v158, v82
	v_exp_f32_e32 v159, v83
	s_waitcnt lgkmcnt(0)
	v_mfma_f32_32x32x16_bf16 v[96:111], v[112:115], v[152:155], v[96:111]
	ds_read_b128 v[112:115], v116 offset:57344
	ds_read_b128 v[116:119], v120 offset:57344
	ds_read_b128 v[120:123], v120 offset:49152
	s_waitcnt lgkmcnt(2)
	v_mfma_f32_32x32x16_bf16 v[64:79], v[112:115], v[152:155], v[64:79]
	ds_read_b128 v[112:115], v124 offset:57344
	ds_read_b128 v[124:127], v124 offset:49152
	ds_read_b128 v[132:135], v144 offset:57344
	ds_read_b128 v[144:147], v144 offset:49152
	v_add_u32_e32 v152, s58, v202
	s_waitcnt lgkmcnt(4)
	v_mfma_f32_32x32x16_bf16 v[96:111], v[120:123], v[148:151], v[96:111]
	ds_read_b128 v[120:123], v152 offset:57344
	ds_read_b128 v[152:155], v152 offset:49152
	v_cvt_pk_bf16_f32 v80, v183, v207
	v_cvt_pk_bf16_f32 v81, v204, v208
	v_cvt_pk_bf16_f32 v82, v205, v209
	v_cvt_pk_bf16_f32 v83, v182, v206
	v_cvt_pk_bf16_f32 v84, v171, v174
	v_mfma_f32_32x32x16_bf16 v[64:79], v[116:119], v[148:151], v[64:79]
	v_exp_f32_e32 v116, v85
	v_exp_f32_e32 v117, v86
	v_exp_f32_e32 v118, v87
	v_exp_f32_e32 v119, v88
	v_exp_f32_e32 v148, v89
	v_exp_f32_e32 v149, v90
	v_exp_f32_e32 v150, v91
	s_waitcnt lgkmcnt(4)
	v_mfma_f32_32x32x16_bf16 v[96:111], v[124:127], v[136:139], v[96:111]
	v_exp_f32_e32 v124, v92
	v_exp_f32_e32 v125, v93
	v_exp_f32_e32 v126, v94
	v_permlane32_swap_b32_e32 v80, v82
	v_cvt_pk_bf16_f32 v85, v172, v175
	v_cvt_pk_bf16_f32 v86, v169, v173
	v_mfma_f32_32x32x16_bf16 v[64:79], v[112:115], v[136:139], v[64:79]
	v_cvt_pk_bf16_f32 v87, v168, v170
	v_cvt_pk_bf16_f32 v88, v156, v157
	v_cvt_pk_bf16_f32 v89, v158, v159
	v_cvt_pk_bf16_f32 v90, v160, v116
	v_cvt_pk_bf16_f32 v91, v117, v118
	v_cvt_pk_bf16_f32 v92, v119, v148
	v_cvt_pk_bf16_f32 v93, v149, v150
	s_waitcnt lgkmcnt(2)
	v_mfma_f32_32x32x16_bf16 v[96:111], v[144:147], v[140:143], v[96:111]
	v_cvt_pk_bf16_f32 v94, v124, v125
	v_cvt_pk_bf16_f32 v95, v126, v95
	v_permlane32_swap_b32_e32 v81, v83
	v_permlane32_swap_b32_e32 v84, v86
	v_permlane32_swap_b32_e32 v85, v87
	v_mfma_f32_32x32x16_bf16 v[64:79], v[132:135], v[140:143], v[64:79]
	v_permlane32_swap_b32_e32 v88, v90
	v_permlane32_swap_b32_e32 v89, v91
	v_permlane32_swap_b32_e32 v92, v94
	v_permlane32_swap_b32_e32 v93, v95
	s_waitcnt lgkmcnt(0)
	v_mfma_f32_32x32x16_bf16 v[96:111], v[152:155], v[128:131], v[96:111]
	v_mfma_f32_32x32x16_bf16 v[64:79], v[120:123], v[128:131], v[64:79]
	v_add_u32_e32 v132, s40, v203
	ds_read_b64_tr_b16 v[112:113], v132 offset:0
	ds_read_b64_tr_b16 v[114:115], v132 offset:0x800
	ds_read_b64_tr_b16 v[116:117], v132 offset:0x1000
	ds_read_b64_tr_b16 v[118:119], v132 offset:0x1800
	ds_read_b64_tr_b16 v[120:121], v132 offset:0x2000
	ds_read_b64_tr_b16 v[122:123], v132 offset:0x2800
	ds_read_b64_tr_b16 v[124:125], v132 offset:0x3000
	ds_read_b64_tr_b16 v[126:127], v132 offset:0x3800
	s_waitcnt lgkmcnt(0)
	s_nop 0
	v_mfma_f32_32x32x16_bf16 v[16:31], v[80:83], v[112:115], v[16:31]
	ds_read_b64_tr_b16 v[112:113], v132 offset:0x200
	ds_read_b64_tr_b16 v[114:115], v132 offset:0xa00
	v_mfma_f32_32x32x16_bf16 v[16:31], v[84:87], v[116:119], v[16:31]
	ds_read_b64_tr_b16 v[116:117], v132 offset:0x1200
	ds_read_b64_tr_b16 v[118:119], v132 offset:0x1a00
	v_mfma_f32_32x32x16_bf16 v[16:31], v[88:91], v[120:123], v[16:31]
	ds_read_b64_tr_b16 v[120:121], v132 offset:0x2200
	ds_read_b64_tr_b16 v[122:123], v132 offset:0x2a00
	ds_read_b64_tr_b16 v[128:129], v132 offset:0x3200
	ds_read_b64_tr_b16 v[130:131], v132 offset:0x3a00
	s_waitcnt lgkmcnt(0)
	v_mfma_f32_32x32x16_bf16 v[16:31], v[92:95], v[124:127], v[16:31]
	v_mfma_f32_32x32x16_bf16 v[32:47], v[80:83], v[112:115], v[32:47]
	s_nop 3
	v_max_f32_e32 v112, v97, v97
	v_max_f32_e32 v113, v96, v96
	v_max_f32_e32 v112, v113, v112
	v_max3_f32 v112, v112, v98, v99
	v_max3_f32 v112, v112, v100, v101
	v_mfma_f32_32x32x16_bf16 v[32:47], v[84:87], v[116:119], v[32:47]
	v_mov_b64_e32 v[116:117], s[14:15]
	v_mov_b64_e32 v[114:115], s[12:13]
	s_nop 1
	v_mfma_f32_32x32x16_bf16 v[48:63], v[80:83], v[114:117], v[48:63]
	v_max3_f32 v80, v112, v102, v103
	v_max3_f32 v80, v80, v104, v105
	v_max3_f32 v80, v80, v106, v107
	v_max3_f32 v80, v80, v108, v109
	v_max3_f32 v80, v80, v110, v111
	v_max3_f32 v80, v80, v64, v65
	v_max3_f32 v80, v80, v66, v67
	v_mfma_f32_32x32x16_bf16 v[48:63], v[84:87], v[114:117], v[48:63]
	v_max3_f32 v80, v80, v68, v69
	v_max3_f32 v80, v80, v70, v71
	v_max3_f32 v80, v80, v72, v73
	v_max3_f32 v80, v80, v74, v75
	v_max3_f32 v80, v80, v76, v77
	v_max3_f32 v80, v80, v78, v79
	v_mov_b32_e32 v81, v80
	v_mfma_f32_32x32x16_bf16 v[32:47], v[88:91], v[120:123], v[32:47]
	s_nop 0
	v_permlane32_swap_b32_e32 v80, v81
	v_max_f32_e32 v81, v81, v81
	v_max_f32_e32 v80, v80, v80
	v_max_f32_e32 v80, v80, v81
	v_cmp_ge_f32_e32 vcc, s71, v80
	s_cmp_eq_u64 vcc, exec
	v_mfma_f32_32x32x16_bf16 v[48:63], v[88:91], v[114:117], v[48:63]
	v_mov_b32_e32 v112, 1.0
	v_mfma_f32_32x32x16_bf16 v[32:47], v[92:95], v[128:131], v[32:47]
	v_mfma_f32_32x32x16_bf16 v[48:63], v[92:95], v[114:117], v[48:63]
	s_cbranch_scc0 .LBB0_759
	v_cmp_gt_f32_e32 vcc, 1.0, v112
	s_cbranch_vccz .LBB0_704

; #define PG8_STAGE(bufoff, gbase, voff) do { _Pragma("unroll") for (int _i = 0; _i < 2; ++_i) \
;         __builtin_amdgcn_global_load_lds((const unsigned*)((const char*)(gbase) + (voff)[_i]), (PG8_LAS unsigned*)(lds + (bufoff) + ldsw + _i * 8192), 16, 0, 0); } while (0)
; #define PG8_LDA(dst, b, h) do { _Pragma("unroll") for (int m = 0; m < 4; ++m) _Pragma("unroll") for (int k = 0; k < 2; ++k) dst[m][k] = *(const PG8_LAS bf16x8*)(lds + PG8_SA(b, h) + aoff + m * 2048 + k * 1024); } while (0)
; #define PG8_LDB(dst, b, h) do { _Pragma("unroll") for (int n = 0; n < 2; ++n) _Pragma("unroll") for (int k = 0; k < 2; ++k) dst[n][k] = *(const PG8_LAS bf16x8*)(lds + PG8_SB(b, h) + boff + n * 2048 + k * 1024); } while (0)
; #define PG8_MMA(ai, bj, At, Bt) do { __builtin_amdgcn_s_setprio(1); _Pragma("unroll") for (int m = 0; m < 4; ++m) _Pragma("unroll") for (int n = 0; n < 2; ++n) _Pragma("unroll") for (int k = 0; k < 2; ++k) \
;         acc[ai][bj][m][n] = __builtin_amdgcn_mfma_f32_16x16x32_bf16(Bt[n][k], At[m][k], acc[ai][bj][m][n], 0, 0, 0); __builtin_amdgcn_s_setprio(0); } while (0)
; #define PG8_WAIT_V(n) asm volatile("s_waitcnt vmcnt(" #n ")" ::: "memory")
; #define PG8_WAIT_L(n) asm volatile("s_waitcnt lgkmcnt(" #n ")" ::: "memory")
; #define PG8_BAR __builtin_amdgcn_s_barrier()
; #define PG8_SCHED __builtin_amdgcn_sched_barrier(0)
; template <class Epi, class Sched, bool ALIGN_EPI = false, bool SP2 = false>
; __device__ __forceinline__ void gemm_phase(PG8_LAS unsigned char* lds, const Gemm g, const Sched& S, const Epi& E) {
;     ...
;         for (int t = 0; t < nt; t += 2) {
;             const bool last = (t == nt - 2);
;             const char* a1 = cA + (size_t)(t + 1) * kstep;
;             const char* a2 = last ? nA : cA + (size_t)(t + 2) * kstep; const char* b2 = last ? nB : cB + (size_t)(t + 2) * kstep;
;             const char* a3 = a2 + kstep; const char* b3 = b2 + kstep;
;             if (last && has_next) S.a_ready(nxt);
;             if constexpr (SP2) {
;             PG8_LDB(B0, 0, 0); PG8_LDB(B1, 0, 1); PG8_SCHED; PG8_LDA(At, 0, 0); PG8_STAGE(PG8_SA(1, 1), a1 + hstepA, voffA);
;             PG8_WAIT_V(8); PG8_WAIT_L(0); PG8_BAR; PG8_MMA(0, 0, At, B0); PG8_MMA(0, 1, At, B1); PG8_BAR; PG8_SCHED;
;             PG8_LDA(At, 0, 1); PG8_STAGE(PG8_SB(0, 0), b2, voffB); PG8_STAGE(PG8_SB(0, 1), b2 + hstepB, voffB); PG8_STAGE(PG8_SA(0, 0), a2, voffA);
.LBB0_971:
	ds_read_b128 v[128:131], v191
	ds_read_b128 v[132:135], v191 offset:1024
	ds_read_b128 v[136:139], v191 offset:2048
	ds_read_b128 v[140:143], v191 offset:3072
	ds_read_b128 v[144:147], v192
	ds_read_b128 v[148:151], v192 offset:1024
	ds_read_b128 v[168:171], v192 offset:2048
	ds_read_b128 v[172:175], v192 offset:3072
	s_add_u32 s34, s30, 0xfffc0080
	s_addc_u32 s35, s31, -1
	s_cmp_eq_u32 s74, 12
	s_cselect_b32 s37, s21, s35
	s_cselect_b32 s36, s27, s34
	s_cselect_b32 s35, s19, s73
	s_cselect_b32 s34, s68, s69
	v_lshl_add_u64 v[184:185], s[30:31], 0, v[160:161]
	s_add_i32 m0, s29, 0xc000
	ds_read_b128 v[176:179], v193
	ds_read_b128 v[180:183], v193 offset:1024
	ds_read_b128 v[196:199], v193 offset:2048
	ds_read_b128 v[200:203], v193 offset:3072
	ds_read_b128 v[204:207], v193 offset:4096
	ds_read_b128 v[208:211], v193 offset:5120
	ds_read_b128 v[212:215], v193 offset:6144
	ds_read_b128 v[216:219], v193 offset:7168
	global_load_lds_dwordx4 v[184:185], off
	v_lshl_add_u64 v[184:185], s[30:31], 0, v[162:163]
	s_add_i32 m0, s29, 0xe000
	s_nop 0
	global_load_lds_dwordx4 v[184:185], off
	s_waitcnt vmcnt(8)
	s_waitcnt lgkmcnt(0)
	s_barrier
	s_setprio 1
	s_waitcnt lgkmcnt(0)
	v_mfma_f32_16x16x32_bf16 v[124:127], v[128:131], v[176:179], v[124:127]
	v_mfma_f32_16x16x32_bf16 v[120:123], v[136:139], v[176:179], v[120:123]
	v_mfma_f32_16x16x32_bf16 v[108:111], v[128:131], v[196:199], v[108:111]
	v_mfma_f32_16x16x32_bf16 v[104:107], v[136:139], v[196:199], v[104:107]
	v_mfma_f32_16x16x32_bf16 v[92:95], v[128:131], v[204:207], v[92:95]
	v_mfma_f32_16x16x32_bf16 v[88:91], v[136:139], v[204:207], v[88:91]
	v_mfma_f32_16x16x32_bf16 v[76:79], v[128:131], v[212:215], v[76:79]
	v_mfma_f32_16x16x32_bf16 v[72:75], v[136:139], v[212:215], v[72:75]
	v_mfma_f32_16x16x32_bf16 v[124:127], v[132:135], v[180:183], v[124:127]
	v_mfma_f32_16x16x32_bf16 v[120:123], v[140:143], v[180:183], v[120:123]
	v_mfma_f32_16x16x32_bf16 v[108:111], v[132:135], v[200:203], v[108:111]
	v_mfma_f32_16x16x32_bf16 v[104:107], v[140:143], v[200:203], v[104:107]
	v_mfma_f32_16x16x32_bf16 v[92:95], v[132:135], v[208:211], v[92:95]
	v_mfma_f32_16x16x32_bf16 v[88:91], v[140:143], v[208:211], v[88:91]
	v_mfma_f32_16x16x32_bf16 v[76:79], v[132:135], v[216:219], v[76:79]
	v_mfma_f32_16x16x32_bf16 v[72:75], v[140:143], v[216:219], v[72:75]
	s_setprio 0
	s_setprio 1
	v_mfma_f32_16x16x32_bf16 v[116:119], v[144:147], v[176:179], v[116:119]
	v_mfma_f32_16x16x32_bf16 v[112:115], v[168:171], v[176:179], v[112:115]
	v_mfma_f32_16x16x32_bf16 v[100:103], v[144:147], v[196:199], v[100:103]
	v_mfma_f32_16x16x32_bf16 v[96:99], v[168:171], v[196:199], v[96:99]
	v_mfma_f32_16x16x32_bf16 v[84:87], v[144:147], v[204:207], v[84:87]
	v_mfma_f32_16x16x32_bf16 v[80:83], v[168:171], v[204:207], v[80:83]
	v_mfma_f32_16x16x32_bf16 v[68:71], v[144:147], v[212:215], v[68:71]
	v_mfma_f32_16x16x32_bf16 v[64:67], v[168:171], v[212:215], v[64:67]
	v_mfma_f32_16x16x32_bf16 v[116:119], v[148:151], v[180:183], v[116:119]
	v_mfma_f32_16x16x32_bf16 v[112:115], v[172:175], v[180:183], v[112:115]
	v_mfma_f32_16x16x32_bf16 v[100:103], v[148:151], v[200:203], v[100:103]
	v_mfma_f32_16x16x32_bf16 v[96:99], v[172:175], v[200:203], v[96:99]
	v_mfma_f32_16x16x32_bf16 v[84:87], v[148:151], v[208:211], v[84:87]
	v_mfma_f32_16x16x32_bf16 v[80:83], v[172:175], v[208:211], v[80:83]
	v_mfma_f32_16x16x32_bf16 v[68:71], v[148:151], v[216:219], v[68:71]
	v_mfma_f32_16x16x32_bf16 v[64:67], v[172:175], v[216:219], v[64:67]
	s_barrier
	s_setprio 0
	s_add_i32 s58, s49, s39
	v_lshl_add_u64 v[184:185], s[34:35], 0, v[154:155]
	s_mov_b32 m0, s58
	ds_read_b128 v[176:179], v193 offset:16384
	ds_read_b128 v[180:183], v193 offset:17408
	ds_read_b128 v[196:199], v193 offset:18432
	ds_read_b128 v[200:203], v193 offset:19456
	ds_read_b128 v[204:207], v193 offset:20480
	ds_read_b128 v[208:211], v193 offset:21504
	ds_read_b128 v[212:215], v193 offset:22528
	ds_read_b128 v[216:219], v193 offset:23552
	global_load_lds_dwordx4 v[184:185], off
	s_add_i32 m0, s58, 0x2000
	s_add_u32 s58, s34, 0x40000
	v_lshl_add_u64 v[220:221], s[34:35], 0, v[158:159]
	s_addc_u32 s59, s35, 0
	s_add_i32 s75, s66, s39
	global_load_lds_dwordx4 v[220:221], off
	v_lshl_add_u64 v[222:223], s[58:59], 0, v[154:155]
	s_mov_b32 m0, s75
	v_lshl_add_u64 v[224:225], s[36:37], 0, v[156:157]
	global_load_lds_dwordx4 v[222:223], off
	v_lshl_add_u64 v[222:223], s[58:59], 0, v[158:159]
	s_add_i32 m0, s75, 0x2000
	s_nop 0
	global_load_lds_dwordx4 v[222:223], off
	v_lshl_add_u64 v[222:223], s[36:37], 0, v[152:153]
	s_mov_b32 m0, s29
	s_nop 0
	global_load_lds_dwordx4 v[222:223], off
	s_mov_b32 m0, s40
	s_nop 0
	global_load_lds_dwordx4 v[224:225], off
	s_waitcnt vmcnt(8)
	s_waitcnt lgkmcnt(0)
	s_barrier
; #define PG8_STAGE(bufoff, gbase, voff) do { _Pragma("unroll") for (int _i = 0; _i < 2; ++_i) \
;         __builtin_amdgcn_global_load_lds((const unsigned*)((const char*)(gbase) + (voff)[_i]), (PG8_LAS unsigned*)(lds + (bufoff) + ldsw + _i * 8192), 16, 0, 0); } while (0)
; #define PG8_LDA(dst, b, h) do { _Pragma("unroll") for (int m = 0; m < 4; ++m) _Pragma("unroll") for (int k = 0; k < 2; ++k) dst[m][k] = *(const PG8_LAS bf16x8*)(lds + PG8_SA(b, h) + aoff + m * 2048 + k * 1024); } while (0)
; #define PG8_LDB(dst, b, h) do { _Pragma("unroll") for (int n = 0; n < 2; ++n) _Pragma("unroll") for (int k = 0; k < 2; ++k) dst[n][k] = *(const PG8_LAS bf16x8*)(lds + PG8_SB(b, h) + boff + n * 2048 + k * 1024); } while (0)
; #define PG8_MMA(ai, bj, At, Bt) do { __builtin_amdgcn_s_setprio(1); _Pragma("unroll") for (int m = 0; m < 4; ++m) _Pragma("unroll") for (int n = 0; n < 2; ++n) _Pragma("unroll") for (int k = 0; k < 2; ++k) \
;         acc[ai][bj][m][n] = __builtin_amdgcn_mfma_f32_16x16x32_bf16(Bt[n][k], At[m][k], acc[ai][bj][m][n], 0, 0, 0); __builtin_amdgcn_s_setprio(0); } while (0)
; #define PG8_WAIT_V(n) asm volatile("s_waitcnt vmcnt(" #n ")" ::: "memory")
; #define PG8_WAIT_L(n) asm volatile("s_waitcnt lgkmcnt(" #n ")" ::: "memory")
; #define PG8_BAR __builtin_amdgcn_s_barrier()
; #define PG8_SCHED __builtin_amdgcn_sched_barrier(0)
; template <class Epi, class Sched, bool ALIGN_EPI = false, bool SP2 = false>
; __device__ __forceinline__ void gemm_phase(PG8_LAS unsigned char* lds, const Gemm g, const Sched& S, const Epi& E) {
;     ...
;             PG8_WAIT_V(8); PG8_WAIT_L(0); PG8_BAR; PG8_MMA(1, 0, At, B0); PG8_MMA(1, 1, At, B1); PG8_BAR; PG8_SCHED;
;             PG8_LDB(B0, 1, 0); PG8_LDB(B1, 1, 1); PG8_SCHED; PG8_LDA(At, 1, 0); PG8_STAGE(PG8_SA(0, 1), a2 + hstepA, voffA);
;             PG8_WAIT_V(8); PG8_WAIT_L(0); PG8_BAR; PG8_MMA(0, 0, At, B0); PG8_MMA(0, 1, At, B1); PG8_BAR; PG8_SCHED;
	s_setprio 1
	s_waitcnt lgkmcnt(0)
	v_mfma_f32_16x16x32_bf16 v[60:63], v[128:131], v[176:179], v[60:63]
	v_mfma_f32_16x16x32_bf16 v[56:59], v[136:139], v[176:179], v[56:59]
	v_mfma_f32_16x16x32_bf16 v[44:47], v[128:131], v[196:199], v[44:47]
	v_mfma_f32_16x16x32_bf16 v[40:43], v[136:139], v[196:199], v[40:43]
	v_mfma_f32_16x16x32_bf16 v[28:31], v[128:131], v[204:207], v[28:31]
	v_mfma_f32_16x16x32_bf16 v[24:27], v[136:139], v[204:207], v[24:27]
	v_mfma_f32_16x16x32_bf16 v[12:15], v[128:131], v[212:215], v[12:15]
	v_mfma_f32_16x16x32_bf16 v[8:11], v[136:139], v[212:215], v[8:11]
	v_mfma_f32_16x16x32_bf16 v[60:63], v[132:135], v[180:183], v[60:63]
	v_mfma_f32_16x16x32_bf16 v[56:59], v[140:143], v[180:183], v[56:59]
	v_mfma_f32_16x16x32_bf16 v[44:47], v[132:135], v[200:203], v[44:47]
	v_mfma_f32_16x16x32_bf16 v[40:43], v[140:143], v[200:203], v[40:43]
	v_mfma_f32_16x16x32_bf16 v[28:31], v[132:135], v[208:211], v[28:31]
	v_mfma_f32_16x16x32_bf16 v[24:27], v[140:143], v[208:211], v[24:27]
	v_mfma_f32_16x16x32_bf16 v[12:15], v[132:135], v[216:219], v[12:15]
	v_mfma_f32_16x16x32_bf16 v[8:11], v[140:143], v[216:219], v[8:11]
	s_setprio 0
	s_setprio 1
	v_mfma_f32_16x16x32_bf16 v[52:55], v[144:147], v[176:179], v[52:55]
	v_mfma_f32_16x16x32_bf16 v[48:51], v[168:171], v[176:179], v[48:51]
	v_mfma_f32_16x16x32_bf16 v[36:39], v[144:147], v[196:199], v[36:39]
	v_mfma_f32_16x16x32_bf16 v[32:35], v[168:171], v[196:199], v[32:35]
	v_mfma_f32_16x16x32_bf16 v[20:23], v[144:147], v[204:207], v[20:23]
	v_mfma_f32_16x16x32_bf16 v[16:19], v[168:171], v[204:207], v[16:19]
	v_mfma_f32_16x16x32_bf16 v[4:7], v[144:147], v[212:215], v[4:7]
	v_mfma_f32_16x16x32_bf16 v[0:3], v[168:171], v[212:215], v[0:3]
	v_mfma_f32_16x16x32_bf16 v[52:55], v[148:151], v[180:183], v[52:55]
	v_mfma_f32_16x16x32_bf16 v[48:51], v[172:175], v[180:183], v[48:51]
	v_mfma_f32_16x16x32_bf16 v[36:39], v[148:151], v[200:203], v[36:39]
	v_mfma_f32_16x16x32_bf16 v[32:35], v[172:175], v[200:203], v[32:35]
	v_mfma_f32_16x16x32_bf16 v[20:23], v[148:151], v[208:211], v[20:23]
	v_mfma_f32_16x16x32_bf16 v[16:19], v[172:175], v[208:211], v[16:19]
	v_mfma_f32_16x16x32_bf16 v[4:7], v[148:151], v[216:219], v[4:7]
	v_mfma_f32_16x16x32_bf16 v[0:3], v[172:175], v[216:219], v[0:3]
	s_barrier
	s_setprio 0
	s_add_i32 s58, 0, 0x18000
	s_add_i32 s59, 0, 0x1c000
	v_add_u32_e32 v140, s58, v189
	v_add_u32_e32 v172, s59, v189
	ds_read_b128 v[128:131], v140
	ds_read_b128 v[132:135], v140 offset:1024
	ds_read_b128 v[136:139], v140 offset:2048
	ds_read_b128 v[140:143], v140 offset:3072
	ds_read_b128 v[144:147], v172
	ds_read_b128 v[148:151], v172 offset:1024
	ds_read_b128 v[168:171], v172 offset:2048
	ds_read_b128 v[172:175], v172 offset:3072
	s_add_u32 s36, s36, 0x40000
	s_addc_u32 s37, s37, 0
	s_mov_b32 m0, s41
	v_lshl_add_u64 v[226:227], s[36:37], 0, v[152:153]
	ds_read_b128 v[176:179], v193 offset:32768
	ds_read_b128 v[180:183], v193 offset:33792
	ds_read_b128 v[196:199], v193 offset:34816
	ds_read_b128 v[200:203], v193 offset:35840
	ds_read_b128 v[204:207], v193 offset:36864
	ds_read_b128 v[208:211], v193 offset:37888
	ds_read_b128 v[212:215], v193 offset:38912
	ds_read_b128 v[216:219], v193 offset:39936
	global_load_lds_dwordx4 v[226:227], off
	v_lshl_add_u64 v[226:227], s[36:37], 0, v[156:157]
	s_mov_b32 m0, s42
	s_nop 0
	global_load_lds_dwordx4 v[226:227], off
	s_waitcnt vmcnt(8)
	s_waitcnt lgkmcnt(0)
	s_barrier
	s_setprio 1
	s_waitcnt lgkmcnt(0)
	v_mfma_f32_16x16x32_bf16 v[124:127], v[128:131], v[176:179], v[124:127]
	v_mfma_f32_16x16x32_bf16 v[120:123], v[136:139], v[176:179], v[120:123]
	v_mfma_f32_16x16x32_bf16 v[108:111], v[128:131], v[196:199], v[108:111]
	v_mfma_f32_16x16x32_bf16 v[104:107], v[136:139], v[196:199], v[104:107]
	v_mfma_f32_16x16x32_bf16 v[92:95], v[128:131], v[204:207], v[92:95]
	v_mfma_f32_16x16x32_bf16 v[88:91], v[136:139], v[204:207], v[88:91]
	v_mfma_f32_16x16x32_bf16 v[76:79], v[128:131], v[212:215], v[76:79]
	v_mfma_f32_16x16x32_bf16 v[72:75], v[136:139], v[212:215], v[72:75]
	v_mfma_f32_16x16x32_bf16 v[124:127], v[132:135], v[180:183], v[124:127]
	v_mfma_f32_16x16x32_bf16 v[120:123], v[140:143], v[180:183], v[120:123]
	v_mfma_f32_16x16x32_bf16 v[108:111], v[132:135], v[200:203], v[108:111]
	v_mfma_f32_16x16x32_bf16 v[104:107], v[140:143], v[200:203], v[104:107]
	v_mfma_f32_16x16x32_bf16 v[92:95], v[132:135], v[208:211], v[92:95]
	v_mfma_f32_16x16x32_bf16 v[88:91], v[140:143], v[208:211], v[88:91]
	v_mfma_f32_16x16x32_bf16 v[76:79], v[132:135], v[216:219], v[76:79]
	v_mfma_f32_16x16x32_bf16 v[72:75], v[140:143], v[216:219], v[72:75]
	s_setprio 0
	s_setprio 1
	v_mfma_f32_16x16x32_bf16 v[116:119], v[144:147], v[176:179], v[116:119]
	v_mfma_f32_16x16x32_bf16 v[112:115], v[168:171], v[176:179], v[112:115]
	v_mfma_f32_16x16x32_bf16 v[100:103], v[144:147], v[196:199], v[100:103]
	v_mfma_f32_16x16x32_bf16 v[96:99], v[168:171], v[196:199], v[96:99]
	v_mfma_f32_16x16x32_bf16 v[84:87], v[144:147], v[204:207], v[84:87]
	v_mfma_f32_16x16x32_bf16 v[80:83], v[168:171], v[204:207], v[80:83]
	v_mfma_f32_16x16x32_bf16 v[68:71], v[144:147], v[212:215], v[68:71]
	v_mfma_f32_16x16x32_bf16 v[64:67], v[168:171], v[212:215], v[64:67]
	v_mfma_f32_16x16x32_bf16 v[116:119], v[148:151], v[180:183], v[116:119]
	v_mfma_f32_16x16x32_bf16 v[112:115], v[172:175], v[180:183], v[112:115]
	v_mfma_f32_16x16x32_bf16 v[100:103], v[148:151], v[200:203], v[100:103]
	v_mfma_f32_16x16x32_bf16 v[96:99], v[172:175], v[200:203], v[96:99]
	v_mfma_f32_16x16x32_bf16 v[84:87], v[148:151], v[208:211], v[84:87]
	v_mfma_f32_16x16x32_bf16 v[80:83], v[172:175], v[208:211], v[80:83]
	v_mfma_f32_16x16x32_bf16 v[68:71], v[148:151], v[216:219], v[68:71]
	v_mfma_f32_16x16x32_bf16 v[64:67], v[172:175], v[216:219], v[64:67]
	s_barrier
; #define PG8_STAGE(bufoff, gbase, voff) do { _Pragma("unroll") for (int _i = 0; _i < 2; ++_i) \
;         __builtin_amdgcn_global_load_lds((const unsigned*)((const char*)(gbase) + (voff)[_i]), (PG8_LAS unsigned*)(lds + (bufoff) + ldsw + _i * 8192), 16, 0, 0); } while (0)
; #define PG8_LDA(dst, b, h) do { _Pragma("unroll") for (int m = 0; m < 4; ++m) _Pragma("unroll") for (int k = 0; k < 2; ++k) dst[m][k] = *(const PG8_LAS bf16x8*)(lds + PG8_SA(b, h) + aoff + m * 2048 + k * 1024); } while (0)
; #define PG8_MMA(ai, bj, At, Bt) do { __builtin_amdgcn_s_setprio(1); _Pragma("unroll") for (int m = 0; m < 4; ++m) _Pragma("unroll") for (int n = 0; n < 2; ++n) _Pragma("unroll") for (int k = 0; k < 2; ++k) \
;         acc[ai][bj][m][n] = __builtin_amdgcn_mfma_f32_16x16x32_bf16(Bt[n][k], At[m][k], acc[ai][bj][m][n], 0, 0, 0); __builtin_amdgcn_s_setprio(0); } while (0)
; #define PG8_WAIT_V(n) asm volatile("s_waitcnt vmcnt(" #n ")" ::: "memory")
; #define PG8_WAIT_L(n) asm volatile("s_waitcnt lgkmcnt(" #n ")" ::: "memory")
; #define PG8_BAR __builtin_amdgcn_s_barrier()
; #define PG8_SCHED __builtin_amdgcn_sched_barrier(0)
; template <class Epi, class Sched, bool ALIGN_EPI = false, bool SP2 = false>
; __device__ __forceinline__ void gemm_phase(PG8_LAS unsigned char* lds, const Gemm g, const Sched& S, const Epi& E) {
;     ...
;             PG8_LDA(At, 1, 1); PG8_STAGE(PG8_SB(1, 0), b3, voffB); PG8_STAGE(PG8_SB(1, 1), b3 + hstepB, voffB); PG8_STAGE(PG8_SA(1, 0), a3, voffA);
;             PG8_WAIT_V(8); PG8_WAIT_L(0); PG8_BAR; PG8_MMA(1, 0, At, B0); PG8_MMA(1, 1, At, B1); PG8_BAR; PG8_SCHED;
;     ...
;         if constexpr (ALIGN_EPI) { if (wr == 0) PG8_BAR; }
	s_setprio 0
	s_add_i32 s36, s58, s39
	v_lshl_add_u64 v[184:185], v[184:185], 0, s[14:15]
	s_mov_b32 m0, s36
	ds_read_b128 v[176:179], v193 offset:49152
	ds_read_b128 v[180:183], v193 offset:50176
	ds_read_b128 v[196:199], v193 offset:51200
	ds_read_b128 v[200:203], v193 offset:52224
	ds_read_b128 v[204:207], v193 offset:53248
	ds_read_b128 v[208:211], v193 offset:54272
	ds_read_b128 v[212:215], v193 offset:55296
	ds_read_b128 v[216:219], v193 offset:56320
	global_load_lds_dwordx4 v[184:185], off
	s_add_i32 m0, s36, 0x2000
	s_add_u32 s34, s34, 0x40080
	v_lshl_add_u64 v[184:185], v[220:221], 0, s[14:15]
	s_addc_u32 s35, s35, 0
	s_add_i32 s36, s59, s39
	global_load_lds_dwordx4 v[184:185], off
	v_lshl_add_u64 v[184:185], s[34:35], 0, v[154:155]
	s_mov_b32 m0, s36
	s_nop 0
	global_load_lds_dwordx4 v[184:185], off
	v_lshl_add_u64 v[184:185], s[34:35], 0, v[158:159]
	s_add_i32 m0, s36, 0x2000
	s_nop 0
	global_load_lds_dwordx4 v[184:185], off
	v_lshl_add_u64 v[184:185], v[222:223], 0, s[14:15]
	s_mov_b32 m0, s44
	s_nop 0
	global_load_lds_dwordx4 v[184:185], off
	v_lshl_add_u64 v[184:185], v[224:225], 0, s[14:15]
	s_mov_b32 m0, s45
	s_nop 0
	global_load_lds_dwordx4 v[184:185], off
	s_waitcnt vmcnt(8)
	s_waitcnt lgkmcnt(0)
	s_barrier
	s_setprio 1
	s_waitcnt lgkmcnt(0)
	v_mfma_f32_16x16x32_bf16 v[60:63], v[128:131], v[176:179], v[60:63]
	v_mfma_f32_16x16x32_bf16 v[56:59], v[136:139], v[176:179], v[56:59]
	v_mfma_f32_16x16x32_bf16 v[44:47], v[128:131], v[196:199], v[44:47]
	v_mfma_f32_16x16x32_bf16 v[40:43], v[136:139], v[196:199], v[40:43]
	v_mfma_f32_16x16x32_bf16 v[28:31], v[128:131], v[204:207], v[28:31]
	v_mfma_f32_16x16x32_bf16 v[24:27], v[136:139], v[204:207], v[24:27]
	v_mfma_f32_16x16x32_bf16 v[12:15], v[128:131], v[212:215], v[12:15]
	v_mfma_f32_16x16x32_bf16 v[8:11], v[136:139], v[212:215], v[8:11]
	v_mfma_f32_16x16x32_bf16 v[60:63], v[132:135], v[180:183], v[60:63]
	v_mfma_f32_16x16x32_bf16 v[56:59], v[140:143], v[180:183], v[56:59]
	v_mfma_f32_16x16x32_bf16 v[44:47], v[132:135], v[200:203], v[44:47]
	v_mfma_f32_16x16x32_bf16 v[40:43], v[140:143], v[200:203], v[40:43]
	v_mfma_f32_16x16x32_bf16 v[28:31], v[132:135], v[208:211], v[28:31]
	v_mfma_f32_16x16x32_bf16 v[24:27], v[140:143], v[208:211], v[24:27]
	v_mfma_f32_16x16x32_bf16 v[12:15], v[132:135], v[216:219], v[12:15]
	v_mfma_f32_16x16x32_bf16 v[8:11], v[140:143], v[216:219], v[8:11]
	s_setprio 0
	s_setprio 1
	v_mfma_f32_16x16x32_bf16 v[52:55], v[144:147], v[176:179], v[52:55]
	v_mfma_f32_16x16x32_bf16 v[48:51], v[168:171], v[176:179], v[48:51]
	v_mfma_f32_16x16x32_bf16 v[36:39], v[144:147], v[196:199], v[36:39]
	v_mfma_f32_16x16x32_bf16 v[32:35], v[168:171], v[196:199], v[32:35]
	v_mfma_f32_16x16x32_bf16 v[20:23], v[144:147], v[204:207], v[20:23]
	v_mfma_f32_16x16x32_bf16 v[16:19], v[168:171], v[204:207], v[16:19]
	v_mfma_f32_16x16x32_bf16 v[4:7], v[144:147], v[212:215], v[4:7]
	v_mfma_f32_16x16x32_bf16 v[0:3], v[168:171], v[212:215], v[0:3]
	v_mfma_f32_16x16x32_bf16 v[52:55], v[148:151], v[180:183], v[52:55]
	v_mfma_f32_16x16x32_bf16 v[48:51], v[172:175], v[180:183], v[48:51]
	v_mfma_f32_16x16x32_bf16 v[36:39], v[148:151], v[200:203], v[36:39]
	v_mfma_f32_16x16x32_bf16 v[32:35], v[172:175], v[200:203], v[32:35]
	v_mfma_f32_16x16x32_bf16 v[20:23], v[148:151], v[208:211], v[20:23]
	v_mfma_f32_16x16x32_bf16 v[16:19], v[172:175], v[208:211], v[16:19]
	v_mfma_f32_16x16x32_bf16 v[4:7], v[148:151], v[216:219], v[4:7]
	v_mfma_f32_16x16x32_bf16 v[0:3], v[172:175], v[216:219], v[0:3]
	s_barrier
	s_setprio 0
	s_add_i32 s74, s74, 2
	s_add_u32 s30, s30, 0x100
	s_addc_u32 s31, s31, 0
	s_add_u32 s69, s69, 0x100
	s_addc_u32 s73, s73, 0
	s_cmp_gt_u32 s74, 13
	s_cbranch_scc0 .LBB0_971
	s_and_b64 vcc, exec, s[16:17]
	s_cbranch_vccz .LBB0_974
	s_barrier

; #define PG8_STAGE(bufoff, gbase, voff) do { _Pragma("unroll") for (int _i = 0; _i < 2; ++_i) \
;         __builtin_amdgcn_global_load_lds((const unsigned*)((const char*)(gbase) + (voff)[_i]), (PG8_LAS unsigned*)(lds + (bufoff) + ldsw + _i * 8192), 16, 0, 0); } while (0)
; #define PG8_LDA(dst, b, h) do { _Pragma("unroll") for (int m = 0; m < 4; ++m) _Pragma("unroll") for (int k = 0; k < 2; ++k) dst[m][k] = *(const PG8_LAS bf16x8*)(lds + PG8_SA(b, h) + aoff + m * 2048 + k * 1024); } while (0)
; #define PG8_LDB(dst, b, h) do { _Pragma("unroll") for (int n = 0; n < 2; ++n) _Pragma("unroll") for (int k = 0; k < 2; ++k) dst[n][k] = *(const PG8_LAS bf16x8*)(lds + PG8_SB(b, h) + boff + n * 2048 + k * 1024); } while (0)
; #define PG8_MMA(ai, bj, At, Bt) do { __builtin_amdgcn_s_setprio(1); _Pragma("unroll") for (int m = 0; m < 4; ++m) _Pragma("unroll") for (int n = 0; n < 2; ++n) _Pragma("unroll") for (int k = 0; k < 2; ++k) \
;         acc[ai][bj][m][n] = __builtin_amdgcn_mfma_f32_16x16x32_bf16(Bt[n][k], At[m][k], acc[ai][bj][m][n], 0, 0, 0); __builtin_amdgcn_s_setprio(0); } while (0)
; #define PG8_WAIT_V(n) asm volatile("s_waitcnt vmcnt(" #n ")" ::: "memory")
; #define PG8_WAIT_L(n) asm volatile("s_waitcnt lgkmcnt(" #n ")" ::: "memory")
; #define PG8_BAR __builtin_amdgcn_s_barrier()
; #define PG8_SCHED __builtin_amdgcn_sched_barrier(0)
; template <class Epi, class Sched, bool ALIGN_EPI = false, bool SP2 = false>
; __device__ __forceinline__ void gemm_phase(PG8_LAS unsigned char* lds, const Gemm g, const Sched& S, const Epi& E) {
;     ...
;         for (int t = 0; t < nt; t += 2) {
;             const bool last = (t == nt - 2);
;             const char* a1 = cA + (size_t)(t + 1) * kstep;
;             const char* a2 = last ? nA : cA + (size_t)(t + 2) * kstep; const char* b2 = last ? nB : cB + (size_t)(t + 2) * kstep;
;             const char* a3 = a2 + kstep; const char* b3 = b2 + kstep;
;             if (last && has_next) S.a_ready(nxt);
;             if constexpr (SP2) {
;             PG8_LDB(B0, 0, 0); PG8_LDB(B1, 0, 1); PG8_SCHED; PG8_LDA(At, 0, 0); PG8_STAGE(PG8_SA(1, 1), a1 + hstepA, voffA);
;             PG8_WAIT_V(8); PG8_WAIT_L(0); PG8_BAR; PG8_MMA(0, 0, At, B0); PG8_MMA(0, 1, At, B1); PG8_BAR; PG8_SCHED;
;             PG8_LDA(At, 0, 1); PG8_STAGE(PG8_SB(0, 0), b2, voffB); PG8_STAGE(PG8_SB(0, 1), b2 + hstepB, voffB); PG8_STAGE(PG8_SA(0, 0), a2, voffA);
.LBB0_1055:
	ds_read_b128 v[144:147], v153
	ds_read_b128 v[158:161], v153 offset:1024
	ds_read_b128 v[162:165], v153 offset:2048
	ds_read_b128 v[166:169], v153 offset:3072
	ds_read_b128 v[170:173], v154
	ds_read_b128 v[174:177], v154 offset:1024
	ds_read_b128 v[178:181], v154 offset:2048
	ds_read_b128 v[182:185], v154 offset:3072
	s_add_u32 s28, s26, 0xfffc0080
	s_addc_u32 s29, s27, -1
	s_cmp_eq_u32 s69, 12
	s_cselect_b32 s31, s19, s29
	s_cselect_b32 s30, s49, s28
	s_cselect_b32 s29, s17, s68
	s_cselect_b32 s28, s66, s67
	v_lshl_add_u64 v[148:149], s[26:27], 0, v[136:137]
	s_add_i32 m0, s25, 0xc000
	ds_read_b128 v[188:191], v155
	ds_read_b128 v[192:195], v155 offset:1024
	ds_read_b128 v[196:199], v155 offset:2048
	ds_read_b128 v[200:203], v155 offset:3072
	ds_read_b128 v[204:207], v155 offset:4096
	ds_read_b128 v[208:211], v155 offset:5120
	ds_read_b128 v[212:215], v155 offset:6144
	ds_read_b128 v[216:219], v155 offset:7168
	global_load_lds_dwordx4 v[148:149], off
	v_lshl_add_u64 v[148:149], s[26:27], 0, v[138:139]
	s_add_i32 m0, s25, 0xe000
	s_nop 0
	global_load_lds_dwordx4 v[148:149], off
	s_waitcnt vmcnt(8)
	s_waitcnt lgkmcnt(0)
	s_barrier
	s_setprio 1
	s_waitcnt lgkmcnt(0)
	v_mfma_f32_16x16x32_bf16 v[116:119], v[144:147], v[188:191], v[116:119]
	v_mfma_f32_16x16x32_bf16 v[112:115], v[162:165], v[188:191], v[112:115]
	v_mfma_f32_16x16x32_bf16 v[108:111], v[144:147], v[196:199], v[108:111]
	v_mfma_f32_16x16x32_bf16 v[100:103], v[162:165], v[196:199], v[100:103]
	v_mfma_f32_16x16x32_bf16 v[92:95], v[144:147], v[204:207], v[92:95]
	v_mfma_f32_16x16x32_bf16 v[84:87], v[162:165], v[204:207], v[84:87]
	v_mfma_f32_16x16x32_bf16 v[76:79], v[144:147], v[212:215], v[76:79]
	v_mfma_f32_16x16x32_bf16 v[68:71], v[162:165], v[212:215], v[68:71]
	v_mfma_f32_16x16x32_bf16 v[116:119], v[158:161], v[192:195], v[116:119]
	v_mfma_f32_16x16x32_bf16 v[112:115], v[166:169], v[192:195], v[112:115]
	v_mfma_f32_16x16x32_bf16 v[108:111], v[158:161], v[200:203], v[108:111]
	v_mfma_f32_16x16x32_bf16 v[100:103], v[166:169], v[200:203], v[100:103]
	v_mfma_f32_16x16x32_bf16 v[92:95], v[158:161], v[208:211], v[92:95]
	v_mfma_f32_16x16x32_bf16 v[84:87], v[166:169], v[208:211], v[84:87]
	v_mfma_f32_16x16x32_bf16 v[76:79], v[158:161], v[216:219], v[76:79]
	v_mfma_f32_16x16x32_bf16 v[68:71], v[166:169], v[216:219], v[68:71]
	s_setprio 0
	s_setprio 1
	v_mfma_f32_16x16x32_bf16 v[124:127], v[170:173], v[188:191], v[124:127]
	v_mfma_f32_16x16x32_bf16 v[120:123], v[178:181], v[188:191], v[120:123]
	v_mfma_f32_16x16x32_bf16 v[104:107], v[170:173], v[196:199], v[104:107]
	v_mfma_f32_16x16x32_bf16 v[96:99], v[178:181], v[196:199], v[96:99]
	v_mfma_f32_16x16x32_bf16 v[88:91], v[170:173], v[204:207], v[88:91]
	v_mfma_f32_16x16x32_bf16 v[80:83], v[178:181], v[204:207], v[80:83]
	v_mfma_f32_16x16x32_bf16 v[72:75], v[170:173], v[212:215], v[72:75]
	v_mfma_f32_16x16x32_bf16 v[64:67], v[178:181], v[212:215], v[64:67]
	v_mfma_f32_16x16x32_bf16 v[124:127], v[174:177], v[192:195], v[124:127]
	v_mfma_f32_16x16x32_bf16 v[120:123], v[182:185], v[192:195], v[120:123]
	v_mfma_f32_16x16x32_bf16 v[104:107], v[174:177], v[200:203], v[104:107]
	v_mfma_f32_16x16x32_bf16 v[96:99], v[182:185], v[200:203], v[96:99]
	v_mfma_f32_16x16x32_bf16 v[88:91], v[174:177], v[208:211], v[88:91]
	v_mfma_f32_16x16x32_bf16 v[80:83], v[182:185], v[208:211], v[80:83]
	v_mfma_f32_16x16x32_bf16 v[72:75], v[174:177], v[216:219], v[72:75]
	v_mfma_f32_16x16x32_bf16 v[64:67], v[182:185], v[216:219], v[64:67]
	s_barrier
	s_setprio 0
	s_add_i32 s58, s45, s35
	v_lshl_add_u64 v[148:149], s[28:29], 0, v[132:133]
	s_mov_b32 m0, s58
	ds_read_b128 v[188:191], v155 offset:16384
	ds_read_b128 v[192:195], v155 offset:17408
	ds_read_b128 v[196:199], v155 offset:18432
	ds_read_b128 v[200:203], v155 offset:19456
	ds_read_b128 v[204:207], v155 offset:20480
	ds_read_b128 v[208:211], v155 offset:21504
	ds_read_b128 v[212:215], v155 offset:22528
	ds_read_b128 v[216:219], v155 offset:23552
	global_load_lds_dwordx4 v[148:149], off
	s_add_i32 m0, s58, 0x2000
	s_add_u32 s58, s28, 0x40000
	v_lshl_add_u64 v[220:221], s[28:29], 0, v[128:129]
	s_addc_u32 s59, s29, 0
	s_add_i32 s73, s46, s35
	global_load_lds_dwordx4 v[220:221], off
	v_lshl_add_u64 v[222:223], s[58:59], 0, v[132:133]
	s_mov_b32 m0, s73
	v_lshl_add_u64 v[224:225], s[30:31], 0, v[130:131]
	global_load_lds_dwordx4 v[222:223], off
	v_lshl_add_u64 v[222:223], s[58:59], 0, v[128:129]
	s_add_i32 m0, s73, 0x2000
	s_nop 0
	global_load_lds_dwordx4 v[222:223], off
	v_lshl_add_u64 v[222:223], s[30:31], 0, v[134:135]
	s_mov_b32 m0, s25
	s_nop 0
	global_load_lds_dwordx4 v[222:223], off
	s_mov_b32 m0, s38
	s_nop 0
	global_load_lds_dwordx4 v[224:225], off
	s_waitcnt vmcnt(8)
	s_waitcnt lgkmcnt(0)
	s_barrier
; #define PG8_STAGE(bufoff, gbase, voff) do { _Pragma("unroll") for (int _i = 0; _i < 2; ++_i) \
;         __builtin_amdgcn_global_load_lds((const unsigned*)((const char*)(gbase) + (voff)[_i]), (PG8_LAS unsigned*)(lds + (bufoff) + ldsw + _i * 8192), 16, 0, 0); } while (0)
; #define PG8_LDA(dst, b, h) do { _Pragma("unroll") for (int m = 0; m < 4; ++m) _Pragma("unroll") for (int k = 0; k < 2; ++k) dst[m][k] = *(const PG8_LAS bf16x8*)(lds + PG8_SA(b, h) + aoff + m * 2048 + k * 1024); } while (0)
; #define PG8_LDB(dst, b, h) do { _Pragma("unroll") for (int n = 0; n < 2; ++n) _Pragma("unroll") for (int k = 0; k < 2; ++k) dst[n][k] = *(const PG8_LAS bf16x8*)(lds + PG8_SB(b, h) + boff + n * 2048 + k * 1024); } while (0)
; #define PG8_MMA(ai, bj, At, Bt) do { __builtin_amdgcn_s_setprio(1); _Pragma("unroll") for (int m = 0; m < 4; ++m) _Pragma("unroll") for (int n = 0; n < 2; ++n) _Pragma("unroll") for (int k = 0; k < 2; ++k) \
;         acc[ai][bj][m][n] = __builtin_amdgcn_mfma_f32_16x16x32_bf16(Bt[n][k], At[m][k], acc[ai][bj][m][n], 0, 0, 0); __builtin_amdgcn_s_setprio(0); } while (0)
; #define PG8_WAIT_V(n) asm volatile("s_waitcnt vmcnt(" #n ")" ::: "memory")
; #define PG8_WAIT_L(n) asm volatile("s_waitcnt lgkmcnt(" #n ")" ::: "memory")
; #define PG8_BAR __builtin_amdgcn_s_barrier()
; #define PG8_SCHED __builtin_amdgcn_sched_barrier(0)
; template <class Epi, class Sched, bool ALIGN_EPI = false, bool SP2 = false>
; __device__ __forceinline__ void gemm_phase(PG8_LAS unsigned char* lds, const Gemm g, const Sched& S, const Epi& E) {
;     ...
;             PG8_WAIT_V(8); PG8_WAIT_L(0); PG8_BAR; PG8_MMA(1, 0, At, B0); PG8_MMA(1, 1, At, B1); PG8_BAR; PG8_SCHED;
;             PG8_LDB(B0, 1, 0); PG8_LDB(B1, 1, 1); PG8_SCHED; PG8_LDA(At, 1, 0); PG8_STAGE(PG8_SA(0, 1), a2 + hstepA, voffA);
;             PG8_WAIT_V(8); PG8_WAIT_L(0); PG8_BAR; PG8_MMA(0, 0, At, B0); PG8_MMA(0, 1, At, B1); PG8_BAR; PG8_SCHED;
	s_setprio 1
	s_waitcnt lgkmcnt(0)
	v_mfma_f32_16x16x32_bf16 v[60:63], v[144:147], v[188:191], v[60:63]
	v_mfma_f32_16x16x32_bf16 v[52:55], v[162:165], v[188:191], v[52:55]
	v_mfma_f32_16x16x32_bf16 v[44:47], v[144:147], v[196:199], v[44:47]
	v_mfma_f32_16x16x32_bf16 v[36:39], v[162:165], v[196:199], v[36:39]
	v_mfma_f32_16x16x32_bf16 v[28:31], v[144:147], v[204:207], v[28:31]
	v_mfma_f32_16x16x32_bf16 v[20:23], v[162:165], v[204:207], v[20:23]
	v_mfma_f32_16x16x32_bf16 v[12:15], v[144:147], v[212:215], v[12:15]
	v_mfma_f32_16x16x32_bf16 v[4:7], v[162:165], v[212:215], v[4:7]
	v_mfma_f32_16x16x32_bf16 v[60:63], v[158:161], v[192:195], v[60:63]
	v_mfma_f32_16x16x32_bf16 v[52:55], v[166:169], v[192:195], v[52:55]
	v_mfma_f32_16x16x32_bf16 v[44:47], v[158:161], v[200:203], v[44:47]
	v_mfma_f32_16x16x32_bf16 v[36:39], v[166:169], v[200:203], v[36:39]
	v_mfma_f32_16x16x32_bf16 v[28:31], v[158:161], v[208:211], v[28:31]
	v_mfma_f32_16x16x32_bf16 v[20:23], v[166:169], v[208:211], v[20:23]
	v_mfma_f32_16x16x32_bf16 v[12:15], v[158:161], v[216:219], v[12:15]
	v_mfma_f32_16x16x32_bf16 v[4:7], v[166:169], v[216:219], v[4:7]
	s_setprio 0
	s_setprio 1
	v_mfma_f32_16x16x32_bf16 v[56:59], v[170:173], v[188:191], v[56:59]
	v_mfma_f32_16x16x32_bf16 v[48:51], v[178:181], v[188:191], v[48:51]
	v_mfma_f32_16x16x32_bf16 v[40:43], v[170:173], v[196:199], v[40:43]
	v_mfma_f32_16x16x32_bf16 v[32:35], v[178:181], v[196:199], v[32:35]
	v_mfma_f32_16x16x32_bf16 v[24:27], v[170:173], v[204:207], v[24:27]
	v_mfma_f32_16x16x32_bf16 v[16:19], v[178:181], v[204:207], v[16:19]
	v_mfma_f32_16x16x32_bf16 v[8:11], v[170:173], v[212:215], v[8:11]
	v_mfma_f32_16x16x32_bf16 v[0:3], v[178:181], v[212:215], v[0:3]
	v_mfma_f32_16x16x32_bf16 v[56:59], v[174:177], v[192:195], v[56:59]
	v_mfma_f32_16x16x32_bf16 v[48:51], v[182:185], v[192:195], v[48:51]
	v_mfma_f32_16x16x32_bf16 v[40:43], v[174:177], v[200:203], v[40:43]
	v_mfma_f32_16x16x32_bf16 v[32:35], v[182:185], v[200:203], v[32:35]
	v_mfma_f32_16x16x32_bf16 v[24:27], v[174:177], v[208:211], v[24:27]
	v_mfma_f32_16x16x32_bf16 v[16:19], v[182:185], v[208:211], v[16:19]
	v_mfma_f32_16x16x32_bf16 v[8:11], v[174:177], v[216:219], v[8:11]
	v_mfma_f32_16x16x32_bf16 v[0:3], v[182:185], v[216:219], v[0:3]
	s_barrier
	s_setprio 0
	s_add_i32 s58, 0, 0x18000
	v_add_u32_e32 v157, s58, v151
	s_add_i32 s59, 0, 0x1c000
	ds_read_b128 v[144:147], v157
	ds_read_b128 v[158:161], v157 offset:1024
	ds_read_b128 v[162:165], v157 offset:2048
	ds_read_b128 v[166:169], v157 offset:3072
	v_add_u32_e32 v157, s59, v151
	ds_read_b128 v[170:173], v157
	ds_read_b128 v[174:177], v157 offset:1024
	ds_read_b128 v[178:181], v157 offset:2048
	ds_read_b128 v[182:185], v157 offset:3072
	s_add_u32 s30, s30, 0x40000
	s_addc_u32 s31, s31, 0
	s_mov_b32 m0, s39
	v_lshl_add_u64 v[226:227], s[30:31], 0, v[134:135]
	ds_read_b128 v[188:191], v155 offset:32768
	ds_read_b128 v[192:195], v155 offset:33792
	ds_read_b128 v[196:199], v155 offset:34816
	ds_read_b128 v[200:203], v155 offset:35840
	ds_read_b128 v[204:207], v155 offset:36864
	ds_read_b128 v[208:211], v155 offset:37888
	ds_read_b128 v[212:215], v155 offset:38912
	ds_read_b128 v[216:219], v155 offset:39936
	global_load_lds_dwordx4 v[226:227], off
	v_lshl_add_u64 v[226:227], s[30:31], 0, v[130:131]
	s_mov_b32 m0, s40
	s_nop 0
	global_load_lds_dwordx4 v[226:227], off
	s_waitcnt vmcnt(8)
	s_waitcnt lgkmcnt(0)
	s_barrier
	s_setprio 1
	s_waitcnt lgkmcnt(0)
	v_mfma_f32_16x16x32_bf16 v[116:119], v[144:147], v[188:191], v[116:119]
	v_mfma_f32_16x16x32_bf16 v[112:115], v[162:165], v[188:191], v[112:115]
	v_mfma_f32_16x16x32_bf16 v[108:111], v[144:147], v[196:199], v[108:111]
	v_mfma_f32_16x16x32_bf16 v[100:103], v[162:165], v[196:199], v[100:103]
	v_mfma_f32_16x16x32_bf16 v[92:95], v[144:147], v[204:207], v[92:95]
	v_mfma_f32_16x16x32_bf16 v[84:87], v[162:165], v[204:207], v[84:87]
	v_mfma_f32_16x16x32_bf16 v[76:79], v[144:147], v[212:215], v[76:79]
	v_mfma_f32_16x16x32_bf16 v[68:71], v[162:165], v[212:215], v[68:71]
	v_mfma_f32_16x16x32_bf16 v[116:119], v[158:161], v[192:195], v[116:119]
	v_mfma_f32_16x16x32_bf16 v[112:115], v[166:169], v[192:195], v[112:115]
	v_mfma_f32_16x16x32_bf16 v[108:111], v[158:161], v[200:203], v[108:111]
	v_mfma_f32_16x16x32_bf16 v[100:103], v[166:169], v[200:203], v[100:103]
	v_mfma_f32_16x16x32_bf16 v[92:95], v[158:161], v[208:211], v[92:95]
	v_mfma_f32_16x16x32_bf16 v[84:87], v[166:169], v[208:211], v[84:87]
	v_mfma_f32_16x16x32_bf16 v[76:79], v[158:161], v[216:219], v[76:79]
	v_mfma_f32_16x16x32_bf16 v[68:71], v[166:169], v[216:219], v[68:71]
	s_setprio 0
	s_setprio 1
	v_mfma_f32_16x16x32_bf16 v[124:127], v[170:173], v[188:191], v[124:127]
	v_mfma_f32_16x16x32_bf16 v[120:123], v[178:181], v[188:191], v[120:123]
	v_mfma_f32_16x16x32_bf16 v[104:107], v[170:173], v[196:199], v[104:107]
	v_mfma_f32_16x16x32_bf16 v[96:99], v[178:181], v[196:199], v[96:99]
	v_mfma_f32_16x16x32_bf16 v[88:91], v[170:173], v[204:207], v[88:91]
	v_mfma_f32_16x16x32_bf16 v[80:83], v[178:181], v[204:207], v[80:83]
	v_mfma_f32_16x16x32_bf16 v[72:75], v[170:173], v[212:215], v[72:75]
	v_mfma_f32_16x16x32_bf16 v[64:67], v[178:181], v[212:215], v[64:67]
	v_mfma_f32_16x16x32_bf16 v[124:127], v[174:177], v[192:195], v[124:127]
	v_mfma_f32_16x16x32_bf16 v[120:123], v[182:185], v[192:195], v[120:123]
	v_mfma_f32_16x16x32_bf16 v[104:107], v[174:177], v[200:203], v[104:107]
	v_mfma_f32_16x16x32_bf16 v[96:99], v[182:185], v[200:203], v[96:99]
	v_mfma_f32_16x16x32_bf16 v[88:91], v[174:177], v[208:211], v[88:91]
	v_mfma_f32_16x16x32_bf16 v[80:83], v[182:185], v[208:211], v[80:83]
	v_mfma_f32_16x16x32_bf16 v[72:75], v[174:177], v[216:219], v[72:75]
	v_mfma_f32_16x16x32_bf16 v[64:67], v[182:185], v[216:219], v[64:67]
	s_barrier
; #define PG8_STAGE(bufoff, gbase, voff) do { _Pragma("unroll") for (int _i = 0; _i < 2; ++_i) \
;         __builtin_amdgcn_global_load_lds((const unsigned*)((const char*)(gbase) + (voff)[_i]), (PG8_LAS unsigned*)(lds + (bufoff) + ldsw + _i * 8192), 16, 0, 0); } while (0)
; #define PG8_LDA(dst, b, h) do { _Pragma("unroll") for (int m = 0; m < 4; ++m) _Pragma("unroll") for (int k = 0; k < 2; ++k) dst[m][k] = *(const PG8_LAS bf16x8*)(lds + PG8_SA(b, h) + aoff + m * 2048 + k * 1024); } while (0)
; #define PG8_MMA(ai, bj, At, Bt) do { __builtin_amdgcn_s_setprio(1); _Pragma("unroll") for (int m = 0; m < 4; ++m) _Pragma("unroll") for (int n = 0; n < 2; ++n) _Pragma("unroll") for (int k = 0; k < 2; ++k) \
;         acc[ai][bj][m][n] = __builtin_amdgcn_mfma_f32_16x16x32_bf16(Bt[n][k], At[m][k], acc[ai][bj][m][n], 0, 0, 0); __builtin_amdgcn_s_setprio(0); } while (0)
; #define PG8_WAIT_V(n) asm volatile("s_waitcnt vmcnt(" #n ")" ::: "memory")
; #define PG8_WAIT_L(n) asm volatile("s_waitcnt lgkmcnt(" #n ")" ::: "memory")
; #define PG8_BAR __builtin_amdgcn_s_barrier()
; #define PG8_SCHED __builtin_amdgcn_sched_barrier(0)
; template <class Epi, class Sched, bool ALIGN_EPI = false, bool SP2 = false>
; __device__ __forceinline__ void gemm_phase(PG8_LAS unsigned char* lds, const Gemm g, const Sched& S, const Epi& E) {
;     ...
;             PG8_LDA(At, 1, 1); PG8_STAGE(PG8_SB(1, 0), b3, voffB); PG8_STAGE(PG8_SB(1, 1), b3 + hstepB, voffB); PG8_STAGE(PG8_SA(1, 0), a3, voffA);
;             PG8_WAIT_V(8); PG8_WAIT_L(0); PG8_BAR; PG8_MMA(1, 0, At, B0); PG8_MMA(1, 1, At, B1); PG8_BAR; PG8_SCHED;
;     ...
;         if constexpr (ALIGN_EPI) { if (wr == 0) PG8_BAR; }
	s_setprio 0
	s_add_i32 s30, s58, s35
	v_lshl_add_u64 v[148:149], v[148:149], 0, s[12:13]
	s_mov_b32 m0, s30
	ds_read_b128 v[188:191], v155 offset:49152
	ds_read_b128 v[192:195], v155 offset:50176
	ds_read_b128 v[196:199], v155 offset:51200
	ds_read_b128 v[200:203], v155 offset:52224
	ds_read_b128 v[204:207], v155 offset:53248
	ds_read_b128 v[208:211], v155 offset:54272
	ds_read_b128 v[212:215], v155 offset:55296
	ds_read_b128 v[216:219], v155 offset:56320
	global_load_lds_dwordx4 v[148:149], off
	s_add_i32 m0, s30, 0x2000
	s_add_u32 s28, s28, 0x40080
	v_lshl_add_u64 v[148:149], v[220:221], 0, s[12:13]
	s_addc_u32 s29, s29, 0
	s_add_i32 s30, s59, s35
	global_load_lds_dwordx4 v[148:149], off
	v_lshl_add_u64 v[148:149], s[28:29], 0, v[132:133]
	s_mov_b32 m0, s30
	s_nop 0
	global_load_lds_dwordx4 v[148:149], off
	v_lshl_add_u64 v[148:149], s[28:29], 0, v[128:129]
	s_add_i32 m0, s30, 0x2000
	s_nop 0
	global_load_lds_dwordx4 v[148:149], off
	v_lshl_add_u64 v[148:149], v[222:223], 0, s[12:13]
	s_mov_b32 m0, s42
	s_nop 0
	global_load_lds_dwordx4 v[148:149], off
	v_lshl_add_u64 v[148:149], v[224:225], 0, s[12:13]
	s_mov_b32 m0, s43
	s_nop 0
	global_load_lds_dwordx4 v[148:149], off
	s_waitcnt vmcnt(8)
	s_waitcnt lgkmcnt(0)
	s_barrier
	s_setprio 1
	s_waitcnt lgkmcnt(0)
	v_mfma_f32_16x16x32_bf16 v[60:63], v[144:147], v[188:191], v[60:63]
	v_mfma_f32_16x16x32_bf16 v[52:55], v[162:165], v[188:191], v[52:55]
	v_mfma_f32_16x16x32_bf16 v[44:47], v[144:147], v[196:199], v[44:47]
	v_mfma_f32_16x16x32_bf16 v[36:39], v[162:165], v[196:199], v[36:39]
	v_mfma_f32_16x16x32_bf16 v[28:31], v[144:147], v[204:207], v[28:31]
	v_mfma_f32_16x16x32_bf16 v[20:23], v[162:165], v[204:207], v[20:23]
	v_mfma_f32_16x16x32_bf16 v[12:15], v[144:147], v[212:215], v[12:15]
	v_mfma_f32_16x16x32_bf16 v[4:7], v[162:165], v[212:215], v[4:7]
	v_mfma_f32_16x16x32_bf16 v[60:63], v[158:161], v[192:195], v[60:63]
	v_mfma_f32_16x16x32_bf16 v[52:55], v[166:169], v[192:195], v[52:55]
	v_mfma_f32_16x16x32_bf16 v[44:47], v[158:161], v[200:203], v[44:47]
	v_mfma_f32_16x16x32_bf16 v[36:39], v[166:169], v[200:203], v[36:39]
	v_mfma_f32_16x16x32_bf16 v[28:31], v[158:161], v[208:211], v[28:31]
	v_mfma_f32_16x16x32_bf16 v[20:23], v[166:169], v[208:211], v[20:23]
	v_mfma_f32_16x16x32_bf16 v[12:15], v[158:161], v[216:219], v[12:15]
	v_mfma_f32_16x16x32_bf16 v[4:7], v[166:169], v[216:219], v[4:7]
	s_setprio 0
	s_setprio 1
	v_mfma_f32_16x16x32_bf16 v[56:59], v[170:173], v[188:191], v[56:59]
	v_mfma_f32_16x16x32_bf16 v[48:51], v[178:181], v[188:191], v[48:51]
	v_mfma_f32_16x16x32_bf16 v[40:43], v[170:173], v[196:199], v[40:43]
	v_mfma_f32_16x16x32_bf16 v[32:35], v[178:181], v[196:199], v[32:35]
	v_mfma_f32_16x16x32_bf16 v[24:27], v[170:173], v[204:207], v[24:27]
	v_mfma_f32_16x16x32_bf16 v[16:19], v[178:181], v[204:207], v[16:19]
	v_mfma_f32_16x16x32_bf16 v[8:11], v[170:173], v[212:215], v[8:11]
	v_mfma_f32_16x16x32_bf16 v[0:3], v[178:181], v[212:215], v[0:3]
	v_mfma_f32_16x16x32_bf16 v[56:59], v[174:177], v[192:195], v[56:59]
	v_mfma_f32_16x16x32_bf16 v[48:51], v[182:185], v[192:195], v[48:51]
	v_mfma_f32_16x16x32_bf16 v[40:43], v[174:177], v[200:203], v[40:43]
	v_mfma_f32_16x16x32_bf16 v[32:35], v[182:185], v[200:203], v[32:35]
	v_mfma_f32_16x16x32_bf16 v[24:27], v[174:177], v[208:211], v[24:27]
	v_mfma_f32_16x16x32_bf16 v[16:19], v[182:185], v[208:211], v[16:19]
	v_mfma_f32_16x16x32_bf16 v[8:11], v[174:177], v[216:219], v[8:11]
	v_mfma_f32_16x16x32_bf16 v[0:3], v[182:185], v[216:219], v[0:3]
	s_barrier
	s_setprio 0
	s_add_i32 s69, s69, 2
	s_add_u32 s26, s26, 0x100
	s_addc_u32 s27, s27, 0
	s_add_u32 s67, s67, 0x100
	s_addc_u32 s68, s68, 0
	s_cmp_gt_u32 s69, 13
	s_cbranch_scc0 .LBB0_1055
	s_and_b64 vcc, exec, s[14:15]
	s_cbranch_vccz .LBB0_1058
	s_barrier

; #define PG8_STAGE(bufoff, gbase, voff) do { _Pragma("unroll") for (int _i = 0; _i < 2; ++_i) \
;         __builtin_amdgcn_global_load_lds((const unsigned*)((const char*)(gbase) + (voff)[_i]), (PG8_LAS unsigned*)(lds + (bufoff) + ldsw + _i * 8192), 16, 0, 0); } while (0)
; #define PG8_LDA(dst, b, h) do { _Pragma("unroll") for (int m = 0; m < 4; ++m) _Pragma("unroll") for (int k = 0; k < 2; ++k) dst[m][k] = *(const PG8_LAS bf16x8*)(lds + PG8_SA(b, h) + aoff + m * 2048 + k * 1024); } while (0)
; #define PG8_LDB(dst, b, h) do { _Pragma("unroll") for (int n = 0; n < 2; ++n) _Pragma("unroll") for (int k = 0; k < 2; ++k) dst[n][k] = *(const PG8_LAS bf16x8*)(lds + PG8_SB(b, h) + boff + n * 2048 + k * 1024); } while (0)
; #define PG8_MMA(ai, bj, At, Bt) do { __builtin_amdgcn_s_setprio(1); _Pragma("unroll") for (int m = 0; m < 4; ++m) _Pragma("unroll") for (int n = 0; n < 2; ++n) _Pragma("unroll") for (int k = 0; k < 2; ++k) \
;         acc[ai][bj][m][n] = __builtin_amdgcn_mfma_f32_16x16x32_bf16(Bt[n][k], At[m][k], acc[ai][bj][m][n], 0, 0, 0); __builtin_amdgcn_s_setprio(0); } while (0)
; #define PG8_WAIT_V(n) asm volatile("s_waitcnt vmcnt(" #n ")" ::: "memory")
; #define PG8_WAIT_L(n) asm volatile("s_waitcnt lgkmcnt(" #n ")" ::: "memory")
; #define PG8_BAR __builtin_amdgcn_s_barrier()
; #define PG8_SCHED __builtin_amdgcn_sched_barrier(0)
; template <class Epi, class Sched, bool ALIGN_EPI = false, bool SP2 = false>
; __device__ __forceinline__ void gemm_phase(PG8_LAS unsigned char* lds, const Gemm g, const Sched& S, const Epi& E) {
;     ...
;         for (int t = 0; t < nt; t += 2) {
;             const bool last = (t == nt - 2);
;             const char* a1 = cA + (size_t)(t + 1) * kstep;
;             const char* a2 = last ? nA : cA + (size_t)(t + 2) * kstep; const char* b2 = last ? nB : cB + (size_t)(t + 2) * kstep;
;             const char* a3 = a2 + kstep; const char* b3 = b2 + kstep;
;             if (last && has_next) S.a_ready(nxt);
;             if constexpr (SP2) {
;             PG8_LDB(B0, 0, 0); PG8_LDB(B1, 0, 1); PG8_SCHED; PG8_LDA(At, 0, 0); PG8_STAGE(PG8_SA(1, 1), a1 + hstepA, voffA);
;             PG8_WAIT_V(8); PG8_WAIT_L(0); PG8_BAR; PG8_MMA(0, 0, At, B0); PG8_MMA(0, 1, At, B1); PG8_BAR; PG8_SCHED;
;             PG8_LDA(At, 0, 1); PG8_STAGE(PG8_SB(0, 0), b2, voffB); PG8_STAGE(PG8_SB(0, 1), b2 + hstepB, voffB); PG8_STAGE(PG8_SA(0, 0), a2, voffA);
.LBB0_1129:
	ds_read_b128 v[128:131], v191
	ds_read_b128 v[132:135], v191 offset:1024
	ds_read_b128 v[136:139], v191 offset:2048
	ds_read_b128 v[140:143], v191 offset:3072
	ds_read_b128 v[144:147], v192
	ds_read_b128 v[148:151], v192 offset:1024
	ds_read_b128 v[168:171], v192 offset:2048
	ds_read_b128 v[172:175], v192 offset:3072
	s_add_u32 s24, s22, 0x100
	s_addc_u32 s25, s23, 0
	s_cmp_eq_u32 s69, 40
	s_cselect_b32 s29, s11, s25
	s_cselect_b32 s28, s10, s24
	s_cselect_b32 s27, s21, s68
	s_cselect_b32 s26, s20, s67
	v_lshl_add_u64 v[184:185], s[22:23], 0, v[160:161]
	s_add_i32 m0, s34, 0xc000
	ds_read_b128 v[176:179], v193
	ds_read_b128 v[180:183], v193 offset:1024
	ds_read_b128 v[196:199], v193 offset:2048
	ds_read_b128 v[200:203], v193 offset:3072
	ds_read_b128 v[204:207], v193 offset:4096
	ds_read_b128 v[208:211], v193 offset:5120
	ds_read_b128 v[212:215], v193 offset:6144
	ds_read_b128 v[216:219], v193 offset:7168
	global_load_lds_dwordx4 v[184:185], off
	v_lshl_add_u64 v[184:185], s[22:23], 0, v[162:163]
	s_add_i32 m0, s34, 0xe000
	s_nop 0
	global_load_lds_dwordx4 v[184:185], off
	s_waitcnt vmcnt(8)
	s_waitcnt lgkmcnt(0)
	s_barrier
	s_setprio 1
	s_waitcnt lgkmcnt(0)
	v_mfma_f32_16x16x32_bf16 v[124:127], v[128:131], v[176:179], v[124:127]
	v_mfma_f32_16x16x32_bf16 v[120:123], v[136:139], v[176:179], v[120:123]
	v_mfma_f32_16x16x32_bf16 v[108:111], v[128:131], v[196:199], v[108:111]
	v_mfma_f32_16x16x32_bf16 v[104:107], v[136:139], v[196:199], v[104:107]
	v_mfma_f32_16x16x32_bf16 v[92:95], v[128:131], v[204:207], v[92:95]
	v_mfma_f32_16x16x32_bf16 v[88:91], v[136:139], v[204:207], v[88:91]
	v_mfma_f32_16x16x32_bf16 v[76:79], v[128:131], v[212:215], v[76:79]
	v_mfma_f32_16x16x32_bf16 v[72:75], v[136:139], v[212:215], v[72:75]
	v_mfma_f32_16x16x32_bf16 v[124:127], v[132:135], v[180:183], v[124:127]
	v_mfma_f32_16x16x32_bf16 v[120:123], v[140:143], v[180:183], v[120:123]
	v_mfma_f32_16x16x32_bf16 v[108:111], v[132:135], v[200:203], v[108:111]
	v_mfma_f32_16x16x32_bf16 v[104:107], v[140:143], v[200:203], v[104:107]
	v_mfma_f32_16x16x32_bf16 v[92:95], v[132:135], v[208:211], v[92:95]
	v_mfma_f32_16x16x32_bf16 v[88:91], v[140:143], v[208:211], v[88:91]
	v_mfma_f32_16x16x32_bf16 v[76:79], v[132:135], v[216:219], v[76:79]
	v_mfma_f32_16x16x32_bf16 v[72:75], v[140:143], v[216:219], v[72:75]
	s_setprio 0
	s_setprio 1
	v_mfma_f32_16x16x32_bf16 v[116:119], v[144:147], v[176:179], v[116:119]
	v_mfma_f32_16x16x32_bf16 v[112:115], v[168:171], v[176:179], v[112:115]
	v_mfma_f32_16x16x32_bf16 v[100:103], v[144:147], v[196:199], v[100:103]
	v_mfma_f32_16x16x32_bf16 v[96:99], v[168:171], v[196:199], v[96:99]
	v_mfma_f32_16x16x32_bf16 v[84:87], v[144:147], v[204:207], v[84:87]
	v_mfma_f32_16x16x32_bf16 v[80:83], v[168:171], v[204:207], v[80:83]
	v_mfma_f32_16x16x32_bf16 v[68:71], v[144:147], v[212:215], v[68:71]
	v_mfma_f32_16x16x32_bf16 v[64:67], v[168:171], v[212:215], v[64:67]
	v_mfma_f32_16x16x32_bf16 v[116:119], v[148:151], v[180:183], v[116:119]
	v_mfma_f32_16x16x32_bf16 v[112:115], v[172:175], v[180:183], v[112:115]
	v_mfma_f32_16x16x32_bf16 v[100:103], v[148:151], v[200:203], v[100:103]
	v_mfma_f32_16x16x32_bf16 v[96:99], v[172:175], v[200:203], v[96:99]
	v_mfma_f32_16x16x32_bf16 v[84:87], v[148:151], v[208:211], v[84:87]
	v_mfma_f32_16x16x32_bf16 v[80:83], v[172:175], v[208:211], v[80:83]
	v_mfma_f32_16x16x32_bf16 v[68:71], v[148:151], v[216:219], v[68:71]
	v_mfma_f32_16x16x32_bf16 v[64:67], v[172:175], v[216:219], v[64:67]
	s_barrier
	s_setprio 0
	s_add_i32 s22, s44, s31
	v_lshl_add_u64 v[184:185], s[26:27], 0, v[154:155]
	s_mov_b32 m0, s22
	ds_read_b128 v[176:179], v193 offset:16384
	ds_read_b128 v[180:183], v193 offset:17408
	ds_read_b128 v[196:199], v193 offset:18432
	ds_read_b128 v[200:203], v193 offset:19456
	ds_read_b128 v[204:207], v193 offset:20480
	ds_read_b128 v[208:211], v193 offset:21504
	ds_read_b128 v[212:215], v193 offset:22528
	ds_read_b128 v[216:219], v193 offset:23552
	global_load_lds_dwordx4 v[184:185], off
	s_add_i32 m0, s22, 0x2000
	s_add_u32 s22, s26, 0xb0000
	v_lshl_add_u64 v[220:221], s[26:27], 0, v[158:159]
	s_addc_u32 s23, s27, 0
	s_add_i32 s58, s45, s31
	global_load_lds_dwordx4 v[220:221], off
	v_lshl_add_u64 v[222:223], s[22:23], 0, v[154:155]
	s_mov_b32 m0, s58
	v_lshl_add_u64 v[224:225], s[28:29], 0, v[156:157]
	global_load_lds_dwordx4 v[222:223], off
	v_lshl_add_u64 v[222:223], s[22:23], 0, v[158:159]
	s_add_i32 m0, s58, 0x2000
	s_nop 0
	global_load_lds_dwordx4 v[222:223], off
	v_lshl_add_u64 v[222:223], s[28:29], 0, v[152:153]
	s_mov_b32 m0, s34
	s_nop 0
	global_load_lds_dwordx4 v[222:223], off
	s_mov_b32 m0, s35
	s_nop 0
	global_load_lds_dwordx4 v[224:225], off
	s_waitcnt vmcnt(8)
	s_waitcnt lgkmcnt(0)
	s_barrier
; #define PG8_STAGE(bufoff, gbase, voff) do { _Pragma("unroll") for (int _i = 0; _i < 2; ++_i) \
;         __builtin_amdgcn_global_load_lds((const unsigned*)((const char*)(gbase) + (voff)[_i]), (PG8_LAS unsigned*)(lds + (bufoff) + ldsw + _i * 8192), 16, 0, 0); } while (0)
; #define PG8_LDA(dst, b, h) do { _Pragma("unroll") for (int m = 0; m < 4; ++m) _Pragma("unroll") for (int k = 0; k < 2; ++k) dst[m][k] = *(const PG8_LAS bf16x8*)(lds + PG8_SA(b, h) + aoff + m * 2048 + k * 1024); } while (0)
; #define PG8_LDB(dst, b, h) do { _Pragma("unroll") for (int n = 0; n < 2; ++n) _Pragma("unroll") for (int k = 0; k < 2; ++k) dst[n][k] = *(const PG8_LAS bf16x8*)(lds + PG8_SB(b, h) + boff + n * 2048 + k * 1024); } while (0)
; #define PG8_MMA(ai, bj, At, Bt) do { __builtin_amdgcn_s_setprio(1); _Pragma("unroll") for (int m = 0; m < 4; ++m) _Pragma("unroll") for (int n = 0; n < 2; ++n) _Pragma("unroll") for (int k = 0; k < 2; ++k) \
;         acc[ai][bj][m][n] = __builtin_amdgcn_mfma_f32_16x16x32_bf16(Bt[n][k], At[m][k], acc[ai][bj][m][n], 0, 0, 0); __builtin_amdgcn_s_setprio(0); } while (0)
; #define PG8_WAIT_V(n) asm volatile("s_waitcnt vmcnt(" #n ")" ::: "memory")
; #define PG8_WAIT_L(n) asm volatile("s_waitcnt lgkmcnt(" #n ")" ::: "memory")
; #define PG8_BAR __builtin_amdgcn_s_barrier()
; #define PG8_SCHED __builtin_amdgcn_sched_barrier(0)
; template <class Epi, class Sched, bool ALIGN_EPI = false, bool SP2 = false>
; __device__ __forceinline__ void gemm_phase(PG8_LAS unsigned char* lds, const Gemm g, const Sched& S, const Epi& E) {
;     ...
;             PG8_WAIT_V(8); PG8_WAIT_L(0); PG8_BAR; PG8_MMA(1, 0, At, B0); PG8_MMA(1, 1, At, B1); PG8_BAR; PG8_SCHED;
;             PG8_LDB(B0, 1, 0); PG8_LDB(B1, 1, 1); PG8_SCHED; PG8_LDA(At, 1, 0); PG8_STAGE(PG8_SA(0, 1), a2 + hstepA, voffA);
;             PG8_WAIT_V(8); PG8_WAIT_L(0); PG8_BAR; PG8_MMA(0, 0, At, B0); PG8_MMA(0, 1, At, B1); PG8_BAR; PG8_SCHED;
	s_setprio 1
	s_waitcnt lgkmcnt(0)
	v_mfma_f32_16x16x32_bf16 v[60:63], v[128:131], v[176:179], v[60:63]
	v_mfma_f32_16x16x32_bf16 v[56:59], v[136:139], v[176:179], v[56:59]
	v_mfma_f32_16x16x32_bf16 v[44:47], v[128:131], v[196:199], v[44:47]
	v_mfma_f32_16x16x32_bf16 v[40:43], v[136:139], v[196:199], v[40:43]
	v_mfma_f32_16x16x32_bf16 v[28:31], v[128:131], v[204:207], v[28:31]
	v_mfma_f32_16x16x32_bf16 v[24:27], v[136:139], v[204:207], v[24:27]
	v_mfma_f32_16x16x32_bf16 v[12:15], v[128:131], v[212:215], v[12:15]
	v_mfma_f32_16x16x32_bf16 v[8:11], v[136:139], v[212:215], v[8:11]
	v_mfma_f32_16x16x32_bf16 v[60:63], v[132:135], v[180:183], v[60:63]
	v_mfma_f32_16x16x32_bf16 v[56:59], v[140:143], v[180:183], v[56:59]
	v_mfma_f32_16x16x32_bf16 v[44:47], v[132:135], v[200:203], v[44:47]
	v_mfma_f32_16x16x32_bf16 v[40:43], v[140:143], v[200:203], v[40:43]
	v_mfma_f32_16x16x32_bf16 v[28:31], v[132:135], v[208:211], v[28:31]
	v_mfma_f32_16x16x32_bf16 v[24:27], v[140:143], v[208:211], v[24:27]
	v_mfma_f32_16x16x32_bf16 v[12:15], v[132:135], v[216:219], v[12:15]
	v_mfma_f32_16x16x32_bf16 v[8:11], v[140:143], v[216:219], v[8:11]
	s_setprio 0
	s_setprio 1
	v_mfma_f32_16x16x32_bf16 v[52:55], v[144:147], v[176:179], v[52:55]
	v_mfma_f32_16x16x32_bf16 v[48:51], v[168:171], v[176:179], v[48:51]
	v_mfma_f32_16x16x32_bf16 v[36:39], v[144:147], v[196:199], v[36:39]
	v_mfma_f32_16x16x32_bf16 v[32:35], v[168:171], v[196:199], v[32:35]
	v_mfma_f32_16x16x32_bf16 v[20:23], v[144:147], v[204:207], v[20:23]
	v_mfma_f32_16x16x32_bf16 v[16:19], v[168:171], v[204:207], v[16:19]
	v_mfma_f32_16x16x32_bf16 v[4:7], v[144:147], v[212:215], v[4:7]
	v_mfma_f32_16x16x32_bf16 v[0:3], v[168:171], v[212:215], v[0:3]
	v_mfma_f32_16x16x32_bf16 v[52:55], v[148:151], v[180:183], v[52:55]
	v_mfma_f32_16x16x32_bf16 v[48:51], v[172:175], v[180:183], v[48:51]
	v_mfma_f32_16x16x32_bf16 v[36:39], v[148:151], v[200:203], v[36:39]
	v_mfma_f32_16x16x32_bf16 v[32:35], v[172:175], v[200:203], v[32:35]
	v_mfma_f32_16x16x32_bf16 v[20:23], v[148:151], v[208:211], v[20:23]
	v_mfma_f32_16x16x32_bf16 v[16:19], v[172:175], v[208:211], v[16:19]
	v_mfma_f32_16x16x32_bf16 v[4:7], v[148:151], v[216:219], v[4:7]
	v_mfma_f32_16x16x32_bf16 v[0:3], v[172:175], v[216:219], v[0:3]
	s_barrier
	s_setprio 0
	s_add_i32 s58, 0, 0x18000
	s_add_i32 s59, 0, 0x1c000
	v_add_u32_e32 v140, s58, v189
	v_add_u32_e32 v172, s59, v189
	ds_read_b128 v[128:131], v140
	ds_read_b128 v[132:135], v140 offset:1024
	ds_read_b128 v[136:139], v140 offset:2048
	ds_read_b128 v[140:143], v140 offset:3072
	ds_read_b128 v[144:147], v172
	ds_read_b128 v[148:151], v172 offset:1024
	ds_read_b128 v[168:171], v172 offset:2048
	ds_read_b128 v[172:175], v172 offset:3072
	s_add_u32 s22, s28, 0xb0000
	s_addc_u32 s23, s29, 0
	s_mov_b32 m0, s36
	v_lshl_add_u64 v[226:227], s[22:23], 0, v[152:153]
	ds_read_b128 v[176:179], v193 offset:32768
	ds_read_b128 v[180:183], v193 offset:33792
	ds_read_b128 v[196:199], v193 offset:34816
	ds_read_b128 v[200:203], v193 offset:35840
	ds_read_b128 v[204:207], v193 offset:36864
	ds_read_b128 v[208:211], v193 offset:37888
	ds_read_b128 v[212:215], v193 offset:38912
	ds_read_b128 v[216:219], v193 offset:39936
	global_load_lds_dwordx4 v[226:227], off
	v_lshl_add_u64 v[226:227], s[22:23], 0, v[156:157]
	s_mov_b32 m0, s37
	s_nop 0
	global_load_lds_dwordx4 v[226:227], off
	s_waitcnt vmcnt(8)
	s_waitcnt lgkmcnt(0)
	s_barrier
	s_setprio 1
	s_waitcnt lgkmcnt(0)
	v_mfma_f32_16x16x32_bf16 v[124:127], v[128:131], v[176:179], v[124:127]
	v_mfma_f32_16x16x32_bf16 v[120:123], v[136:139], v[176:179], v[120:123]
	v_mfma_f32_16x16x32_bf16 v[108:111], v[128:131], v[196:199], v[108:111]
	v_mfma_f32_16x16x32_bf16 v[104:107], v[136:139], v[196:199], v[104:107]
	v_mfma_f32_16x16x32_bf16 v[92:95], v[128:131], v[204:207], v[92:95]
	v_mfma_f32_16x16x32_bf16 v[88:91], v[136:139], v[204:207], v[88:91]
	v_mfma_f32_16x16x32_bf16 v[76:79], v[128:131], v[212:215], v[76:79]
	v_mfma_f32_16x16x32_bf16 v[72:75], v[136:139], v[212:215], v[72:75]
	v_mfma_f32_16x16x32_bf16 v[124:127], v[132:135], v[180:183], v[124:127]
	v_mfma_f32_16x16x32_bf16 v[120:123], v[140:143], v[180:183], v[120:123]
	v_mfma_f32_16x16x32_bf16 v[108:111], v[132:135], v[200:203], v[108:111]
	v_mfma_f32_16x16x32_bf16 v[104:107], v[140:143], v[200:203], v[104:107]
	v_mfma_f32_16x16x32_bf16 v[92:95], v[132:135], v[208:211], v[92:95]
	v_mfma_f32_16x16x32_bf16 v[88:91], v[140:143], v[208:211], v[88:91]
	v_mfma_f32_16x16x32_bf16 v[76:79], v[132:135], v[216:219], v[76:79]
	v_mfma_f32_16x16x32_bf16 v[72:75], v[140:143], v[216:219], v[72:75]
	s_setprio 0
	s_setprio 1
	v_mfma_f32_16x16x32_bf16 v[116:119], v[144:147], v[176:179], v[116:119]
	v_mfma_f32_16x16x32_bf16 v[112:115], v[168:171], v[176:179], v[112:115]
	v_mfma_f32_16x16x32_bf16 v[100:103], v[144:147], v[196:199], v[100:103]
	v_mfma_f32_16x16x32_bf16 v[96:99], v[168:171], v[196:199], v[96:99]
	v_mfma_f32_16x16x32_bf16 v[84:87], v[144:147], v[204:207], v[84:87]
	v_mfma_f32_16x16x32_bf16 v[80:83], v[168:171], v[204:207], v[80:83]
	v_mfma_f32_16x16x32_bf16 v[68:71], v[144:147], v[212:215], v[68:71]
	v_mfma_f32_16x16x32_bf16 v[64:67], v[168:171], v[212:215], v[64:67]
	v_mfma_f32_16x16x32_bf16 v[116:119], v[148:151], v[180:183], v[116:119]
	v_mfma_f32_16x16x32_bf16 v[112:115], v[172:175], v[180:183], v[112:115]
	v_mfma_f32_16x16x32_bf16 v[100:103], v[148:151], v[200:203], v[100:103]
	v_mfma_f32_16x16x32_bf16 v[96:99], v[172:175], v[200:203], v[96:99]
	v_mfma_f32_16x16x32_bf16 v[84:87], v[148:151], v[208:211], v[84:87]
	v_mfma_f32_16x16x32_bf16 v[80:83], v[172:175], v[208:211], v[80:83]
	v_mfma_f32_16x16x32_bf16 v[68:71], v[148:151], v[216:219], v[68:71]
	v_mfma_f32_16x16x32_bf16 v[64:67], v[172:175], v[216:219], v[64:67]
	s_barrier
; #define PG8_STAGE(bufoff, gbase, voff) do { _Pragma("unroll") for (int _i = 0; _i < 2; ++_i) \
;         __builtin_amdgcn_global_load_lds((const unsigned*)((const char*)(gbase) + (voff)[_i]), (PG8_LAS unsigned*)(lds + (bufoff) + ldsw + _i * 8192), 16, 0, 0); } while (0)
; #define PG8_LDA(dst, b, h) do { _Pragma("unroll") for (int m = 0; m < 4; ++m) _Pragma("unroll") for (int k = 0; k < 2; ++k) dst[m][k] = *(const PG8_LAS bf16x8*)(lds + PG8_SA(b, h) + aoff + m * 2048 + k * 1024); } while (0)
; #define PG8_MMA(ai, bj, At, Bt) do { __builtin_amdgcn_s_setprio(1); _Pragma("unroll") for (int m = 0; m < 4; ++m) _Pragma("unroll") for (int n = 0; n < 2; ++n) _Pragma("unroll") for (int k = 0; k < 2; ++k) \
;         acc[ai][bj][m][n] = __builtin_amdgcn_mfma_f32_16x16x32_bf16(Bt[n][k], At[m][k], acc[ai][bj][m][n], 0, 0, 0); __builtin_amdgcn_s_setprio(0); } while (0)
; #define PG8_WAIT_V(n) asm volatile("s_waitcnt vmcnt(" #n ")" ::: "memory")
; #define PG8_WAIT_L(n) asm volatile("s_waitcnt lgkmcnt(" #n ")" ::: "memory")
; #define PG8_BAR __builtin_amdgcn_s_barrier()
; #define PG8_SCHED __builtin_amdgcn_sched_barrier(0)
; template <class Epi, class Sched, bool ALIGN_EPI = false, bool SP2 = false>
; __device__ __forceinline__ void gemm_phase(PG8_LAS unsigned char* lds, const Gemm g, const Sched& S, const Epi& E) {
;     ...
;             PG8_LDA(At, 1, 1); PG8_STAGE(PG8_SB(1, 0), b3, voffB); PG8_STAGE(PG8_SB(1, 1), b3 + hstepB, voffB); PG8_STAGE(PG8_SA(1, 0), a3, voffA);
;             PG8_WAIT_V(8); PG8_WAIT_L(0); PG8_BAR; PG8_MMA(1, 0, At, B0); PG8_MMA(1, 1, At, B1); PG8_BAR; PG8_SCHED;
;     ...
;         if constexpr (ALIGN_EPI) { if (wr == 0) PG8_BAR; }
	s_setprio 0
	s_add_i32 s22, s58, s31
	v_lshl_add_u64 v[184:185], v[184:185], 0, s[16:17]
	s_mov_b32 m0, s22
	ds_read_b128 v[176:179], v193 offset:49152
	ds_read_b128 v[180:183], v193 offset:50176
	ds_read_b128 v[196:199], v193 offset:51200
	ds_read_b128 v[200:203], v193 offset:52224
	ds_read_b128 v[204:207], v193 offset:53248
	ds_read_b128 v[208:211], v193 offset:54272
	ds_read_b128 v[212:215], v193 offset:55296
	ds_read_b128 v[216:219], v193 offset:56320
	global_load_lds_dwordx4 v[184:185], off
	s_add_i32 m0, s22, 0x2000
	s_add_u32 s22, s26, 0xb0080
	v_lshl_add_u64 v[184:185], v[220:221], 0, s[16:17]
	s_addc_u32 s23, s27, 0
	s_add_i32 s26, s59, s31
	global_load_lds_dwordx4 v[184:185], off
	v_lshl_add_u64 v[184:185], s[22:23], 0, v[154:155]
	s_mov_b32 m0, s26
	s_nop 0
	global_load_lds_dwordx4 v[184:185], off
	v_lshl_add_u64 v[184:185], s[22:23], 0, v[158:159]
	s_add_i32 m0, s26, 0x2000
	s_nop 0
	global_load_lds_dwordx4 v[184:185], off
	v_lshl_add_u64 v[184:185], v[222:223], 0, s[16:17]
	s_mov_b32 m0, s39
	s_nop 0
	global_load_lds_dwordx4 v[184:185], off
	v_lshl_add_u64 v[184:185], v[224:225], 0, s[16:17]
	s_mov_b32 m0, s40
	s_nop 0
	global_load_lds_dwordx4 v[184:185], off
	s_waitcnt vmcnt(8)
	s_waitcnt lgkmcnt(0)
	s_barrier
	s_setprio 1
	s_waitcnt lgkmcnt(0)
	v_mfma_f32_16x16x32_bf16 v[60:63], v[128:131], v[176:179], v[60:63]
	v_mfma_f32_16x16x32_bf16 v[56:59], v[136:139], v[176:179], v[56:59]
	v_mfma_f32_16x16x32_bf16 v[44:47], v[128:131], v[196:199], v[44:47]
	v_mfma_f32_16x16x32_bf16 v[40:43], v[136:139], v[196:199], v[40:43]
	v_mfma_f32_16x16x32_bf16 v[28:31], v[128:131], v[204:207], v[28:31]
	v_mfma_f32_16x16x32_bf16 v[24:27], v[136:139], v[204:207], v[24:27]
	v_mfma_f32_16x16x32_bf16 v[12:15], v[128:131], v[212:215], v[12:15]
	v_mfma_f32_16x16x32_bf16 v[8:11], v[136:139], v[212:215], v[8:11]
	v_mfma_f32_16x16x32_bf16 v[60:63], v[132:135], v[180:183], v[60:63]
	v_mfma_f32_16x16x32_bf16 v[56:59], v[140:143], v[180:183], v[56:59]
	v_mfma_f32_16x16x32_bf16 v[44:47], v[132:135], v[200:203], v[44:47]
	v_mfma_f32_16x16x32_bf16 v[40:43], v[140:143], v[200:203], v[40:43]
	v_mfma_f32_16x16x32_bf16 v[28:31], v[132:135], v[208:211], v[28:31]
	v_mfma_f32_16x16x32_bf16 v[24:27], v[140:143], v[208:211], v[24:27]
	v_mfma_f32_16x16x32_bf16 v[12:15], v[132:135], v[216:219], v[12:15]
	v_mfma_f32_16x16x32_bf16 v[8:11], v[140:143], v[216:219], v[8:11]
	s_setprio 0
	s_setprio 1
	v_mfma_f32_16x16x32_bf16 v[52:55], v[144:147], v[176:179], v[52:55]
	v_mfma_f32_16x16x32_bf16 v[48:51], v[168:171], v[176:179], v[48:51]
	v_mfma_f32_16x16x32_bf16 v[36:39], v[144:147], v[196:199], v[36:39]
	v_mfma_f32_16x16x32_bf16 v[32:35], v[168:171], v[196:199], v[32:35]
	v_mfma_f32_16x16x32_bf16 v[20:23], v[144:147], v[204:207], v[20:23]
	v_mfma_f32_16x16x32_bf16 v[16:19], v[168:171], v[204:207], v[16:19]
	v_mfma_f32_16x16x32_bf16 v[4:7], v[144:147], v[212:215], v[4:7]
	v_mfma_f32_16x16x32_bf16 v[0:3], v[168:171], v[212:215], v[0:3]
	v_mfma_f32_16x16x32_bf16 v[52:55], v[148:151], v[180:183], v[52:55]
	v_mfma_f32_16x16x32_bf16 v[48:51], v[172:175], v[180:183], v[48:51]
	v_mfma_f32_16x16x32_bf16 v[36:39], v[148:151], v[200:203], v[36:39]
	v_mfma_f32_16x16x32_bf16 v[32:35], v[172:175], v[200:203], v[32:35]
	v_mfma_f32_16x16x32_bf16 v[20:23], v[148:151], v[208:211], v[20:23]
	v_mfma_f32_16x16x32_bf16 v[16:19], v[172:175], v[208:211], v[16:19]
	v_mfma_f32_16x16x32_bf16 v[4:7], v[148:151], v[216:219], v[4:7]
	v_mfma_f32_16x16x32_bf16 v[0:3], v[172:175], v[216:219], v[0:3]
	s_barrier
	s_setprio 0
	s_add_i32 s69, s69, 2
	s_add_u32 s67, s67, 0x100
	s_addc_u32 s68, s68, 0
	s_cmp_gt_u32 s69, 41
	s_mov_b64 s[22:23], s[24:25]
	s_cbranch_scc0 .LBB0_1129
	s_and_b64 vcc, exec, s[18:19]
	s_cbranch_vccz .LBB0_1132
	s_barrier

; #define PG8_STAGE(bufoff, gbase, voff) do { _Pragma("unroll") for (int _i = 0; _i < 2; ++_i) \
;         __builtin_amdgcn_global_load_lds((const unsigned*)((const char*)(gbase) + (voff)[_i]), (PG8_LAS unsigned*)(lds + (bufoff) + ldsw + _i * 8192), 16, 0, 0); } while (0)
; #define PG8_LDA(dst, b, h) do { _Pragma("unroll") for (int m = 0; m < 4; ++m) _Pragma("unroll") for (int k = 0; k < 2; ++k) dst[m][k] = *(const PG8_LAS bf16x8*)(lds + PG8_SA(b, h) + aoff + m * 2048 + k * 1024); } while (0)
; #define PG8_LDB(dst, b, h) do { _Pragma("unroll") for (int n = 0; n < 2; ++n) _Pragma("unroll") for (int k = 0; k < 2; ++k) dst[n][k] = *(const PG8_LAS bf16x8*)(lds + PG8_SB(b, h) + boff + n * 2048 + k * 1024); } while (0)
; #define PG8_MMA(ai, bj, At, Bt) do { __builtin_amdgcn_s_setprio(1); _Pragma("unroll") for (int m = 0; m < 4; ++m) _Pragma("unroll") for (int n = 0; n < 2; ++n) _Pragma("unroll") for (int k = 0; k < 2; ++k) \
;         acc[ai][bj][m][n] = __builtin_amdgcn_mfma_f32_16x16x32_bf16(Bt[n][k], At[m][k], acc[ai][bj][m][n], 0, 0, 0); __builtin_amdgcn_s_setprio(0); } while (0)
; #define PG8_BAR __builtin_amdgcn_s_barrier()
; template <class Epi, class Sched, bool ALIGN_EPI = false, bool SP2 = false>
; __device__ __forceinline__ void gemm_phase(PG8_LAS unsigned char* lds, const Gemm g, const Sched& S, const Epi& E) {
;     ...
;         const bool has_next = S.next(ui + 1, nxt);
;         const char* nA = has_next ? (const char*)g.A + (size_t)nxt.pm * tstepA : cA; const char* nB = has_next ? (const char*)g.Bt + (size_t)nxt.pn * tstepB : cB;
;         for (int t = 0; t < nt; t += 2) {
;             const bool last = (t == nt - 2);
;             const char* a1 = cA + (size_t)(t + 1) * kstep;
;             const char* a2 = last ? nA : cA + (size_t)(t + 2) * kstep; const char* b2 = last ? nB : cB + (size_t)(t + 2) * kstep;
;             const char* a3 = a2 + kstep; const char* b3 = b2 + kstep;
;             if (last && has_next) S.a_ready(nxt);
;             if constexpr (SP2) {
;             PG8_LDB(B0, 0, 0); PG8_LDB(B1, 0, 1); PG8_SCHED; PG8_LDA(At, 0, 0); PG8_STAGE(PG8_SA(1, 1), a1 + hstepA, voffA);
;             PG8_WAIT_V(8); PG8_WAIT_L(0); PG8_BAR; PG8_MMA(0, 0, At, B0); PG8_MMA(0, 1, At, B1); PG8_BAR; PG8_SCHED;
;             PG8_LDA(At, 0, 1); PG8_STAGE(PG8_SB(0, 0), b2, voffB); PG8_STAGE(PG8_SB(0, 1), b2 + hstepB, voffB); PG8_STAGE(PG8_SA(0, 0), a2, voffA);
.LBB0_1161:
	s_add_u32 s43, s36, s42
	s_addc_u32 s48, s37, 0
	s_add_u32 s46, s43, 0x100
	s_addc_u32 s47, s48, 0
	s_and_b64 s[44:45], s[40:41], exec
	s_cselect_b32 s45, s25, s47
	s_cselect_b32 s44, s89, s46
	s_add_u32 s42, s34, s42
	s_addc_u32 s46, s35, 0
	s_add_u32 s42, s42, 0x100
	s_addc_u32 s46, s46, 0
	s_and_b64 s[40:41], s[40:41], exec
	s_cselect_b32 s47, s23, s46
	s_cselect_b32 s46, s90, s42
	s_add_u32 s64, s43, 0x10080
	ds_read_b128 v[146:149], v143
	ds_read_b128 v[150:153], v143 offset:1024
	ds_read_b128 v[154:157], v143 offset:2048
	ds_read_b128 v[158:161], v143 offset:3072
	ds_read_b128 v[162:165], v144
	ds_read_b128 v[166:169], v144 offset:1024
	ds_read_b128 v[170:173], v144 offset:2048
	ds_read_b128 v[174:177], v144 offset:3072
	s_addc_u32 s65, s48, 0
	s_add_i32 s97, s82, s67
	s_add_i32 m0, s31, 0xc000
	s_add_i32 s59, s31, 0xe000
	s_add_i32 s58, s97, 0x2000
	s_add_u32 s48, s46, 0x10000
	s_addc_u32 s49, s47, 0
	s_add_i32 vcc_hi, s83, s67
	s_add_i32 vcc_lo, vcc_hi, 0x2000
	s_add_i32 s96, 0, 0x18000
	s_add_i32 s95, 0, 0x1c000
	s_add_u32 s42, s44, 0x10000
	s_addc_u32 s43, s45, 0
	s_add_i32 s94, s96, s67
	s_add_i32 s92, s94, 0x2000
	s_add_u32 s40, s46, 0x10080
	s_addc_u32 s41, s47, 0
	s_add_i32 s93, s95, s67
	s_add_i32 s91, s93, 0x2000
	v_lshl_add_u64 v[212:213], s[64:65], 0, v[134:135]
	ds_read_b128 v[178:181], v145
	ds_read_b128 v[182:185], v145 offset:1024
	ds_read_b128 v[188:191], v145 offset:2048
	ds_read_b128 v[192:195], v145 offset:3072
	ds_read_b128 v[196:199], v145 offset:4096
	ds_read_b128 v[200:203], v145 offset:5120
	ds_read_b128 v[204:207], v145 offset:6144
	ds_read_b128 v[208:211], v145 offset:7168
	global_load_lds_dwordx4 v[212:213], off
	v_lshl_add_u64 v[212:213], s[64:65], 0, v[130:131]
	s_mov_b32 m0, s59
	s_nop 0
	global_load_lds_dwordx4 v[212:213], off
	s_waitcnt vmcnt(8)
	s_waitcnt lgkmcnt(0)
	s_barrier
	s_setprio 1
	s_waitcnt lgkmcnt(0)
	v_mfma_f32_16x16x32_bf16 v[124:127], v[146:149], v[178:181], v[124:127]
	v_mfma_f32_16x16x32_bf16 v[120:123], v[154:157], v[178:181], v[120:123]
	v_mfma_f32_16x16x32_bf16 v[116:119], v[146:149], v[188:191], v[116:119]
	v_mfma_f32_16x16x32_bf16 v[108:111], v[154:157], v[188:191], v[108:111]
	v_mfma_f32_16x16x32_bf16 v[100:103], v[146:149], v[196:199], v[100:103]
	v_mfma_f32_16x16x32_bf16 v[92:95], v[154:157], v[196:199], v[92:95]
	v_mfma_f32_16x16x32_bf16 v[84:87], v[146:149], v[204:207], v[84:87]
	v_mfma_f32_16x16x32_bf16 v[76:79], v[154:157], v[204:207], v[76:79]
	v_mfma_f32_16x16x32_bf16 v[124:127], v[150:153], v[182:185], v[124:127]
	v_mfma_f32_16x16x32_bf16 v[120:123], v[158:161], v[182:185], v[120:123]
	v_mfma_f32_16x16x32_bf16 v[116:119], v[150:153], v[192:195], v[116:119]
	v_mfma_f32_16x16x32_bf16 v[108:111], v[158:161], v[192:195], v[108:111]
	v_mfma_f32_16x16x32_bf16 v[100:103], v[150:153], v[200:203], v[100:103]
	v_mfma_f32_16x16x32_bf16 v[92:95], v[158:161], v[200:203], v[92:95]
	v_mfma_f32_16x16x32_bf16 v[84:87], v[150:153], v[208:211], v[84:87]
	v_mfma_f32_16x16x32_bf16 v[76:79], v[158:161], v[208:211], v[76:79]
	s_setprio 0
	s_setprio 1
	v_mfma_f32_16x16x32_bf16 v[112:115], v[162:165], v[178:181], v[112:115]
	v_mfma_f32_16x16x32_bf16 v[104:107], v[170:173], v[178:181], v[104:107]
	v_mfma_f32_16x16x32_bf16 v[96:99], v[162:165], v[188:191], v[96:99]
	v_mfma_f32_16x16x32_bf16 v[88:91], v[170:173], v[188:191], v[88:91]
	v_mfma_f32_16x16x32_bf16 v[80:83], v[162:165], v[196:199], v[80:83]
	v_mfma_f32_16x16x32_bf16 v[72:75], v[170:173], v[196:199], v[72:75]
	v_mfma_f32_16x16x32_bf16 v[68:71], v[162:165], v[204:207], v[68:71]
	v_mfma_f32_16x16x32_bf16 v[64:67], v[170:173], v[204:207], v[64:67]
	v_mfma_f32_16x16x32_bf16 v[112:115], v[166:169], v[182:185], v[112:115]
	v_mfma_f32_16x16x32_bf16 v[104:107], v[174:177], v[182:185], v[104:107]
	v_mfma_f32_16x16x32_bf16 v[96:99], v[166:169], v[192:195], v[96:99]
	v_mfma_f32_16x16x32_bf16 v[88:91], v[174:177], v[192:195], v[88:91]
	v_mfma_f32_16x16x32_bf16 v[80:83], v[166:169], v[200:203], v[80:83]
	v_mfma_f32_16x16x32_bf16 v[72:75], v[174:177], v[200:203], v[72:75]
	v_mfma_f32_16x16x32_bf16 v[68:71], v[166:169], v[208:211], v[68:71]
	v_mfma_f32_16x16x32_bf16 v[64:67], v[174:177], v[208:211], v[64:67]
	s_barrier
	s_setprio 0
	s_mov_b32 m0, s97
	v_lshl_add_u64 v[212:213], s[46:47], 0, v[132:133]
	ds_read_b128 v[178:181], v145 offset:16384
	ds_read_b128 v[182:185], v145 offset:17408
	ds_read_b128 v[188:191], v145 offset:18432
	ds_read_b128 v[192:195], v145 offset:19456
	ds_read_b128 v[196:199], v145 offset:20480
	ds_read_b128 v[200:203], v145 offset:21504
	ds_read_b128 v[204:207], v145 offset:22528
	ds_read_b128 v[208:211], v145 offset:23552
	global_load_lds_dwordx4 v[212:213], off
	v_lshl_add_u64 v[214:215], s[46:47], 0, v[128:129]
	s_mov_b32 m0, s58
	v_lshl_add_u64 v[216:217], s[48:49], 0, v[132:133]
	global_load_lds_dwordx4 v[214:215], off
	s_mov_b32 m0, vcc_hi
	v_lshl_add_u64 v[218:219], s[44:45], 0, v[130:131]
	global_load_lds_dwordx4 v[216:217], off
	v_lshl_add_u64 v[216:217], s[48:49], 0, v[128:129]
	s_mov_b32 m0, vcc_lo
	s_nop 0
	global_load_lds_dwordx4 v[216:217], off
	v_lshl_add_u64 v[216:217], s[44:45], 0, v[134:135]
	s_mov_b32 m0, s31
	s_nop 0
	global_load_lds_dwordx4 v[216:217], off
	s_mov_b32 m0, s74
	s_nop 0
	global_load_lds_dwordx4 v[218:219], off
	s_waitcnt vmcnt(8)
	s_waitcnt lgkmcnt(0)
	s_barrier
; #define PG8_STAGE(bufoff, gbase, voff) do { _Pragma("unroll") for (int _i = 0; _i < 2; ++_i) \
;         __builtin_amdgcn_global_load_lds((const unsigned*)((const char*)(gbase) + (voff)[_i]), (PG8_LAS unsigned*)(lds + (bufoff) + ldsw + _i * 8192), 16, 0, 0); } while (0)
; #define PG8_LDA(dst, b, h) do { _Pragma("unroll") for (int m = 0; m < 4; ++m) _Pragma("unroll") for (int k = 0; k < 2; ++k) dst[m][k] = *(const PG8_LAS bf16x8*)(lds + PG8_SA(b, h) + aoff + m * 2048 + k * 1024); } while (0)
; #define PG8_LDB(dst, b, h) do { _Pragma("unroll") for (int n = 0; n < 2; ++n) _Pragma("unroll") for (int k = 0; k < 2; ++k) dst[n][k] = *(const PG8_LAS bf16x8*)(lds + PG8_SB(b, h) + boff + n * 2048 + k * 1024); } while (0)
; #define PG8_MMA(ai, bj, At, Bt) do { __builtin_amdgcn_s_setprio(1); _Pragma("unroll") for (int m = 0; m < 4; ++m) _Pragma("unroll") for (int n = 0; n < 2; ++n) _Pragma("unroll") for (int k = 0; k < 2; ++k) \
;         acc[ai][bj][m][n] = __builtin_amdgcn_mfma_f32_16x16x32_bf16(Bt[n][k], At[m][k], acc[ai][bj][m][n], 0, 0, 0); __builtin_amdgcn_s_setprio(0); } while (0)
; #define PG8_WAIT_V(n) asm volatile("s_waitcnt vmcnt(" #n ")" ::: "memory")
; #define PG8_WAIT_L(n) asm volatile("s_waitcnt lgkmcnt(" #n ")" ::: "memory")
; #define PG8_BAR __builtin_amdgcn_s_barrier()
; #define PG8_SCHED __builtin_amdgcn_sched_barrier(0)
; template <class Epi, class Sched, bool ALIGN_EPI = false, bool SP2 = false>
; __device__ __forceinline__ void gemm_phase(PG8_LAS unsigned char* lds, const Gemm g, const Sched& S, const Epi& E) {
;     ...
;             PG8_WAIT_V(8); PG8_WAIT_L(0); PG8_BAR; PG8_MMA(1, 0, At, B0); PG8_MMA(1, 1, At, B1); PG8_BAR; PG8_SCHED;
;             PG8_LDB(B0, 1, 0); PG8_LDB(B1, 1, 1); PG8_SCHED; PG8_LDA(At, 1, 0); PG8_STAGE(PG8_SA(0, 1), a2 + hstepA, voffA);
;             PG8_WAIT_V(8); PG8_WAIT_L(0); PG8_BAR; PG8_MMA(0, 0, At, B0); PG8_MMA(0, 1, At, B1); PG8_BAR; PG8_SCHED;
	s_setprio 1
	s_waitcnt lgkmcnt(0)
	v_mfma_f32_16x16x32_bf16 v[60:63], v[146:149], v[178:181], v[60:63]
	v_mfma_f32_16x16x32_bf16 v[56:59], v[154:157], v[178:181], v[56:59]
	v_mfma_f32_16x16x32_bf16 v[52:55], v[146:149], v[188:191], v[52:55]
	v_mfma_f32_16x16x32_bf16 v[44:47], v[154:157], v[188:191], v[44:47]
	v_mfma_f32_16x16x32_bf16 v[36:39], v[146:149], v[196:199], v[36:39]
	v_mfma_f32_16x16x32_bf16 v[28:31], v[154:157], v[196:199], v[28:31]
	v_mfma_f32_16x16x32_bf16 v[20:23], v[146:149], v[204:207], v[20:23]
	v_mfma_f32_16x16x32_bf16 v[12:15], v[154:157], v[204:207], v[12:15]
	v_mfma_f32_16x16x32_bf16 v[60:63], v[150:153], v[182:185], v[60:63]
	v_mfma_f32_16x16x32_bf16 v[56:59], v[158:161], v[182:185], v[56:59]
	v_mfma_f32_16x16x32_bf16 v[52:55], v[150:153], v[192:195], v[52:55]
	v_mfma_f32_16x16x32_bf16 v[44:47], v[158:161], v[192:195], v[44:47]
	v_mfma_f32_16x16x32_bf16 v[36:39], v[150:153], v[200:203], v[36:39]
	v_mfma_f32_16x16x32_bf16 v[28:31], v[158:161], v[200:203], v[28:31]
	v_mfma_f32_16x16x32_bf16 v[20:23], v[150:153], v[208:211], v[20:23]
	v_mfma_f32_16x16x32_bf16 v[12:15], v[158:161], v[208:211], v[12:15]
	s_setprio 0
	s_setprio 1
	v_mfma_f32_16x16x32_bf16 v[48:51], v[162:165], v[178:181], v[48:51]
	v_mfma_f32_16x16x32_bf16 v[40:43], v[170:173], v[178:181], v[40:43]
	v_mfma_f32_16x16x32_bf16 v[32:35], v[162:165], v[188:191], v[32:35]
	v_mfma_f32_16x16x32_bf16 v[24:27], v[170:173], v[188:191], v[24:27]
	v_mfma_f32_16x16x32_bf16 v[16:19], v[162:165], v[196:199], v[16:19]
	v_mfma_f32_16x16x32_bf16 v[8:11], v[170:173], v[196:199], v[8:11]
	v_mfma_f32_16x16x32_bf16 v[4:7], v[162:165], v[204:207], v[4:7]
	v_mfma_f32_16x16x32_bf16 v[0:3], v[170:173], v[204:207], v[0:3]
	v_mfma_f32_16x16x32_bf16 v[48:51], v[166:169], v[182:185], v[48:51]
	v_mfma_f32_16x16x32_bf16 v[40:43], v[174:177], v[182:185], v[40:43]
	v_mfma_f32_16x16x32_bf16 v[32:35], v[166:169], v[192:195], v[32:35]
	v_mfma_f32_16x16x32_bf16 v[24:27], v[174:177], v[192:195], v[24:27]
	v_mfma_f32_16x16x32_bf16 v[16:19], v[166:169], v[200:203], v[16:19]
	v_mfma_f32_16x16x32_bf16 v[8:11], v[174:177], v[200:203], v[8:11]
	v_mfma_f32_16x16x32_bf16 v[4:7], v[166:169], v[208:211], v[4:7]
	v_mfma_f32_16x16x32_bf16 v[0:3], v[174:177], v[208:211], v[0:3]
	s_barrier
	s_setprio 0
	v_add_u32_e32 v158, s96, v141
	v_add_u32_e32 v174, s95, v141
	ds_read_b128 v[146:149], v158
	ds_read_b128 v[150:153], v158 offset:1024
	ds_read_b128 v[154:157], v158 offset:2048
	ds_read_b128 v[158:161], v158 offset:3072
	ds_read_b128 v[162:165], v174
	ds_read_b128 v[166:169], v174 offset:1024
	ds_read_b128 v[170:173], v174 offset:2048
	ds_read_b128 v[174:177], v174 offset:3072
	s_mov_b32 m0, s75
	v_lshl_add_u64 v[220:221], s[42:43], 0, v[134:135]
	ds_read_b128 v[178:181], v145 offset:32768
	ds_read_b128 v[182:185], v145 offset:33792
	ds_read_b128 v[188:191], v145 offset:34816
	ds_read_b128 v[192:195], v145 offset:35840
	ds_read_b128 v[196:199], v145 offset:36864
	ds_read_b128 v[200:203], v145 offset:37888
	ds_read_b128 v[204:207], v145 offset:38912
	ds_read_b128 v[208:211], v145 offset:39936
	global_load_lds_dwordx4 v[220:221], off
	v_lshl_add_u64 v[220:221], s[42:43], 0, v[130:131]
	s_mov_b32 m0, s76
	s_nop 0
	global_load_lds_dwordx4 v[220:221], off
	s_waitcnt vmcnt(8)
	s_waitcnt lgkmcnt(0)
	s_barrier
	s_setprio 1
	s_waitcnt lgkmcnt(0)
	v_mfma_f32_16x16x32_bf16 v[124:127], v[146:149], v[178:181], v[124:127]
	v_mfma_f32_16x16x32_bf16 v[120:123], v[154:157], v[178:181], v[120:123]
	v_mfma_f32_16x16x32_bf16 v[116:119], v[146:149], v[188:191], v[116:119]
	v_mfma_f32_16x16x32_bf16 v[108:111], v[154:157], v[188:191], v[108:111]
	v_mfma_f32_16x16x32_bf16 v[100:103], v[146:149], v[196:199], v[100:103]
	v_mfma_f32_16x16x32_bf16 v[92:95], v[154:157], v[196:199], v[92:95]
	v_mfma_f32_16x16x32_bf16 v[84:87], v[146:149], v[204:207], v[84:87]
	v_mfma_f32_16x16x32_bf16 v[76:79], v[154:157], v[204:207], v[76:79]
	v_mfma_f32_16x16x32_bf16 v[124:127], v[150:153], v[182:185], v[124:127]
	v_mfma_f32_16x16x32_bf16 v[120:123], v[158:161], v[182:185], v[120:123]
	v_mfma_f32_16x16x32_bf16 v[116:119], v[150:153], v[192:195], v[116:119]
	v_mfma_f32_16x16x32_bf16 v[108:111], v[158:161], v[192:195], v[108:111]
	v_mfma_f32_16x16x32_bf16 v[100:103], v[150:153], v[200:203], v[100:103]
	v_mfma_f32_16x16x32_bf16 v[92:95], v[158:161], v[200:203], v[92:95]
	v_mfma_f32_16x16x32_bf16 v[84:87], v[150:153], v[208:211], v[84:87]
	v_mfma_f32_16x16x32_bf16 v[76:79], v[158:161], v[208:211], v[76:79]
	s_setprio 0
	s_setprio 1
	v_mfma_f32_16x16x32_bf16 v[112:115], v[162:165], v[178:181], v[112:115]
	v_mfma_f32_16x16x32_bf16 v[104:107], v[170:173], v[178:181], v[104:107]
	v_mfma_f32_16x16x32_bf16 v[96:99], v[162:165], v[188:191], v[96:99]
	v_mfma_f32_16x16x32_bf16 v[88:91], v[170:173], v[188:191], v[88:91]
	v_mfma_f32_16x16x32_bf16 v[80:83], v[162:165], v[196:199], v[80:83]
	v_mfma_f32_16x16x32_bf16 v[72:75], v[170:173], v[196:199], v[72:75]
	v_mfma_f32_16x16x32_bf16 v[68:71], v[162:165], v[204:207], v[68:71]
	v_mfma_f32_16x16x32_bf16 v[64:67], v[170:173], v[204:207], v[64:67]
	v_mfma_f32_16x16x32_bf16 v[112:115], v[166:169], v[182:185], v[112:115]
	v_mfma_f32_16x16x32_bf16 v[104:107], v[174:177], v[182:185], v[104:107]
	v_mfma_f32_16x16x32_bf16 v[96:99], v[166:169], v[192:195], v[96:99]
	v_mfma_f32_16x16x32_bf16 v[88:91], v[174:177], v[192:195], v[88:91]
	v_mfma_f32_16x16x32_bf16 v[80:83], v[166:169], v[200:203], v[80:83]
	v_mfma_f32_16x16x32_bf16 v[72:75], v[174:177], v[200:203], v[72:75]
	v_mfma_f32_16x16x32_bf16 v[68:71], v[166:169], v[208:211], v[68:71]
	v_mfma_f32_16x16x32_bf16 v[64:67], v[174:177], v[208:211], v[64:67]
	s_barrier
; #define PG8_STAGE(bufoff, gbase, voff) do { _Pragma("unroll") for (int _i = 0; _i < 2; ++_i) \
;         __builtin_amdgcn_global_load_lds((const unsigned*)((const char*)(gbase) + (voff)[_i]), (PG8_LAS unsigned*)(lds + (bufoff) + ldsw + _i * 8192), 16, 0, 0); } while (0)
; #define PG8_LDA(dst, b, h) do { _Pragma("unroll") for (int m = 0; m < 4; ++m) _Pragma("unroll") for (int k = 0; k < 2; ++k) dst[m][k] = *(const PG8_LAS bf16x8*)(lds + PG8_SA(b, h) + aoff + m * 2048 + k * 1024); } while (0)
; #define PG8_MMA(ai, bj, At, Bt) do { __builtin_amdgcn_s_setprio(1); _Pragma("unroll") for (int m = 0; m < 4; ++m) _Pragma("unroll") for (int n = 0; n < 2; ++n) _Pragma("unroll") for (int k = 0; k < 2; ++k) \
;         acc[ai][bj][m][n] = __builtin_amdgcn_mfma_f32_16x16x32_bf16(Bt[n][k], At[m][k], acc[ai][bj][m][n], 0, 0, 0); __builtin_amdgcn_s_setprio(0); } while (0)
; #define PG8_WAIT_V(n) asm volatile("s_waitcnt vmcnt(" #n ")" ::: "memory")
; #define PG8_WAIT_L(n) asm volatile("s_waitcnt lgkmcnt(" #n ")" ::: "memory")
; #define PG8_BAR __builtin_amdgcn_s_barrier()
; #define PG8_SCHED __builtin_amdgcn_sched_barrier(0)
; template <class Epi, class Sched, bool ALIGN_EPI = false, bool SP2 = false>
; __device__ __forceinline__ void gemm_phase(PG8_LAS unsigned char* lds, const Gemm g, const Sched& S, const Epi& E) {
;     ...
;             PG8_LDA(At, 1, 1); PG8_STAGE(PG8_SB(1, 0), b3, voffB); PG8_STAGE(PG8_SB(1, 1), b3 + hstepB, voffB); PG8_STAGE(PG8_SA(1, 0), a3, voffA);
;             PG8_WAIT_V(8); PG8_WAIT_L(0); PG8_BAR; PG8_MMA(1, 0, At, B0); PG8_MMA(1, 1, At, B1); PG8_BAR; PG8_SCHED;
;     ...
;         if constexpr (ALIGN_EPI) { if (wr == 0) PG8_BAR; }
	s_setprio 0
	s_mov_b32 m0, s94
	v_lshl_add_u64 v[212:213], v[212:213], 0, s[10:11]
	ds_read_b128 v[178:181], v145 offset:49152
	ds_read_b128 v[182:185], v145 offset:50176
	ds_read_b128 v[188:191], v145 offset:51200
	ds_read_b128 v[192:195], v145 offset:52224
	ds_read_b128 v[196:199], v145 offset:53248
	ds_read_b128 v[200:203], v145 offset:54272
	ds_read_b128 v[204:207], v145 offset:55296
	ds_read_b128 v[208:211], v145 offset:56320
	global_load_lds_dwordx4 v[212:213], off
	v_lshl_add_u64 v[212:213], v[214:215], 0, s[10:11]
	s_mov_b32 m0, s92
	s_nop 0
	global_load_lds_dwordx4 v[212:213], off
	v_lshl_add_u64 v[212:213], s[40:41], 0, v[132:133]
	s_mov_b32 m0, s93
	s_nop 0
	global_load_lds_dwordx4 v[212:213], off
	v_lshl_add_u64 v[212:213], s[40:41], 0, v[128:129]
	s_mov_b32 m0, s91
	s_nop 0
	global_load_lds_dwordx4 v[212:213], off
	v_lshl_add_u64 v[212:213], v[216:217], 0, s[10:11]
	s_mov_b32 m0, s78
	s_nop 0
	global_load_lds_dwordx4 v[212:213], off
	v_lshl_add_u64 v[212:213], v[218:219], 0, s[10:11]
	s_mov_b32 m0, s79
	s_nop 0
	global_load_lds_dwordx4 v[212:213], off
	s_waitcnt vmcnt(8)
	s_waitcnt lgkmcnt(0)
	s_barrier
	s_setprio 1
	s_waitcnt lgkmcnt(0)
	v_mfma_f32_16x16x32_bf16 v[60:63], v[146:149], v[178:181], v[60:63]
	v_mfma_f32_16x16x32_bf16 v[56:59], v[154:157], v[178:181], v[56:59]
	v_mfma_f32_16x16x32_bf16 v[52:55], v[146:149], v[188:191], v[52:55]
	v_mfma_f32_16x16x32_bf16 v[44:47], v[154:157], v[188:191], v[44:47]
	v_mfma_f32_16x16x32_bf16 v[36:39], v[146:149], v[196:199], v[36:39]
	v_mfma_f32_16x16x32_bf16 v[28:31], v[154:157], v[196:199], v[28:31]
	v_mfma_f32_16x16x32_bf16 v[20:23], v[146:149], v[204:207], v[20:23]
	v_mfma_f32_16x16x32_bf16 v[12:15], v[154:157], v[204:207], v[12:15]
	v_mfma_f32_16x16x32_bf16 v[60:63], v[150:153], v[182:185], v[60:63]
	v_mfma_f32_16x16x32_bf16 v[56:59], v[158:161], v[182:185], v[56:59]
	v_mfma_f32_16x16x32_bf16 v[52:55], v[150:153], v[192:195], v[52:55]
	v_mfma_f32_16x16x32_bf16 v[44:47], v[158:161], v[192:195], v[44:47]
	v_mfma_f32_16x16x32_bf16 v[36:39], v[150:153], v[200:203], v[36:39]
	v_mfma_f32_16x16x32_bf16 v[28:31], v[158:161], v[200:203], v[28:31]
	v_mfma_f32_16x16x32_bf16 v[20:23], v[150:153], v[208:211], v[20:23]
	v_mfma_f32_16x16x32_bf16 v[12:15], v[158:161], v[208:211], v[12:15]
	s_setprio 0
	s_setprio 1
	v_mfma_f32_16x16x32_bf16 v[48:51], v[162:165], v[178:181], v[48:51]
	v_mfma_f32_16x16x32_bf16 v[40:43], v[170:173], v[178:181], v[40:43]
	v_mfma_f32_16x16x32_bf16 v[32:35], v[162:165], v[188:191], v[32:35]
	v_mfma_f32_16x16x32_bf16 v[24:27], v[170:173], v[188:191], v[24:27]
	v_mfma_f32_16x16x32_bf16 v[16:19], v[162:165], v[196:199], v[16:19]
	v_mfma_f32_16x16x32_bf16 v[8:11], v[170:173], v[196:199], v[8:11]
	v_mfma_f32_16x16x32_bf16 v[4:7], v[162:165], v[204:207], v[4:7]
	v_mfma_f32_16x16x32_bf16 v[0:3], v[170:173], v[204:207], v[0:3]
	v_mfma_f32_16x16x32_bf16 v[48:51], v[166:169], v[182:185], v[48:51]
	v_mfma_f32_16x16x32_bf16 v[40:43], v[174:177], v[182:185], v[40:43]
	v_mfma_f32_16x16x32_bf16 v[32:35], v[166:169], v[192:195], v[32:35]
	v_mfma_f32_16x16x32_bf16 v[24:27], v[174:177], v[192:195], v[24:27]
	v_mfma_f32_16x16x32_bf16 v[16:19], v[166:169], v[200:203], v[16:19]
	v_mfma_f32_16x16x32_bf16 v[8:11], v[174:177], v[200:203], v[8:11]
	v_mfma_f32_16x16x32_bf16 v[4:7], v[166:169], v[208:211], v[4:7]
	v_mfma_f32_16x16x32_bf16 v[0:3], v[174:177], v[208:211], v[0:3]
	s_barrier
	s_setprio 0
	s_movk_i32 s42, 0x100
	s_andn2_b64 vcc, exec, s[38:39]
	s_mov_b64 s[40:41], -1
	s_mov_b64 s[38:39], 0
	s_cbranch_vccz .LBB0_1161
	s_and_b64 vcc, exec, s[14:15]
	s_cbranch_vccz .LBB0_1164
	s_barrier

; #define PG8_STAGE(bufoff, gbase, voff) do { _Pragma("unroll") for (int _i = 0; _i < 2; ++_i) \
;         __builtin_amdgcn_global_load_lds((const unsigned*)((const char*)(gbase) + (voff)[_i]), (PG8_LAS unsigned*)(lds + (bufoff) + ldsw + _i * 8192), 16, 0, 0); } while (0)
; #define PG8_LDA(dst, b, h) do { _Pragma("unroll") for (int m = 0; m < 4; ++m) _Pragma("unroll") for (int k = 0; k < 2; ++k) dst[m][k] = *(const PG8_LAS bf16x8*)(lds + PG8_SA(b, h) + aoff + m * 2048 + k * 1024); } while (0)
; #define PG8_LDB(dst, b, h) do { _Pragma("unroll") for (int n = 0; n < 2; ++n) _Pragma("unroll") for (int k = 0; k < 2; ++k) dst[n][k] = *(const PG8_LAS bf16x8*)(lds + PG8_SB(b, h) + boff + n * 2048 + k * 1024); } while (0)
; #define PG8_MMA(ai, bj, At, Bt) do { __builtin_amdgcn_s_setprio(1); _Pragma("unroll") for (int m = 0; m < 4; ++m) _Pragma("unroll") for (int n = 0; n < 2; ++n) _Pragma("unroll") for (int k = 0; k < 2; ++k) \
;         acc[ai][bj][m][n] = __builtin_amdgcn_mfma_f32_16x16x32_bf16(Bt[n][k], At[m][k], acc[ai][bj][m][n], 0, 0, 0); __builtin_amdgcn_s_setprio(0); } while (0)
; #define PG8_WAIT_V(n) asm volatile("s_waitcnt vmcnt(" #n ")" ::: "memory")
; #define PG8_WAIT_L(n) asm volatile("s_waitcnt lgkmcnt(" #n ")" ::: "memory")
; #define PG8_BAR __builtin_amdgcn_s_barrier()
; #define PG8_SCHED __builtin_amdgcn_sched_barrier(0)
; template <class Epi, class Sched, bool ALIGN_EPI = false, bool SP2 = false>
; __device__ __forceinline__ void gemm_phase(PG8_LAS unsigned char* lds, const Gemm g, const Sched& S, const Epi& E) {
;     ...
;         for (int t = 0; t < nt; t += 2) {
;             const bool last = (t == nt - 2);
;             const char* a1 = cA + (size_t)(t + 1) * kstep;
;             const char* a2 = last ? nA : cA + (size_t)(t + 2) * kstep; const char* b2 = last ? nB : cB + (size_t)(t + 2) * kstep;
;             const char* a3 = a2 + kstep; const char* b3 = b2 + kstep;
;             if (last && has_next) S.a_ready(nxt);
;             if constexpr (SP2) {
;             PG8_LDB(B0, 0, 0); PG8_LDB(B1, 0, 1); PG8_SCHED; PG8_LDA(At, 0, 0); PG8_STAGE(PG8_SA(1, 1), a1 + hstepA, voffA);
;             PG8_WAIT_V(8); PG8_WAIT_L(0); PG8_BAR; PG8_MMA(0, 0, At, B0); PG8_MMA(0, 1, At, B1); PG8_BAR; PG8_SCHED;
;             PG8_LDA(At, 0, 1); PG8_STAGE(PG8_SB(0, 0), b2, voffB); PG8_STAGE(PG8_SB(0, 1), b2 + hstepB, voffB); PG8_STAGE(PG8_SA(0, 0), a2, voffA);
.LBB0_1231:
	ds_read_b128 v[112:115], v185
	ds_read_b128 v[116:119], v185 offset:1024
	ds_read_b128 v[128:131], v185 offset:2048
	ds_read_b128 v[140:143], v185 offset:3072
	ds_read_b128 v[144:147], v188
	ds_read_b128 v[148:151], v188 offset:1024
	ds_read_b128 v[168:171], v188 offset:2048
	ds_read_b128 v[172:175], v188 offset:3072
	s_add_u32 s34, s30, 0xfffc0080
	s_addc_u32 s35, s31, -1
	s_cmp_eq_u32 s69, 12
	s_cselect_b32 s37, s21, s35
	s_cselect_b32 s36, s27, s34
	s_cselect_b32 s35, s19, s68
	s_cselect_b32 s34, s66, s67
	v_lshl_add_u64 v[180:181], s[30:31], 0, v[160:161]
	s_add_i32 m0, s29, 0xc000
	ds_read_b128 v[176:179], v189
	ds_read_b128 v[192:195], v189 offset:1024
	ds_read_b128 v[196:199], v189 offset:2048
	ds_read_b128 v[200:203], v189 offset:3072
	ds_read_b128 v[204:207], v189 offset:4096
	ds_read_b128 v[208:211], v189 offset:5120
	ds_read_b128 v[212:215], v189 offset:6144
	ds_read_b128 v[216:219], v189 offset:7168
	global_load_lds_dwordx4 v[180:181], off
	v_lshl_add_u64 v[180:181], s[30:31], 0, v[162:163]
	s_add_i32 m0, s29, 0xe000
	s_nop 0
	global_load_lds_dwordx4 v[180:181], off
	s_waitcnt vmcnt(8)
	s_waitcnt lgkmcnt(0)
	s_barrier
	s_setprio 1
	s_waitcnt lgkmcnt(0)
	v_mfma_f32_16x16x32_bf16 v[136:139], v[112:115], v[176:179], v[136:139]
	v_mfma_f32_16x16x32_bf16 v[132:135], v[128:131], v[176:179], v[132:135]
	v_mfma_f32_16x16x32_bf16 v[108:111], v[112:115], v[196:199], v[108:111]
	v_mfma_f32_16x16x32_bf16 v[104:107], v[128:131], v[196:199], v[104:107]
	v_mfma_f32_16x16x32_bf16 v[92:95], v[112:115], v[204:207], v[92:95]
	v_mfma_f32_16x16x32_bf16 v[88:91], v[128:131], v[204:207], v[88:91]
	v_mfma_f32_16x16x32_bf16 v[76:79], v[112:115], v[212:215], v[76:79]
	v_mfma_f32_16x16x32_bf16 v[72:75], v[128:131], v[212:215], v[72:75]
	v_mfma_f32_16x16x32_bf16 v[136:139], v[116:119], v[192:195], v[136:139]
	v_mfma_f32_16x16x32_bf16 v[132:135], v[140:143], v[192:195], v[132:135]
	v_mfma_f32_16x16x32_bf16 v[108:111], v[116:119], v[200:203], v[108:111]
	v_mfma_f32_16x16x32_bf16 v[104:107], v[140:143], v[200:203], v[104:107]
	v_mfma_f32_16x16x32_bf16 v[92:95], v[116:119], v[208:211], v[92:95]
	v_mfma_f32_16x16x32_bf16 v[88:91], v[140:143], v[208:211], v[88:91]
	v_mfma_f32_16x16x32_bf16 v[76:79], v[116:119], v[216:219], v[76:79]
	v_mfma_f32_16x16x32_bf16 v[72:75], v[140:143], v[216:219], v[72:75]
	s_setprio 0
	s_setprio 1
	v_mfma_f32_16x16x32_bf16 v[124:127], v[144:147], v[176:179], v[124:127]
	v_mfma_f32_16x16x32_bf16 v[120:123], v[168:171], v[176:179], v[120:123]
	v_mfma_f32_16x16x32_bf16 v[100:103], v[144:147], v[196:199], v[100:103]
	v_mfma_f32_16x16x32_bf16 v[96:99], v[168:171], v[196:199], v[96:99]
	v_mfma_f32_16x16x32_bf16 v[84:87], v[144:147], v[204:207], v[84:87]
	v_mfma_f32_16x16x32_bf16 v[80:83], v[168:171], v[204:207], v[80:83]
	v_mfma_f32_16x16x32_bf16 v[68:71], v[144:147], v[212:215], v[68:71]
	v_mfma_f32_16x16x32_bf16 v[64:67], v[168:171], v[212:215], v[64:67]
	v_mfma_f32_16x16x32_bf16 v[124:127], v[148:151], v[192:195], v[124:127]
	v_mfma_f32_16x16x32_bf16 v[120:123], v[172:175], v[192:195], v[120:123]
	v_mfma_f32_16x16x32_bf16 v[100:103], v[148:151], v[200:203], v[100:103]
	v_mfma_f32_16x16x32_bf16 v[96:99], v[172:175], v[200:203], v[96:99]
	v_mfma_f32_16x16x32_bf16 v[84:87], v[148:151], v[208:211], v[84:87]
	v_mfma_f32_16x16x32_bf16 v[80:83], v[172:175], v[208:211], v[80:83]
	v_mfma_f32_16x16x32_bf16 v[68:71], v[148:151], v[216:219], v[68:71]
	v_mfma_f32_16x16x32_bf16 v[64:67], v[172:175], v[216:219], v[64:67]
	s_barrier
	s_setprio 0
	s_add_i32 s58, s49, s39
	v_lshl_add_u64 v[180:181], s[34:35], 0, v[154:155]
	s_mov_b32 m0, s58
	ds_read_b128 v[176:179], v189 offset:16384
	ds_read_b128 v[192:195], v189 offset:17408
	ds_read_b128 v[196:199], v189 offset:18432
	ds_read_b128 v[200:203], v189 offset:19456
	ds_read_b128 v[204:207], v189 offset:20480
	ds_read_b128 v[208:211], v189 offset:21504
	ds_read_b128 v[212:215], v189 offset:22528
	ds_read_b128 v[216:219], v189 offset:23552
	global_load_lds_dwordx4 v[180:181], off
	s_add_i32 m0, s58, 0x2000
	s_add_u32 s58, s34, 0x40000
	v_lshl_add_u64 v[220:221], s[34:35], 0, v[158:159]
	s_addc_u32 s59, s35, 0
	s_add_i32 s73, s64, s39
	global_load_lds_dwordx4 v[220:221], off
	v_lshl_add_u64 v[222:223], s[58:59], 0, v[154:155]
	s_mov_b32 m0, s73
	v_lshl_add_u64 v[224:225], s[36:37], 0, v[156:157]
	global_load_lds_dwordx4 v[222:223], off
	v_lshl_add_u64 v[222:223], s[58:59], 0, v[158:159]
	s_add_i32 m0, s73, 0x2000
	s_nop 0
	global_load_lds_dwordx4 v[222:223], off
	v_lshl_add_u64 v[222:223], s[36:37], 0, v[152:153]
	s_mov_b32 m0, s29
	s_nop 0
	global_load_lds_dwordx4 v[222:223], off
	s_mov_b32 m0, s40
	s_nop 0
	global_load_lds_dwordx4 v[224:225], off
	s_waitcnt vmcnt(8)
	s_waitcnt lgkmcnt(0)
	s_barrier
; #define PG8_STAGE(bufoff, gbase, voff) do { _Pragma("unroll") for (int _i = 0; _i < 2; ++_i) \
;         __builtin_amdgcn_global_load_lds((const unsigned*)((const char*)(gbase) + (voff)[_i]), (PG8_LAS unsigned*)(lds + (bufoff) + ldsw + _i * 8192), 16, 0, 0); } while (0)
; #define PG8_LDA(dst, b, h) do { _Pragma("unroll") for (int m = 0; m < 4; ++m) _Pragma("unroll") for (int k = 0; k < 2; ++k) dst[m][k] = *(const PG8_LAS bf16x8*)(lds + PG8_SA(b, h) + aoff + m * 2048 + k * 1024); } while (0)
; #define PG8_LDB(dst, b, h) do { _Pragma("unroll") for (int n = 0; n < 2; ++n) _Pragma("unroll") for (int k = 0; k < 2; ++k) dst[n][k] = *(const PG8_LAS bf16x8*)(lds + PG8_SB(b, h) + boff + n * 2048 + k * 1024); } while (0)
; #define PG8_MMA(ai, bj, At, Bt) do { __builtin_amdgcn_s_setprio(1); _Pragma("unroll") for (int m = 0; m < 4; ++m) _Pragma("unroll") for (int n = 0; n < 2; ++n) _Pragma("unroll") for (int k = 0; k < 2; ++k) \
;         acc[ai][bj][m][n] = __builtin_amdgcn_mfma_f32_16x16x32_bf16(Bt[n][k], At[m][k], acc[ai][bj][m][n], 0, 0, 0); __builtin_amdgcn_s_setprio(0); } while (0)
; #define PG8_WAIT_V(n) asm volatile("s_waitcnt vmcnt(" #n ")" ::: "memory")
; #define PG8_WAIT_L(n) asm volatile("s_waitcnt lgkmcnt(" #n ")" ::: "memory")
; #define PG8_BAR __builtin_amdgcn_s_barrier()
; #define PG8_SCHED __builtin_amdgcn_sched_barrier(0)
; template <class Epi, class Sched, bool ALIGN_EPI = false, bool SP2 = false>
; __device__ __forceinline__ void gemm_phase(PG8_LAS unsigned char* lds, const Gemm g, const Sched& S, const Epi& E) {
;     ...
;             PG8_WAIT_V(8); PG8_WAIT_L(0); PG8_BAR; PG8_MMA(1, 0, At, B0); PG8_MMA(1, 1, At, B1); PG8_BAR; PG8_SCHED;
;             PG8_LDB(B0, 1, 0); PG8_LDB(B1, 1, 1); PG8_SCHED; PG8_LDA(At, 1, 0); PG8_STAGE(PG8_SA(0, 1), a2 + hstepA, voffA);
;             PG8_WAIT_V(8); PG8_WAIT_L(0); PG8_BAR; PG8_MMA(0, 0, At, B0); PG8_MMA(0, 1, At, B1); PG8_BAR; PG8_SCHED;
	s_setprio 1
	s_waitcnt lgkmcnt(0)
	v_mfma_f32_16x16x32_bf16 v[60:63], v[112:115], v[176:179], v[60:63]
	v_mfma_f32_16x16x32_bf16 v[56:59], v[128:131], v[176:179], v[56:59]
	v_mfma_f32_16x16x32_bf16 v[44:47], v[112:115], v[196:199], v[44:47]
	v_mfma_f32_16x16x32_bf16 v[40:43], v[128:131], v[196:199], v[40:43]
	v_mfma_f32_16x16x32_bf16 v[28:31], v[112:115], v[204:207], v[28:31]
	v_mfma_f32_16x16x32_bf16 v[24:27], v[128:131], v[204:207], v[24:27]
	v_mfma_f32_16x16x32_bf16 v[12:15], v[112:115], v[212:215], v[12:15]
	v_mfma_f32_16x16x32_bf16 v[8:11], v[128:131], v[212:215], v[8:11]
	v_mfma_f32_16x16x32_bf16 v[60:63], v[116:119], v[192:195], v[60:63]
	v_mfma_f32_16x16x32_bf16 v[56:59], v[140:143], v[192:195], v[56:59]
	v_mfma_f32_16x16x32_bf16 v[44:47], v[116:119], v[200:203], v[44:47]
	v_mfma_f32_16x16x32_bf16 v[40:43], v[140:143], v[200:203], v[40:43]
	v_mfma_f32_16x16x32_bf16 v[28:31], v[116:119], v[208:211], v[28:31]
	v_mfma_f32_16x16x32_bf16 v[24:27], v[140:143], v[208:211], v[24:27]
	v_mfma_f32_16x16x32_bf16 v[12:15], v[116:119], v[216:219], v[12:15]
	v_mfma_f32_16x16x32_bf16 v[8:11], v[140:143], v[216:219], v[8:11]
	s_setprio 0
	s_setprio 1
	v_mfma_f32_16x16x32_bf16 v[52:55], v[144:147], v[176:179], v[52:55]
	v_mfma_f32_16x16x32_bf16 v[48:51], v[168:171], v[176:179], v[48:51]
	v_mfma_f32_16x16x32_bf16 v[36:39], v[144:147], v[196:199], v[36:39]
	v_mfma_f32_16x16x32_bf16 v[32:35], v[168:171], v[196:199], v[32:35]
	v_mfma_f32_16x16x32_bf16 v[20:23], v[144:147], v[204:207], v[20:23]
	v_mfma_f32_16x16x32_bf16 v[16:19], v[168:171], v[204:207], v[16:19]
	v_mfma_f32_16x16x32_bf16 v[4:7], v[144:147], v[212:215], v[4:7]
	v_mfma_f32_16x16x32_bf16 v[0:3], v[168:171], v[212:215], v[0:3]
	v_mfma_f32_16x16x32_bf16 v[52:55], v[148:151], v[192:195], v[52:55]
	v_mfma_f32_16x16x32_bf16 v[48:51], v[172:175], v[192:195], v[48:51]
	v_mfma_f32_16x16x32_bf16 v[36:39], v[148:151], v[200:203], v[36:39]
	v_mfma_f32_16x16x32_bf16 v[32:35], v[172:175], v[200:203], v[32:35]
	v_mfma_f32_16x16x32_bf16 v[20:23], v[148:151], v[208:211], v[20:23]
	v_mfma_f32_16x16x32_bf16 v[16:19], v[172:175], v[208:211], v[16:19]
	v_mfma_f32_16x16x32_bf16 v[4:7], v[148:151], v[216:219], v[4:7]
	v_mfma_f32_16x16x32_bf16 v[0:3], v[172:175], v[216:219], v[0:3]
	s_barrier
	s_setprio 0
	s_add_i32 s58, 0, 0x18000
	s_add_i32 s59, 0, 0x1c000
	v_add_u32_e32 v140, s58, v183
	v_add_u32_e32 v172, s59, v183
	ds_read_b128 v[112:115], v140
	ds_read_b128 v[116:119], v140 offset:1024
	ds_read_b128 v[128:131], v140 offset:2048
	ds_read_b128 v[140:143], v140 offset:3072
	ds_read_b128 v[144:147], v172
	ds_read_b128 v[148:151], v172 offset:1024
	ds_read_b128 v[168:171], v172 offset:2048
	ds_read_b128 v[172:175], v172 offset:3072
	s_add_u32 s36, s36, 0x40000
	s_addc_u32 s37, s37, 0
	s_mov_b32 m0, s41
	v_lshl_add_u64 v[226:227], s[36:37], 0, v[152:153]
	ds_read_b128 v[176:179], v189 offset:32768
	ds_read_b128 v[192:195], v189 offset:33792
	ds_read_b128 v[196:199], v189 offset:34816
	ds_read_b128 v[200:203], v189 offset:35840
	ds_read_b128 v[204:207], v189 offset:36864
	ds_read_b128 v[208:211], v189 offset:37888
	ds_read_b128 v[212:215], v189 offset:38912
	ds_read_b128 v[216:219], v189 offset:39936
	global_load_lds_dwordx4 v[226:227], off
	v_lshl_add_u64 v[226:227], s[36:37], 0, v[156:157]
	s_mov_b32 m0, s42
	s_nop 0
	global_load_lds_dwordx4 v[226:227], off
	s_waitcnt vmcnt(8)
	s_waitcnt lgkmcnt(0)
	s_barrier
	s_setprio 1
	s_waitcnt lgkmcnt(0)
	v_mfma_f32_16x16x32_bf16 v[136:139], v[112:115], v[176:179], v[136:139]
	v_mfma_f32_16x16x32_bf16 v[132:135], v[128:131], v[176:179], v[132:135]
	v_mfma_f32_16x16x32_bf16 v[108:111], v[112:115], v[196:199], v[108:111]
	v_mfma_f32_16x16x32_bf16 v[104:107], v[128:131], v[196:199], v[104:107]
	v_mfma_f32_16x16x32_bf16 v[92:95], v[112:115], v[204:207], v[92:95]
	v_mfma_f32_16x16x32_bf16 v[88:91], v[128:131], v[204:207], v[88:91]
	v_mfma_f32_16x16x32_bf16 v[76:79], v[112:115], v[212:215], v[76:79]
	v_mfma_f32_16x16x32_bf16 v[72:75], v[128:131], v[212:215], v[72:75]
	v_mfma_f32_16x16x32_bf16 v[136:139], v[116:119], v[192:195], v[136:139]
	v_mfma_f32_16x16x32_bf16 v[132:135], v[140:143], v[192:195], v[132:135]
	v_mfma_f32_16x16x32_bf16 v[108:111], v[116:119], v[200:203], v[108:111]
	v_mfma_f32_16x16x32_bf16 v[104:107], v[140:143], v[200:203], v[104:107]
	v_mfma_f32_16x16x32_bf16 v[92:95], v[116:119], v[208:211], v[92:95]
	v_mfma_f32_16x16x32_bf16 v[88:91], v[140:143], v[208:211], v[88:91]
	v_mfma_f32_16x16x32_bf16 v[76:79], v[116:119], v[216:219], v[76:79]
	v_mfma_f32_16x16x32_bf16 v[72:75], v[140:143], v[216:219], v[72:75]
	s_setprio 0
	s_setprio 1
	v_mfma_f32_16x16x32_bf16 v[124:127], v[144:147], v[176:179], v[124:127]
	v_mfma_f32_16x16x32_bf16 v[120:123], v[168:171], v[176:179], v[120:123]
	v_mfma_f32_16x16x32_bf16 v[100:103], v[144:147], v[196:199], v[100:103]
	v_mfma_f32_16x16x32_bf16 v[96:99], v[168:171], v[196:199], v[96:99]
	v_mfma_f32_16x16x32_bf16 v[84:87], v[144:147], v[204:207], v[84:87]
	v_mfma_f32_16x16x32_bf16 v[80:83], v[168:171], v[204:207], v[80:83]
	v_mfma_f32_16x16x32_bf16 v[68:71], v[144:147], v[212:215], v[68:71]
	v_mfma_f32_16x16x32_bf16 v[64:67], v[168:171], v[212:215], v[64:67]
	v_mfma_f32_16x16x32_bf16 v[124:127], v[148:151], v[192:195], v[124:127]
	v_mfma_f32_16x16x32_bf16 v[120:123], v[172:175], v[192:195], v[120:123]
	v_mfma_f32_16x16x32_bf16 v[100:103], v[148:151], v[200:203], v[100:103]
	v_mfma_f32_16x16x32_bf16 v[96:99], v[172:175], v[200:203], v[96:99]
	v_mfma_f32_16x16x32_bf16 v[84:87], v[148:151], v[208:211], v[84:87]
	v_mfma_f32_16x16x32_bf16 v[80:83], v[172:175], v[208:211], v[80:83]
	v_mfma_f32_16x16x32_bf16 v[68:71], v[148:151], v[216:219], v[68:71]
	v_mfma_f32_16x16x32_bf16 v[64:67], v[172:175], v[216:219], v[64:67]
	s_barrier
; #define PG8_STAGE(bufoff, gbase, voff) do { _Pragma("unroll") for (int _i = 0; _i < 2; ++_i) \
;         __builtin_amdgcn_global_load_lds((const unsigned*)((const char*)(gbase) + (voff)[_i]), (PG8_LAS unsigned*)(lds + (bufoff) + ldsw + _i * 8192), 16, 0, 0); } while (0)
; #define PG8_LDA(dst, b, h) do { _Pragma("unroll") for (int m = 0; m < 4; ++m) _Pragma("unroll") for (int k = 0; k < 2; ++k) dst[m][k] = *(const PG8_LAS bf16x8*)(lds + PG8_SA(b, h) + aoff + m * 2048 + k * 1024); } while (0)
; #define PG8_MMA(ai, bj, At, Bt) do { __builtin_amdgcn_s_setprio(1); _Pragma("unroll") for (int m = 0; m < 4; ++m) _Pragma("unroll") for (int n = 0; n < 2; ++n) _Pragma("unroll") for (int k = 0; k < 2; ++k) \
;         acc[ai][bj][m][n] = __builtin_amdgcn_mfma_f32_16x16x32_bf16(Bt[n][k], At[m][k], acc[ai][bj][m][n], 0, 0, 0); __builtin_amdgcn_s_setprio(0); } while (0)
; #define PG8_WAIT_V(n) asm volatile("s_waitcnt vmcnt(" #n ")" ::: "memory")
; #define PG8_WAIT_L(n) asm volatile("s_waitcnt lgkmcnt(" #n ")" ::: "memory")
; #define PG8_BAR __builtin_amdgcn_s_barrier()
; #define PG8_SCHED __builtin_amdgcn_sched_barrier(0)
; template <class Epi, class Sched, bool ALIGN_EPI = false, bool SP2 = false>
; __device__ __forceinline__ void gemm_phase(PG8_LAS unsigned char* lds, const Gemm g, const Sched& S, const Epi& E) {
;     ...
;             PG8_LDA(At, 1, 1); PG8_STAGE(PG8_SB(1, 0), b3, voffB); PG8_STAGE(PG8_SB(1, 1), b3 + hstepB, voffB); PG8_STAGE(PG8_SA(1, 0), a3, voffA);
;             PG8_WAIT_V(8); PG8_WAIT_L(0); PG8_BAR; PG8_MMA(1, 0, At, B0); PG8_MMA(1, 1, At, B1); PG8_BAR; PG8_SCHED;
;     ...
;         if constexpr (ALIGN_EPI) { if (wr == 0) PG8_BAR; }
	s_setprio 0
	s_add_i32 s36, s58, s39
	v_lshl_add_u64 v[180:181], v[180:181], 0, s[14:15]
	s_mov_b32 m0, s36
	ds_read_b128 v[176:179], v189 offset:49152
	ds_read_b128 v[192:195], v189 offset:50176
	ds_read_b128 v[196:199], v189 offset:51200
	ds_read_b128 v[200:203], v189 offset:52224
	ds_read_b128 v[204:207], v189 offset:53248
	ds_read_b128 v[208:211], v189 offset:54272
	ds_read_b128 v[212:215], v189 offset:55296
	ds_read_b128 v[216:219], v189 offset:56320
	global_load_lds_dwordx4 v[180:181], off
	s_add_i32 m0, s36, 0x2000
	s_add_u32 s34, s34, 0x40080
	v_lshl_add_u64 v[180:181], v[220:221], 0, s[14:15]
	s_addc_u32 s35, s35, 0
	s_add_i32 s36, s59, s39
	global_load_lds_dwordx4 v[180:181], off
	v_lshl_add_u64 v[180:181], s[34:35], 0, v[154:155]
	s_mov_b32 m0, s36
	s_nop 0
	global_load_lds_dwordx4 v[180:181], off
	v_lshl_add_u64 v[180:181], s[34:35], 0, v[158:159]
	s_add_i32 m0, s36, 0x2000
	s_nop 0
	global_load_lds_dwordx4 v[180:181], off
	v_lshl_add_u64 v[180:181], v[222:223], 0, s[14:15]
	s_mov_b32 m0, s44
	s_nop 0
	global_load_lds_dwordx4 v[180:181], off
	v_lshl_add_u64 v[180:181], v[224:225], 0, s[14:15]
	s_mov_b32 m0, s45
	s_nop 0
	global_load_lds_dwordx4 v[180:181], off
	s_waitcnt vmcnt(8)
	s_waitcnt lgkmcnt(0)
	s_barrier
	s_setprio 1
	s_waitcnt lgkmcnt(0)
	v_mfma_f32_16x16x32_bf16 v[60:63], v[112:115], v[176:179], v[60:63]
	v_mfma_f32_16x16x32_bf16 v[56:59], v[128:131], v[176:179], v[56:59]
	v_mfma_f32_16x16x32_bf16 v[44:47], v[112:115], v[196:199], v[44:47]
	v_mfma_f32_16x16x32_bf16 v[40:43], v[128:131], v[196:199], v[40:43]
	v_mfma_f32_16x16x32_bf16 v[28:31], v[112:115], v[204:207], v[28:31]
	v_mfma_f32_16x16x32_bf16 v[24:27], v[128:131], v[204:207], v[24:27]
	v_mfma_f32_16x16x32_bf16 v[12:15], v[112:115], v[212:215], v[12:15]
	v_mfma_f32_16x16x32_bf16 v[8:11], v[128:131], v[212:215], v[8:11]
	v_mfma_f32_16x16x32_bf16 v[60:63], v[116:119], v[192:195], v[60:63]
	v_mfma_f32_16x16x32_bf16 v[56:59], v[140:143], v[192:195], v[56:59]
	v_mfma_f32_16x16x32_bf16 v[44:47], v[116:119], v[200:203], v[44:47]
	v_mfma_f32_16x16x32_bf16 v[40:43], v[140:143], v[200:203], v[40:43]
	v_mfma_f32_16x16x32_bf16 v[28:31], v[116:119], v[208:211], v[28:31]
	v_mfma_f32_16x16x32_bf16 v[24:27], v[140:143], v[208:211], v[24:27]
	v_mfma_f32_16x16x32_bf16 v[12:15], v[116:119], v[216:219], v[12:15]
	v_mfma_f32_16x16x32_bf16 v[8:11], v[140:143], v[216:219], v[8:11]
	s_setprio 0
	s_setprio 1
	v_mfma_f32_16x16x32_bf16 v[52:55], v[144:147], v[176:179], v[52:55]
	v_mfma_f32_16x16x32_bf16 v[48:51], v[168:171], v[176:179], v[48:51]
	v_mfma_f32_16x16x32_bf16 v[36:39], v[144:147], v[196:199], v[36:39]
	v_mfma_f32_16x16x32_bf16 v[32:35], v[168:171], v[196:199], v[32:35]
	v_mfma_f32_16x16x32_bf16 v[20:23], v[144:147], v[204:207], v[20:23]
	v_mfma_f32_16x16x32_bf16 v[16:19], v[168:171], v[204:207], v[16:19]
	v_mfma_f32_16x16x32_bf16 v[4:7], v[144:147], v[212:215], v[4:7]
	v_mfma_f32_16x16x32_bf16 v[0:3], v[168:171], v[212:215], v[0:3]
	v_mfma_f32_16x16x32_bf16 v[52:55], v[148:151], v[192:195], v[52:55]
	v_mfma_f32_16x16x32_bf16 v[48:51], v[172:175], v[192:195], v[48:51]
	v_mfma_f32_16x16x32_bf16 v[36:39], v[148:151], v[200:203], v[36:39]
	v_mfma_f32_16x16x32_bf16 v[32:35], v[172:175], v[200:203], v[32:35]
	v_mfma_f32_16x16x32_bf16 v[20:23], v[148:151], v[208:211], v[20:23]
	v_mfma_f32_16x16x32_bf16 v[16:19], v[172:175], v[208:211], v[16:19]
	v_mfma_f32_16x16x32_bf16 v[4:7], v[148:151], v[216:219], v[4:7]
	v_mfma_f32_16x16x32_bf16 v[0:3], v[172:175], v[216:219], v[0:3]
	s_barrier
	s_setprio 0
	s_add_i32 s69, s69, 2
	s_add_u32 s30, s30, 0x100
	s_addc_u32 s31, s31, 0
	s_add_u32 s67, s67, 0x100
	s_addc_u32 s68, s68, 0
	s_cmp_gt_u32 s69, 13
	s_cbranch_scc0 .LBB0_1231
	s_and_b64 vcc, exec, s[16:17]
	s_cbranch_vccz .LBB0_1234
	s_barrier

; __global__ void __launch_bounds__(512, 2) mk_fwd(Params P) {
;   extern __shared__ __attribute__((aligned(16))) unsigned char lds[];
	.amdhsa_kernel _Z6mk_fwd6Params
		.amdhsa_group_segment_fixed_size 0
		.amdhsa_private_segment_fixed_size 0
		.amdhsa_kernarg_size 480
		.amdhsa_user_sgpr_count 2
		.amdhsa_user_sgpr_dispatch_ptr 0
		.amdhsa_user_sgpr_queue_ptr 0
		.amdhsa_user_sgpr_kernarg_segment_ptr 1
		.amdhsa_user_sgpr_dispatch_id 0
		.amdhsa_user_sgpr_kernarg_preload_length 0
		.amdhsa_user_sgpr_kernarg_preload_offset 0
		.amdhsa_user_sgpr_private_segment_size 0
		.amdhsa_uses_dynamic_stack 0
		.amdhsa_enable_private_segment 0
		.amdhsa_system_sgpr_workgroup_id_x 1
		.amdhsa_system_sgpr_workgroup_id_y 0
		.amdhsa_system_sgpr_workgroup_id_z 0
		.amdhsa_system_sgpr_workgroup_info 0
		.amdhsa_system_vgpr_workitem_id 2
		.amdhsa_next_free_vgpr 256
		.amdhsa_next_free_sgpr 99
		.amdhsa_accum_offset 256
		.amdhsa_reserve_vcc 1
		.amdhsa_float_round_mode_32 0
		.amdhsa_float_round_mode_16_64 0
		.amdhsa_float_denorm_mode_32 3
		.amdhsa_float_denorm_mode_16_64 3
		.amdhsa_dx10_clamp 1
		.amdhsa_ieee_mode 1
		.amdhsa_fp16_overflow 0
		.amdhsa_tg_split 0
		.amdhsa_exception_fp_ieee_invalid_op 0
		.amdhsa_exception_fp_denorm_src 0
		.amdhsa_exception_fp_ieee_div_zero 0
		.amdhsa_exception_fp_ieee_overflow 0
		.amdhsa_exception_fp_ieee_underflow 0
		.amdhsa_exception_fp_ieee_inexact 0
		.amdhsa_exception_int_div_zero 0
	.end_amdhsa_kernel

; __global__ void __launch_bounds__(512, 2) mk_fwd(Params P) {
amdhsa.kernels:
  - .agpr_count:     0
    .args:
      - .offset:         0
        .size:           224
        .value_kind:     by_value
      - .offset:         224
        .size:           4
        .value_kind:     hidden_block_count_x
      - .offset:         228
        .size:           4
        .value_kind:     hidden_block_count_y
      - .offset:         232
        .size:           4
        .value_kind:     hidden_block_count_z
      - .offset:         236
        .size:           2
        .value_kind:     hidden_group_size_x
      - .offset:         238
        .size:           2
        .value_kind:     hidden_group_size_y
      - .offset:         240
        .size:           2
        .value_kind:     hidden_group_size_z
      - .offset:         242
        .size:           2
        .value_kind:     hidden_remainder_x
      - .offset:         244
        .size:           2
        .value_kind:     hidden_remainder_y
      - .offset:         246
        .size:           2
        .value_kind:     hidden_remainder_z
      - .offset:         264
        .size:           8
        .value_kind:     hidden_global_offset_x
      - .offset:         272
        .size:           8
        .value_kind:     hidden_global_offset_y
      - .offset:         280
        .size:           8
        .value_kind:     hidden_global_offset_z
      - .offset:         288
        .size:           2
        .value_kind:     hidden_grid_dims
      - .offset:         312
        .size:           8
        .value_kind:     hidden_multigrid_sync_arg
      - .offset:         344
        .size:           4
        .value_kind:     hidden_dynamic_lds_size
    .group_segment_fixed_size: 0
    .kernarg_segment_align: 8
    .kernarg_segment_size: 480
    .language:       OpenCL C
    .language_version:
      - 2
      - 0
    .max_flat_workgroup_size: 512
    .name:           _Z6mk_fwd6Params
    .private_segment_fixed_size: 0
    .sgpr_count:     105
    .sgpr_spill_count: 4
    .symbol:         _Z6mk_fwd6Params.kd
    .uniform_work_group_size: 1
    .uses_dynamic_stack: false
    .vgpr_count:     256
    .vgpr_spill_count: 0
    .wavefront_size: 64
